# v26: v11 with the hand-written P7 score sections padded so every 8-byte instruction is 8-byte aligned (byte-phase alignment)
# baseline (speedup 1.0000x reference)
; DI void attn_sample_item(const Params& p, int item, ldsp lds, int tid_) {
;     ...
;   float q[4][4];
; #pragma unroll
;   for (int t = 0; t < 4; ++t) { f32x4 a = {0.f, 0.f, 0.f, 0.f}; const float* pp = (const float*)(p.ws + B_PART) + (size_t)(b * 4 + t) * 1024 + h * 256 + lane * 4;
; #pragma unroll
;     for (int kp = 0; kp < 4; ++kp) a += *(const f32x4*)(pp + (size_t)kp * 512 * 1024);
;     q[t][0] = a[0] * 0.0625f; q[t][1] = a[1] * 0.0625f; q[t][2] = a[2] * 0.0625f; q[t][3] = a[3] * 0.0625f; }
;   const bool b0 = lane & 1, b1 = lane & 2;
;   f32x4 kvA[16], kvB[16];
; #pragma unroll
;   for (int j = 0; j < 16; ++j) kvA[j] = __builtin_nontemporal_load((const f32x4*)(ck + (size_t)(wid * 32 + j) * 1024 + lane * 4));
; #pragma unroll
;   for (int j = 0; j < 16; ++j) kvB[j] = __builtin_nontemporal_load((const f32x4*)(ck + (size_t)(wid * 32 + 16 + j) * 1024 + lane * 4));
.LBB0_1604:
	s_ashr_i32 s4, s40, 2
	s_ashr_i32 s5, s4, 31
	s_lshl_b64 s[4:5], s[4:5], 18
	s_and_b32 s26, s0, 0x300
	v_mov_b32_e32 v222, v212
	s_or_b32 s4, s4, s26
	s_and_b32 s28, s40, -4
	s_lshl_b32 s6, s26, 2
	s_add_u32 s6, s36, s6
	v_and_b32_e32 v223, 63, v222
	s_addc_u32 s7, s37, 0
	v_lshlrev_b32_e32 v144, 4, v223
	s_ashr_i32 s29, s28, 31
	v_lshl_add_u64 v[48:49], s[6:7], 0, v[144:145]
	s_lshl_b64 s[6:7], s[28:29], 12
	v_lshl_add_u64 v[8:9], v[48:49], 0, s[6:7]
	v_add_co_u32_e32 v4, vcc, s3, v8
	s_or_b32 s6, s28, 1
	s_nop 0
	v_addc_co_u32_e32 v5, vcc, 0, v9, vcc
	v_add_co_u32_e32 v10, vcc, s33, v8
	s_ashr_i32 s7, s6, 31
	s_nop 0
	v_addc_co_u32_e32 v11, vcc, 0, v9, vcc
	v_add_co_u32_e32 v12, vcc, s38, v8
	s_lshl_b64 s[6:7], s[6:7], 12
	s_nop 0
	v_addc_co_u32_e32 v13, vcc, 0, v9, vcc
	v_lshl_add_u64 v[24:25], v[48:49], 0, s[6:7]
	v_add_co_u32_e32 v20, vcc, s3, v24
	s_or_b32 s6, s28, 2
	s_nop 0
	v_addc_co_u32_e32 v21, vcc, 0, v25, vcc
	v_add_co_u32_e32 v26, vcc, s33, v24
	s_ashr_i32 s7, s6, 31
	s_nop 0
	v_addc_co_u32_e32 v27, vcc, 0, v25, vcc
	v_add_co_u32_e32 v28, vcc, s38, v24
	s_lshl_b64 s[6:7], s[6:7], 12
	global_load_dwordx4 v[0:3], v[8:9], off
	s_nop 0
	global_load_dwordx4 v[4:7], v[4:5], off
	v_addc_co_u32_e32 v29, vcc, 0, v25, vcc
	v_lshl_add_u64 v[44:45], v[48:49], 0, s[6:7]
	global_load_dwordx4 v[8:11], v[10:11], off
	s_nop 0
	global_load_dwordx4 v[12:15], v[12:13], off
	s_nop 0
	global_load_dwordx4 v[16:19], v[24:25], off
	s_nop 0
	global_load_dwordx4 v[20:23], v[20:21], off
	v_add_co_u32_e32 v36, vcc, s3, v44
	global_load_dwordx4 v[24:27], v[26:27], off
	s_nop 0
	global_load_dwordx4 v[28:31], v[28:29], off
	v_addc_co_u32_e32 v37, vcc, 0, v45, vcc
	v_add_co_u32_e32 v40, vcc, s33, v44
	global_load_dwordx4 v[32:35], v[44:45], off
	s_nop 0
	global_load_dwordx4 v[36:39], v[36:37], off
	v_addc_co_u32_e32 v41, vcc, 0, v45, vcc
	v_add_co_u32_e32 v44, vcc, s38, v44
	global_load_dwordx4 v[40:43], v[40:41], off
	s_nop 0
	v_addc_co_u32_e32 v45, vcc, 0, v45, vcc
	global_load_dwordx4 v[44:47], v[44:45], off
	s_or_b32 s6, s40, 3
	s_ashr_i32 s7, s6, 31
	s_lshl_b64 s[6:7], s[6:7], 12
	s_lshl_b64 s[30:31], s[4:5], 2
	s_add_u32 s4, s12, s30
	s_addc_u32 s5, s13, s31
	s_waitcnt vmcnt(11)
	v_pk_add_f32 v[2:3], v[2:3], 0 op_sel_hi:[1,0]
	v_pk_add_f32 v[0:1], v[0:1], 0 op_sel_hi:[1,0]
	s_waitcnt vmcnt(10)
	v_pk_add_f32 v[2:3], v[2:3], v[6:7]
	v_pk_add_f32 v[0:1], v[0:1], v[4:5]
	s_waitcnt vmcnt(9)
	v_pk_add_f32 v[2:3], v[2:3], v[10:11]
	s_waitcnt vmcnt(7)
	v_pk_add_f32 v[4:5], v[18:19], 0 op_sel_hi:[1,0]
	v_pk_add_f32 v[6:7], v[16:17], 0 op_sel_hi:[1,0]
	v_pk_add_f32 v[0:1], v[0:1], v[8:9]
	s_waitcnt vmcnt(6)
	v_pk_add_f32 v[4:5], v[4:5], v[22:23]
	v_pk_add_f32 v[6:7], v[6:7], v[20:21]
	v_pk_add_f32 v[2:3], v[2:3], v[14:15]
	v_pk_add_f32 v[0:1], v[0:1], v[12:13]
	s_waitcnt vmcnt(5)
	v_pk_add_f32 v[4:5], v[4:5], v[26:27]
	v_pk_add_f32 v[6:7], v[6:7], v[24:25]
	v_mul_f32_e32 v228, 0x3d800000, v0
	v_mul_f32_e32 v231, 0x3d800000, v1
	v_mul_f32_e32 v229, 0x3d800000, v2
	v_mul_f32_e32 v225, 0x3d800000, v3
	s_waitcnt vmcnt(4)
	v_pk_add_f32 v[0:1], v[4:5], v[30:31]
	v_pk_add_f32 v[2:3], v[6:7], v[28:29]
	v_mul_f32_e32 v227, 0x3d800000, v0
	v_mul_f32_e32 v226, 0x3d800000, v2
	v_mul_f32_e32 v230, 0x3d800000, v3
	v_mul_f32_e32 v224, 0x3d800000, v1
	s_waitcnt vmcnt(3)
	v_pk_add_f32 v[0:1], v[34:35], 0 op_sel_hi:[1,0]
	v_pk_add_f32 v[2:3], v[32:33], 0 op_sel_hi:[1,0]
	s_waitcnt vmcnt(2)
	v_pk_add_f32 v[0:1], v[0:1], v[38:39]
	v_pk_add_f32 v[2:3], v[2:3], v[36:37]
	s_waitcnt vmcnt(1)
	v_pk_add_f32 v[0:1], v[0:1], v[42:43]
	v_pk_add_f32 v[2:3], v[2:3], v[40:41]
	s_waitcnt vmcnt(0)
	v_pk_add_f32 v[210:211], v[0:1], v[46:47]
	v_pk_add_f32 v[0:1], v[2:3], v[44:45]
	v_mul_f32_e32 v233, 0x3d800000, v210
	v_mul_f32_e32 v232, 0x3d800000, v0
	v_mul_f32_e32 v234, 0x3d800000, v1
	v_lshl_add_u64 v[0:1], v[48:49], 0, s[6:7]
	v_add_co_u32_e32 v2, vcc, s3, v0
	v_ashrrev_i32_e32 v210, 6, v222
	s_nop 0
	v_addc_co_u32_e32 v3, vcc, 0, v1, vcc
	global_load_dwordx4 v[128:131], v[0:1], off
	global_load_dwordx4 v[132:135], v[2:3], off
	v_add_co_u32_e32 v2, vcc, s33, v0
	v_mul_f32_e32 v211, 0x3d800000, v211
	s_nop 0
	v_addc_co_u32_e32 v3, vcc, 0, v1, vcc
	v_add_co_u32_e32 v0, vcc, s38, v0
	v_cmp_lt_i32_e64 s[6:7], v218, v216
	s_nop 0
	v_addc_co_u32_e32 v1, vcc, 0, v1, vcc
	global_load_dwordx4 v[136:139], v[2:3], off
	global_load_dwordx4 v[140:143], v[0:1], off
	v_lshlrev_b32_e32 v0, 5, v210
	v_ashrrev_i32_e32 v1, 31, v0
	v_or_b32_e32 v6, 1, v0
	v_lshl_add_u64 v[2:3], s[4:5], 0, v[144:145]
	v_lshlrev_b64 v[162:163], 12, v[0:1]
	v_ashrrev_i32_e32 v7, 31, v6
	v_lshl_add_u64 v[4:5], v[2:3], 0, v[162:163]
	v_lshlrev_b64 v[166:167], 12, v[6:7]
	v_lshl_add_u64 v[6:7], v[2:3], 0, v[166:167]
	global_load_dwordx4 v[124:127], v[4:5], off nt
	global_load_dwordx4 v[120:123], v[6:7], off nt
	v_or_b32_e32 v4, 2, v0
	v_ashrrev_i32_e32 v5, 31, v4
	v_or_b32_e32 v6, 3, v0
	v_lshlrev_b64 v[168:169], 12, v[4:5]
	v_ashrrev_i32_e32 v7, 31, v6
	v_lshl_add_u64 v[4:5], v[2:3], 0, v[168:169]
	v_lshlrev_b64 v[172:173], 12, v[6:7]
	v_lshl_add_u64 v[6:7], v[2:3], 0, v[172:173]
	global_load_dwordx4 v[116:119], v[4:5], off nt
	global_load_dwordx4 v[112:115], v[6:7], off nt
	v_or_b32_e32 v4, 4, v0
	v_ashrrev_i32_e32 v5, 31, v4
	v_or_b32_e32 v6, 5, v0
	v_lshlrev_b64 v[176:177], 12, v[4:5]
	v_ashrrev_i32_e32 v7, 31, v6
	v_lshl_add_u64 v[4:5], v[2:3], 0, v[176:177]
	v_lshlrev_b64 v[180:181], 12, v[6:7]
	v_lshl_add_u64 v[6:7], v[2:3], 0, v[180:181]
	global_load_dwordx4 v[108:111], v[4:5], off nt
	global_load_dwordx4 v[104:107], v[6:7], off nt
	v_or_b32_e32 v4, 6, v0
	v_ashrrev_i32_e32 v5, 31, v4
	v_or_b32_e32 v6, 7, v0
; DI void attn_sample_item(const Params& p, int item, ldsp lds, int tid_) {
;     ...
;   for (int t = 0; t < 4; ++t) { f32x4 a = {0.f, 0.f, 0.f, 0.f}; const float* pp = (const float*)(p.ws + B_PART) + (size_t)(b * 4 + t) * 1024 + h * 256 + lane * 4;
; #pragma unroll
;     for (int kp = 0; kp < 4; ++kp) a += *(const f32x4*)(pp + (size_t)kp * 512 * 1024);
;     q[t][0] = a[0] * 0.0625f; q[t][1] = a[1] * 0.0625f; q[t][2] = a[2] * 0.0625f; q[t][3] = a[3] * 0.0625f; }
;   const bool b0 = lane & 1, b1 = lane & 2;
;   f32x4 kvA[16], kvB[16];
; #pragma unroll
;   for (int j = 0; j < 16; ++j) kvA[j] = __builtin_nontemporal_load((const f32x4*)(ck + (size_t)(wid * 32 + j) * 1024 + lane * 4));
; #pragma unroll
;   for (int j = 0; j < 16; ++j) kvB[j] = __builtin_nontemporal_load((const f32x4*)(ck + (size_t)(wid * 32 + 16 + j) * 1024 + lane * 4));
	v_lshlrev_b64 v[182:183], 12, v[4:5]
	v_ashrrev_i32_e32 v7, 31, v6
	v_lshl_add_u64 v[4:5], v[2:3], 0, v[182:183]
	v_lshlrev_b64 v[186:187], 12, v[6:7]
	v_lshl_add_u64 v[6:7], v[2:3], 0, v[186:187]
	global_load_dwordx4 v[100:103], v[4:5], off nt
	global_load_dwordx4 v[96:99], v[6:7], off nt
	v_or_b32_e32 v4, 8, v0
	v_ashrrev_i32_e32 v5, 31, v4
	v_or_b32_e32 v6, 9, v0
	v_lshlrev_b64 v[190:191], 12, v[4:5]
	v_ashrrev_i32_e32 v7, 31, v6
	v_lshl_add_u64 v[4:5], v[2:3], 0, v[190:191]
	v_lshlrev_b64 v[194:195], 12, v[6:7]
	v_lshl_add_u64 v[6:7], v[2:3], 0, v[194:195]
	global_load_dwordx4 v[92:95], v[4:5], off nt
	global_load_dwordx4 v[88:91], v[6:7], off nt
	v_or_b32_e32 v4, 10, v0
	v_ashrrev_i32_e32 v5, 31, v4
	v_or_b32_e32 v6, 11, v0
	v_lshlrev_b64 v[198:199], 12, v[4:5]
	v_ashrrev_i32_e32 v7, 31, v6
	v_lshl_add_u64 v[4:5], v[2:3], 0, v[198:199]
	v_lshlrev_b64 v[200:201], 12, v[6:7]
	v_lshl_add_u64 v[6:7], v[2:3], 0, v[200:201]
	global_load_dwordx4 v[84:87], v[4:5], off nt
	global_load_dwordx4 v[80:83], v[6:7], off nt
	v_or_b32_e32 v4, 12, v0
	v_ashrrev_i32_e32 v5, 31, v4
	v_or_b32_e32 v6, 13, v0
	v_lshlrev_b64 v[202:203], 12, v[4:5]
	v_ashrrev_i32_e32 v7, 31, v6
	v_lshl_add_u64 v[4:5], v[2:3], 0, v[202:203]
	v_lshlrev_b64 v[204:205], 12, v[6:7]
	v_lshl_add_u64 v[6:7], v[2:3], 0, v[204:205]
	global_load_dwordx4 v[76:79], v[4:5], off nt
	global_load_dwordx4 v[72:75], v[6:7], off nt
	v_or_b32_e32 v4, 14, v0
	v_ashrrev_i32_e32 v5, 31, v4
	v_or_b32_e32 v6, 15, v0
	v_lshlrev_b64 v[206:207], 12, v[4:5]
	v_ashrrev_i32_e32 v7, 31, v6
	v_lshl_add_u64 v[4:5], v[2:3], 0, v[206:207]
	v_lshlrev_b64 v[208:209], 12, v[6:7]
	v_lshl_add_u64 v[6:7], v[2:3], 0, v[208:209]
	global_load_dwordx4 v[68:71], v[4:5], off nt
	global_load_dwordx4 v[64:67], v[6:7], off nt
	v_or_b32_e32 v4, 16, v0
	v_ashrrev_i32_e32 v5, 31, v4
	v_or_b32_e32 v6, 17, v0
	v_lshlrev_b64 v[146:147], 12, v[4:5]
	v_ashrrev_i32_e32 v7, 31, v6
	v_lshl_add_u64 v[4:5], v[2:3], 0, v[146:147]
	v_lshlrev_b64 v[148:149], 12, v[6:7]
	v_lshl_add_u64 v[6:7], v[2:3], 0, v[148:149]
	global_load_dwordx4 v[60:63], v[4:5], off nt
	global_load_dwordx4 v[56:59], v[6:7], off nt
	v_or_b32_e32 v4, 18, v0
	v_ashrrev_i32_e32 v5, 31, v4
	v_or_b32_e32 v6, 19, v0
	v_lshlrev_b64 v[150:151], 12, v[4:5]
	v_ashrrev_i32_e32 v7, 31, v6
	v_lshl_add_u64 v[4:5], v[2:3], 0, v[150:151]
	v_lshlrev_b64 v[152:153], 12, v[6:7]
	v_lshl_add_u64 v[6:7], v[2:3], 0, v[152:153]
	global_load_dwordx4 v[52:55], v[4:5], off nt
	global_load_dwordx4 v[48:51], v[6:7], off nt
	v_or_b32_e32 v4, 20, v0
	v_ashrrev_i32_e32 v5, 31, v4
	v_or_b32_e32 v6, 21, v0
	v_lshlrev_b64 v[154:155], 12, v[4:5]
	v_ashrrev_i32_e32 v7, 31, v6
	v_lshl_add_u64 v[4:5], v[2:3], 0, v[154:155]
	v_lshlrev_b64 v[156:157], 12, v[6:7]
	v_lshl_add_u64 v[6:7], v[2:3], 0, v[156:157]
	global_load_dwordx4 v[44:47], v[4:5], off nt
	global_load_dwordx4 v[40:43], v[6:7], off nt
	v_or_b32_e32 v4, 22, v0
	v_ashrrev_i32_e32 v5, 31, v4
	v_or_b32_e32 v6, 23, v0
	v_lshlrev_b64 v[158:159], 12, v[4:5]
	v_ashrrev_i32_e32 v7, 31, v6
	v_lshl_add_u64 v[4:5], v[2:3], 0, v[158:159]
	v_lshlrev_b64 v[160:161], 12, v[6:7]
	v_lshl_add_u64 v[6:7], v[2:3], 0, v[160:161]
	global_load_dwordx4 v[36:39], v[4:5], off nt
	global_load_dwordx4 v[32:35], v[6:7], off nt
	v_or_b32_e32 v4, 24, v0
	v_ashrrev_i32_e32 v5, 31, v4
	v_or_b32_e32 v6, 25, v0
	v_lshlrev_b64 v[164:165], 12, v[4:5]
	v_ashrrev_i32_e32 v7, 31, v6
	v_lshl_add_u64 v[4:5], v[2:3], 0, v[164:165]
	v_lshlrev_b64 v[170:171], 12, v[6:7]
	v_lshl_add_u64 v[6:7], v[2:3], 0, v[170:171]
	global_load_dwordx4 v[28:31], v[4:5], off nt
	global_load_dwordx4 v[24:27], v[6:7], off nt
	v_or_b32_e32 v4, 26, v0
	v_ashrrev_i32_e32 v5, 31, v4
	v_or_b32_e32 v6, 27, v0
	v_lshlrev_b64 v[174:175], 12, v[4:5]
	v_ashrrev_i32_e32 v7, 31, v6
	v_lshl_add_u64 v[4:5], v[2:3], 0, v[174:175]
	v_lshlrev_b64 v[178:179], 12, v[6:7]
	v_lshl_add_u64 v[6:7], v[2:3], 0, v[178:179]
	global_load_dwordx4 v[20:23], v[4:5], off nt
	global_load_dwordx4 v[16:19], v[6:7], off nt
	v_or_b32_e32 v4, 28, v0
	v_ashrrev_i32_e32 v5, 31, v4
	v_or_b32_e32 v6, 29, v0
	v_lshlrev_b64 v[184:185], 12, v[4:5]
	v_ashrrev_i32_e32 v7, 31, v6
	v_lshl_add_u64 v[4:5], v[2:3], 0, v[184:185]
	v_lshlrev_b64 v[188:189], 12, v[6:7]
	v_lshl_add_u64 v[6:7], v[2:3], 0, v[188:189]
	global_load_dwordx4 v[12:15], v[4:5], off nt
	global_load_dwordx4 v[8:11], v[6:7], off nt
	v_or_b32_e32 v4, 30, v0
	v_or_b32_e32 v0, 31, v0
	v_ashrrev_i32_e32 v5, 31, v4
	v_ashrrev_i32_e32 v1, 31, v0
	v_lshlrev_b64 v[192:193], 12, v[4:5]
	v_lshlrev_b64 v[196:197], 12, v[0:1]
	v_lshl_add_u64 v[4:5], v[2:3], 0, v[192:193]
	v_lshl_add_u64 v[0:1], v[2:3], 0, v[196:197]
	global_load_dwordx4 v[4:7], v[4:5], off nt
	s_nop 0
	global_load_dwordx4 v[0:3], v[0:1], off nt
	s_waitcnt vmcnt(35)
	v_pk_add_f32 v[128:129], v[128:129], 0 op_sel_hi:[1,0]
	v_pk_add_f32 v[130:131], v[130:131], 0 op_sel_hi:[1,0]
	s_waitcnt vmcnt(34)
	v_pk_add_f32 v[128:129], v[128:129], v[132:133]
	v_pk_add_f32 v[130:131], v[130:131], v[134:135]
	s_waitcnt vmcnt(33)
	v_pk_add_f32 v[128:129], v[128:129], v[136:137]
	v_pk_add_f32 v[130:131], v[130:131], v[138:139]
	s_waitcnt vmcnt(32)
; DI void attn_sample_item(const Params& p, int item, ldsp lds, int tid_) {
;     ...
;     q[t][0] = a[0] * 0.0625f; q[t][1] = a[1] * 0.0625f; q[t][2] = a[2] * 0.0625f; q[t][3] = a[3] * 0.0625f; }
;   const bool b0 = lane & 1, b1 = lane & 2;
;   f32x4 kvA[16], kvB[16];
; #pragma unroll
;   for (int j = 0; j < 16; ++j) kvA[j] = __builtin_nontemporal_load((const f32x4*)(ck + (size_t)(wid * 32 + j) * 1024 + lane * 4));
; #pragma unroll
;   for (int j = 0; j < 16; ++j) kvB[j] = __builtin_nontemporal_load((const f32x4*)(ck + (size_t)(wid * 32 + 16 + j) * 1024 + lane * 4));
	v_pk_add_f32 v[128:129], v[128:129], v[140:141]
	v_pk_add_f32 v[130:131], v[130:131], v[142:143]
	v_mul_f32_e32 v138, 0x3d800000, v129
	v_mul_f32_e32 v135, 0x3d800000, v128
	v_mul_f32_e32 v134, 0x3d800000, v131
	v_mul_f32_e32 v137, 0x3d800000, v130
	v_lshlrev_b32_e32 v128, 2, v215
	v_lshlrev_b32_e32 v129, 2, v217
	v_lshlrev_b32_e32 v130, 2, v218
	v_lshlrev_b32_e32 v131, 2, v219
	v_lshlrev_b32_e32 v132, 2, v220
	v_lshlrev_b32_e32 v133, 2, v221
	v_lshl_add_u32 v136, v210, 7, 16
	v_and_b32_e32 v139, 3, v223
	v_bfrev_b32_e32 v139, v139
	v_lshrrev_b32_e32 v139, 20, v139
	v_and_b32_e32 v235, -4, v223
	v_add3_u32 v235, v136, v139, v235
	v_mov_b32_e32 v236, v228
	v_mov_b32_e32 v237, v226
	v_mov_b32_e32 v238, v231
	v_mov_b32_e32 v239, v230
	v_mov_b32_e32 v240, v229
	v_mov_b32_e32 v241, v227
	v_mov_b32_e32 v242, v225
	v_mov_b32_e32 v243, v224
	v_mov_b32_e32 v244, v232
	v_mov_b32_e32 v245, v135
	v_mov_b32_e32 v246, v234
	v_mov_b32_e32 v247, v138
	v_mov_b32_e32 v248, v233
	v_mov_b32_e32 v249, v137
	v_mov_b32_e32 v250, v211
	v_mov_b32_e32 v251, v134
	s_mov_b32 vcc_lo, 0x55555555
	s_mov_b32 vcc_hi, 0x55555555
	s_mov_b32 s4, 0x33333333
	s_mov_b32 s5, 0x33333333
	s_mov_b32 s6, 0x0f0f0f0f
	s_mov_b32 s7, 0x0f0f0f0f
	s_mov_b32 s64, 0x00ff00ff
	s_mov_b32 s65, 0x00ff00ff
	s_waitcnt vmcnt(31)
	s_nop 0
	v_pk_mul_f32 v[252:253], v[236:237], v[124:125] op_sel_hi:[1,0]
	v_pk_mul_f32 v[254:255], v[244:245], v[124:125] op_sel_hi:[1,0]
	v_pk_fma_f32 v[252:253], v[238:239], v[124:125], v[252:253] op_sel:[0,1,0]
	v_pk_fma_f32 v[254:255], v[246:247], v[124:125], v[254:255] op_sel:[0,1,0]
	v_pk_fma_f32 v[252:253], v[240:241], v[126:127], v[252:253] op_sel_hi:[1,0,1]
	v_pk_fma_f32 v[254:255], v[248:249], v[126:127], v[254:255] op_sel_hi:[1,0,1]
	v_pk_fma_f32 v[252:253], v[242:243], v[126:127], v[252:253] op_sel:[0,1,0]
	v_pk_fma_f32 v[254:255], v[250:251], v[126:127], v[254:255] op_sel:[0,1,0]
	s_waitcnt vmcnt(30)
	s_nop 0
	v_pk_mul_f32 v[140:141], v[236:237], v[120:121] op_sel_hi:[1,0]
	v_pk_mul_f32 v[142:143], v[244:245], v[120:121] op_sel_hi:[1,0]
	v_pk_fma_f32 v[140:141], v[238:239], v[120:121], v[140:141] op_sel:[0,1,0]
	v_pk_fma_f32 v[142:143], v[246:247], v[120:121], v[142:143] op_sel:[0,1,0]
	v_pk_fma_f32 v[140:141], v[240:241], v[122:123], v[140:141] op_sel_hi:[1,0,1]
	v_pk_fma_f32 v[142:143], v[248:249], v[122:123], v[142:143] op_sel_hi:[1,0,1]
	v_pk_fma_f32 v[140:141], v[242:243], v[122:123], v[140:141] op_sel:[0,1,0]
	v_pk_fma_f32 v[142:143], v[250:251], v[122:123], v[142:143] op_sel:[0,1,0]
	v_add_f32_dpp v124, v252, v252 quad_perm:[1,0,3,2] row_mask:0xf bank_mask:0xf
	v_add_f32_dpp v125, v253, v253 quad_perm:[1,0,3,2] row_mask:0xf bank_mask:0xf
	v_add_f32_dpp v126, v254, v254 quad_perm:[1,0,3,2] row_mask:0xf bank_mask:0xf
	v_add_f32_dpp v127, v255, v255 quad_perm:[1,0,3,2] row_mask:0xf bank_mask:0xf
	v_cndmask_b32_e32 v124, v126, v124, vcc
	v_cndmask_b32_e32 v125, v127, v125, vcc
	s_waitcnt vmcnt(29)
	s_nop 0
	v_pk_mul_f32 v[252:253], v[236:237], v[116:117] op_sel_hi:[1,0]
	v_pk_mul_f32 v[254:255], v[244:245], v[116:117] op_sel_hi:[1,0]
	v_pk_fma_f32 v[252:253], v[238:239], v[116:117], v[252:253] op_sel:[0,1,0]
	v_pk_fma_f32 v[254:255], v[246:247], v[116:117], v[254:255] op_sel:[0,1,0]
	v_pk_fma_f32 v[252:253], v[240:241], v[118:119], v[252:253] op_sel_hi:[1,0,1]
	v_pk_fma_f32 v[254:255], v[248:249], v[118:119], v[254:255] op_sel_hi:[1,0,1]
	v_pk_fma_f32 v[252:253], v[242:243], v[118:119], v[252:253] op_sel:[0,1,0]
	v_pk_fma_f32 v[254:255], v[250:251], v[118:119], v[254:255] op_sel:[0,1,0]
	v_add_f32_dpp v120, v140, v140 quad_perm:[1,0,3,2] row_mask:0xf bank_mask:0xf
	v_add_f32_dpp v121, v141, v141 quad_perm:[1,0,3,2] row_mask:0xf bank_mask:0xf
	v_add_f32_dpp v122, v142, v142 quad_perm:[1,0,3,2] row_mask:0xf bank_mask:0xf
	v_add_f32_dpp v123, v143, v143 quad_perm:[1,0,3,2] row_mask:0xf bank_mask:0xf
	v_cndmask_b32_e32 v120, v122, v120, vcc
	v_cndmask_b32_e32 v121, v123, v121, vcc
	v_add_f32_dpp v126, v124, v124 quad_perm:[2,3,0,1] row_mask:0xf bank_mask:0xf
	v_add_f32_dpp v127, v125, v125 quad_perm:[2,3,0,1] row_mask:0xf bank_mask:0xf
	v_cndmask_b32_e64 v124, v127, v126, s[4:5]
	s_waitcnt vmcnt(28)
	s_nop 0
	v_pk_mul_f32 v[140:141], v[236:237], v[112:113] op_sel_hi:[1,0]
	v_pk_mul_f32 v[142:143], v[244:245], v[112:113] op_sel_hi:[1,0]
	v_pk_fma_f32 v[140:141], v[238:239], v[112:113], v[140:141] op_sel:[0,1,0]
	v_pk_fma_f32 v[142:143], v[246:247], v[112:113], v[142:143] op_sel:[0,1,0]
	v_pk_fma_f32 v[140:141], v[240:241], v[114:115], v[140:141] op_sel_hi:[1,0,1]
	v_pk_fma_f32 v[142:143], v[248:249], v[114:115], v[142:143] op_sel_hi:[1,0,1]
	v_pk_fma_f32 v[140:141], v[242:243], v[114:115], v[140:141] op_sel:[0,1,0]
	v_pk_fma_f32 v[142:143], v[250:251], v[114:115], v[142:143] op_sel:[0,1,0]
	v_add_f32_dpp v116, v252, v252 quad_perm:[1,0,3,2] row_mask:0xf bank_mask:0xf
	v_add_f32_dpp v117, v253, v253 quad_perm:[1,0,3,2] row_mask:0xf bank_mask:0xf
	v_add_f32_dpp v118, v254, v254 quad_perm:[1,0,3,2] row_mask:0xf bank_mask:0xf
	v_add_f32_dpp v119, v255, v255 quad_perm:[1,0,3,2] row_mask:0xf bank_mask:0xf
	v_cndmask_b32_e32 v116, v118, v116, vcc
	v_cndmask_b32_e32 v117, v119, v117, vcc
	v_add_f32_dpp v122, v120, v120 quad_perm:[2,3,0,1] row_mask:0xf bank_mask:0xf
	v_add_f32_dpp v123, v121, v121 quad_perm:[2,3,0,1] row_mask:0xf bank_mask:0xf
	v_cndmask_b32_e64 v120, v123, v122, s[4:5]
	v_cndmask_b32_e64 v125, v120, v124, s[6:7]
	v_cndmask_b32_e64 v126, v124, v120, s[6:7]
	s_waitcnt vmcnt(27)
; DI void attn_sample_item(const Params& p, int item, ldsp lds, int tid_) {
;     ...
;   SC_SCORE(kvA, 0)
;   SC_SCORE(kvB, 1)
	s_nop 0
	v_pk_mul_f32 v[252:253], v[236:237], v[108:109] op_sel_hi:[1,0]
	v_pk_mul_f32 v[254:255], v[244:245], v[108:109] op_sel_hi:[1,0]
	v_pk_fma_f32 v[252:253], v[238:239], v[108:109], v[252:253] op_sel:[0,1,0]
	v_pk_fma_f32 v[254:255], v[246:247], v[108:109], v[254:255] op_sel:[0,1,0]
	v_pk_fma_f32 v[252:253], v[240:241], v[110:111], v[252:253] op_sel_hi:[1,0,1]
	v_pk_fma_f32 v[254:255], v[248:249], v[110:111], v[254:255] op_sel_hi:[1,0,1]
	v_pk_fma_f32 v[252:253], v[242:243], v[110:111], v[252:253] op_sel:[0,1,0]
	v_pk_fma_f32 v[254:255], v[250:251], v[110:111], v[254:255] op_sel:[0,1,0]
	v_add_f32_dpp v124, v126, v125 row_ror:4 row_mask:0xf bank_mask:0xf
	v_add_f32_dpp v112, v140, v140 quad_perm:[1,0,3,2] row_mask:0xf bank_mask:0xf
	v_add_f32_dpp v113, v141, v141 quad_perm:[1,0,3,2] row_mask:0xf bank_mask:0xf
	v_add_f32_dpp v114, v142, v142 quad_perm:[1,0,3,2] row_mask:0xf bank_mask:0xf
	v_add_f32_dpp v115, v143, v143 quad_perm:[1,0,3,2] row_mask:0xf bank_mask:0xf
	v_cndmask_b32_e32 v112, v114, v112, vcc
	v_cndmask_b32_e32 v113, v115, v113, vcc
	v_add_f32_dpp v118, v116, v116 quad_perm:[2,3,0,1] row_mask:0xf bank_mask:0xf
	v_add_f32_dpp v119, v117, v117 quad_perm:[2,3,0,1] row_mask:0xf bank_mask:0xf
	v_cndmask_b32_e64 v116, v119, v118, s[4:5]
	s_waitcnt vmcnt(26)
	s_nop 0
	v_pk_mul_f32 v[140:141], v[236:237], v[104:105] op_sel_hi:[1,0]
	v_pk_mul_f32 v[142:143], v[244:245], v[104:105] op_sel_hi:[1,0]
	v_pk_fma_f32 v[140:141], v[238:239], v[104:105], v[140:141] op_sel:[0,1,0]
	v_pk_fma_f32 v[142:143], v[246:247], v[104:105], v[142:143] op_sel:[0,1,0]
	v_pk_fma_f32 v[140:141], v[240:241], v[106:107], v[140:141] op_sel_hi:[1,0,1]
	v_pk_fma_f32 v[142:143], v[248:249], v[106:107], v[142:143] op_sel_hi:[1,0,1]
	v_pk_fma_f32 v[140:141], v[242:243], v[106:107], v[140:141] op_sel:[0,1,0]
	v_pk_fma_f32 v[142:143], v[250:251], v[106:107], v[142:143] op_sel:[0,1,0]
	v_add_f32_dpp v108, v252, v252 quad_perm:[1,0,3,2] row_mask:0xf bank_mask:0xf
	v_add_f32_dpp v109, v253, v253 quad_perm:[1,0,3,2] row_mask:0xf bank_mask:0xf
	v_add_f32_dpp v110, v254, v254 quad_perm:[1,0,3,2] row_mask:0xf bank_mask:0xf
	v_add_f32_dpp v111, v255, v255 quad_perm:[1,0,3,2] row_mask:0xf bank_mask:0xf
	v_cndmask_b32_e32 v108, v110, v108, vcc
	v_cndmask_b32_e32 v109, v111, v109, vcc
	v_add_f32_dpp v114, v112, v112 quad_perm:[2,3,0,1] row_mask:0xf bank_mask:0xf
	v_add_f32_dpp v115, v113, v113 quad_perm:[2,3,0,1] row_mask:0xf bank_mask:0xf
	v_cndmask_b32_e64 v112, v115, v114, s[4:5]
	v_cndmask_b32_e64 v117, v112, v116, s[6:7]
	v_cndmask_b32_e64 v118, v116, v112, s[6:7]
	s_waitcnt vmcnt(25)
	s_nop 0
	v_pk_mul_f32 v[252:253], v[236:237], v[100:101] op_sel_hi:[1,0]
	v_pk_mul_f32 v[254:255], v[244:245], v[100:101] op_sel_hi:[1,0]
	v_pk_fma_f32 v[252:253], v[238:239], v[100:101], v[252:253] op_sel:[0,1,0]
	v_pk_fma_f32 v[254:255], v[246:247], v[100:101], v[254:255] op_sel:[0,1,0]
	v_pk_fma_f32 v[252:253], v[240:241], v[102:103], v[252:253] op_sel_hi:[1,0,1]
	v_pk_fma_f32 v[254:255], v[248:249], v[102:103], v[254:255] op_sel_hi:[1,0,1]
	v_pk_fma_f32 v[252:253], v[242:243], v[102:103], v[252:253] op_sel:[0,1,0]
	v_pk_fma_f32 v[254:255], v[250:251], v[102:103], v[254:255] op_sel:[0,1,0]
	v_add_f32_dpp v116, v118, v117 row_ror:4 row_mask:0xf bank_mask:0xf
	v_cndmask_b32_e64 v125, v116, v124, s[64:65]
	v_cndmask_b32_e64 v126, v124, v116, s[64:65]
	v_add_f32_dpp v104, v140, v140 quad_perm:[1,0,3,2] row_mask:0xf bank_mask:0xf
	v_add_f32_dpp v105, v141, v141 quad_perm:[1,0,3,2] row_mask:0xf bank_mask:0xf
	v_add_f32_dpp v106, v142, v142 quad_perm:[1,0,3,2] row_mask:0xf bank_mask:0xf
	v_add_f32_dpp v107, v143, v143 quad_perm:[1,0,3,2] row_mask:0xf bank_mask:0xf
	v_cndmask_b32_e32 v104, v106, v104, vcc
	v_cndmask_b32_e32 v105, v107, v105, vcc
	v_add_f32_dpp v110, v108, v108 quad_perm:[2,3,0,1] row_mask:0xf bank_mask:0xf
	v_add_f32_dpp v111, v109, v109 quad_perm:[2,3,0,1] row_mask:0xf bank_mask:0xf
	v_cndmask_b32_e64 v108, v111, v110, s[4:5]
	s_waitcnt vmcnt(24)
	s_nop 0
	v_pk_mul_f32 v[140:141], v[236:237], v[96:97] op_sel_hi:[1,0]
	v_pk_mul_f32 v[142:143], v[244:245], v[96:97] op_sel_hi:[1,0]
	v_pk_fma_f32 v[140:141], v[238:239], v[96:97], v[140:141] op_sel:[0,1,0]
	v_pk_fma_f32 v[142:143], v[246:247], v[96:97], v[142:143] op_sel:[0,1,0]
	v_pk_fma_f32 v[140:141], v[240:241], v[98:99], v[140:141] op_sel_hi:[1,0,1]
	v_pk_fma_f32 v[142:143], v[248:249], v[98:99], v[142:143] op_sel_hi:[1,0,1]
	v_pk_fma_f32 v[140:141], v[242:243], v[98:99], v[140:141] op_sel:[0,1,0]
	v_pk_fma_f32 v[142:143], v[250:251], v[98:99], v[142:143] op_sel:[0,1,0]
	v_add_f32_dpp v124, v126, v125 row_ror:8 row_mask:0xf bank_mask:0xf
	v_add_f32_dpp v100, v252, v252 quad_perm:[1,0,3,2] row_mask:0xf bank_mask:0xf
	v_add_f32_dpp v101, v253, v253 quad_perm:[1,0,3,2] row_mask:0xf bank_mask:0xf
	v_add_f32_dpp v102, v254, v254 quad_perm:[1,0,3,2] row_mask:0xf bank_mask:0xf
	v_add_f32_dpp v103, v255, v255 quad_perm:[1,0,3,2] row_mask:0xf bank_mask:0xf
	v_cndmask_b32_e32 v100, v102, v100, vcc
	v_cndmask_b32_e32 v101, v103, v101, vcc
	v_add_f32_dpp v106, v104, v104 quad_perm:[2,3,0,1] row_mask:0xf bank_mask:0xf
	v_add_f32_dpp v107, v105, v105 quad_perm:[2,3,0,1] row_mask:0xf bank_mask:0xf
	v_cndmask_b32_e64 v104, v107, v106, s[4:5]
	v_cndmask_b32_e64 v109, v104, v108, s[6:7]
	v_cndmask_b32_e64 v110, v108, v104, s[6:7]
	s_waitcnt vmcnt(23)
; DI void attn_sample_item(const Params& p, int item, ldsp lds, int tid_) {
;     ...
;   SC_SCORE(kvA, 0)
;   SC_SCORE(kvB, 1)
	s_nop 0
	v_pk_mul_f32 v[252:253], v[236:237], v[92:93] op_sel_hi:[1,0]
	v_pk_mul_f32 v[254:255], v[244:245], v[92:93] op_sel_hi:[1,0]
	v_pk_fma_f32 v[252:253], v[238:239], v[92:93], v[252:253] op_sel:[0,1,0]
	v_pk_fma_f32 v[254:255], v[246:247], v[92:93], v[254:255] op_sel:[0,1,0]
	v_pk_fma_f32 v[252:253], v[240:241], v[94:95], v[252:253] op_sel_hi:[1,0,1]
	v_pk_fma_f32 v[254:255], v[248:249], v[94:95], v[254:255] op_sel_hi:[1,0,1]
	v_pk_fma_f32 v[252:253], v[242:243], v[94:95], v[252:253] op_sel:[0,1,0]
	v_pk_fma_f32 v[254:255], v[250:251], v[94:95], v[254:255] op_sel:[0,1,0]
	v_add_f32_dpp v108, v110, v109 row_ror:4 row_mask:0xf bank_mask:0xf
	v_add_f32_dpp v96, v140, v140 quad_perm:[1,0,3,2] row_mask:0xf bank_mask:0xf
	v_add_f32_dpp v97, v141, v141 quad_perm:[1,0,3,2] row_mask:0xf bank_mask:0xf
	v_add_f32_dpp v98, v142, v142 quad_perm:[1,0,3,2] row_mask:0xf bank_mask:0xf
	v_add_f32_dpp v99, v143, v143 quad_perm:[1,0,3,2] row_mask:0xf bank_mask:0xf
	v_cndmask_b32_e32 v96, v98, v96, vcc
	v_cndmask_b32_e32 v97, v99, v97, vcc
	v_add_f32_dpp v102, v100, v100 quad_perm:[2,3,0,1] row_mask:0xf bank_mask:0xf
	v_add_f32_dpp v103, v101, v101 quad_perm:[2,3,0,1] row_mask:0xf bank_mask:0xf
	v_cndmask_b32_e64 v100, v103, v102, s[4:5]
	s_waitcnt vmcnt(22)
	s_nop 0
	v_pk_mul_f32 v[140:141], v[236:237], v[88:89] op_sel_hi:[1,0]
	v_pk_mul_f32 v[142:143], v[244:245], v[88:89] op_sel_hi:[1,0]
	v_pk_fma_f32 v[140:141], v[238:239], v[88:89], v[140:141] op_sel:[0,1,0]
	v_pk_fma_f32 v[142:143], v[246:247], v[88:89], v[142:143] op_sel:[0,1,0]
	v_pk_fma_f32 v[140:141], v[240:241], v[90:91], v[140:141] op_sel_hi:[1,0,1]
	v_pk_fma_f32 v[142:143], v[248:249], v[90:91], v[142:143] op_sel_hi:[1,0,1]
	v_pk_fma_f32 v[140:141], v[242:243], v[90:91], v[140:141] op_sel:[0,1,0]
	v_pk_fma_f32 v[142:143], v[250:251], v[90:91], v[142:143] op_sel:[0,1,0]
	v_add_f32_dpp v92, v252, v252 quad_perm:[1,0,3,2] row_mask:0xf bank_mask:0xf
	v_add_f32_dpp v93, v253, v253 quad_perm:[1,0,3,2] row_mask:0xf bank_mask:0xf
	v_add_f32_dpp v94, v254, v254 quad_perm:[1,0,3,2] row_mask:0xf bank_mask:0xf
	v_add_f32_dpp v95, v255, v255 quad_perm:[1,0,3,2] row_mask:0xf bank_mask:0xf
	v_cndmask_b32_e32 v92, v94, v92, vcc
	v_cndmask_b32_e32 v93, v95, v93, vcc
	v_add_f32_dpp v98, v96, v96 quad_perm:[2,3,0,1] row_mask:0xf bank_mask:0xf
	v_add_f32_dpp v99, v97, v97 quad_perm:[2,3,0,1] row_mask:0xf bank_mask:0xf
	v_cndmask_b32_e64 v96, v99, v98, s[4:5]
	v_cndmask_b32_e64 v101, v96, v100, s[6:7]
	v_cndmask_b32_e64 v102, v100, v96, s[6:7]
	s_waitcnt vmcnt(21)
	s_nop 0
	v_pk_mul_f32 v[252:253], v[236:237], v[84:85] op_sel_hi:[1,0]
	v_pk_mul_f32 v[254:255], v[244:245], v[84:85] op_sel_hi:[1,0]
	v_pk_fma_f32 v[252:253], v[238:239], v[84:85], v[252:253] op_sel:[0,1,0]
	v_pk_fma_f32 v[254:255], v[246:247], v[84:85], v[254:255] op_sel:[0,1,0]
	v_pk_fma_f32 v[252:253], v[240:241], v[86:87], v[252:253] op_sel_hi:[1,0,1]
	v_pk_fma_f32 v[254:255], v[248:249], v[86:87], v[254:255] op_sel_hi:[1,0,1]
	v_pk_fma_f32 v[252:253], v[242:243], v[86:87], v[252:253] op_sel:[0,1,0]
	v_pk_fma_f32 v[254:255], v[250:251], v[86:87], v[254:255] op_sel:[0,1,0]
	v_add_f32_dpp v100, v102, v101 row_ror:4 row_mask:0xf bank_mask:0xf
	v_cndmask_b32_e64 v109, v100, v108, s[64:65]
	v_cndmask_b32_e64 v110, v108, v100, s[64:65]
	v_add_f32_dpp v88, v140, v140 quad_perm:[1,0,3,2] row_mask:0xf bank_mask:0xf
	v_add_f32_dpp v89, v141, v141 quad_perm:[1,0,3,2] row_mask:0xf bank_mask:0xf
	v_add_f32_dpp v90, v142, v142 quad_perm:[1,0,3,2] row_mask:0xf bank_mask:0xf
	v_add_f32_dpp v91, v143, v143 quad_perm:[1,0,3,2] row_mask:0xf bank_mask:0xf
	v_cndmask_b32_e32 v88, v90, v88, vcc
	v_cndmask_b32_e32 v89, v91, v89, vcc
	v_add_f32_dpp v94, v92, v92 quad_perm:[2,3,0,1] row_mask:0xf bank_mask:0xf
	v_add_f32_dpp v95, v93, v93 quad_perm:[2,3,0,1] row_mask:0xf bank_mask:0xf
	v_cndmask_b32_e64 v92, v95, v94, s[4:5]
	s_waitcnt vmcnt(20)
	s_nop 0
	v_pk_mul_f32 v[140:141], v[236:237], v[80:81] op_sel_hi:[1,0]
	v_pk_mul_f32 v[142:143], v[244:245], v[80:81] op_sel_hi:[1,0]
	v_pk_fma_f32 v[140:141], v[238:239], v[80:81], v[140:141] op_sel:[0,1,0]
	v_pk_fma_f32 v[142:143], v[246:247], v[80:81], v[142:143] op_sel:[0,1,0]
	v_pk_fma_f32 v[140:141], v[240:241], v[82:83], v[140:141] op_sel_hi:[1,0,1]
	v_pk_fma_f32 v[142:143], v[248:249], v[82:83], v[142:143] op_sel_hi:[1,0,1]
	v_pk_fma_f32 v[140:141], v[242:243], v[82:83], v[140:141] op_sel:[0,1,0]
	v_pk_fma_f32 v[142:143], v[250:251], v[82:83], v[142:143] op_sel:[0,1,0]
	v_add_f32_dpp v108, v110, v109 row_ror:8 row_mask:0xf bank_mask:0xf
	v_add_f32_dpp v84, v252, v252 quad_perm:[1,0,3,2] row_mask:0xf bank_mask:0xf
	v_add_f32_dpp v85, v253, v253 quad_perm:[1,0,3,2] row_mask:0xf bank_mask:0xf
	v_add_f32_dpp v86, v254, v254 quad_perm:[1,0,3,2] row_mask:0xf bank_mask:0xf
	v_add_f32_dpp v87, v255, v255 quad_perm:[1,0,3,2] row_mask:0xf bank_mask:0xf
	v_cndmask_b32_e32 v84, v86, v84, vcc
	v_cndmask_b32_e32 v85, v87, v85, vcc
	v_add_f32_dpp v90, v88, v88 quad_perm:[2,3,0,1] row_mask:0xf bank_mask:0xf
	v_add_f32_dpp v91, v89, v89 quad_perm:[2,3,0,1] row_mask:0xf bank_mask:0xf
	v_cndmask_b32_e64 v88, v91, v90, s[4:5]
	v_cndmask_b32_e64 v93, v88, v92, s[6:7]
	v_cndmask_b32_e64 v94, v92, v88, s[6:7]
	s_waitcnt vmcnt(19)
; DI void attn_sample_item(const Params& p, int item, ldsp lds, int tid_) {
;     ...
;   SC_SCORE(kvA, 0)
;   SC_SCORE(kvB, 1)
	s_nop 0
	v_pk_mul_f32 v[252:253], v[236:237], v[76:77] op_sel_hi:[1,0]
	v_pk_mul_f32 v[254:255], v[244:245], v[76:77] op_sel_hi:[1,0]
	v_pk_fma_f32 v[252:253], v[238:239], v[76:77], v[252:253] op_sel:[0,1,0]
	v_pk_fma_f32 v[254:255], v[246:247], v[76:77], v[254:255] op_sel:[0,1,0]
	v_pk_fma_f32 v[252:253], v[240:241], v[78:79], v[252:253] op_sel_hi:[1,0,1]
	v_pk_fma_f32 v[254:255], v[248:249], v[78:79], v[254:255] op_sel_hi:[1,0,1]
	v_pk_fma_f32 v[252:253], v[242:243], v[78:79], v[252:253] op_sel:[0,1,0]
	v_pk_fma_f32 v[254:255], v[250:251], v[78:79], v[254:255] op_sel:[0,1,0]
	v_permlane16_swap_b32_e32 v124, v108
	v_add_f32_e32 v124, v124, v108
	v_add_f32_dpp v92, v94, v93 row_ror:4 row_mask:0xf bank_mask:0xf
	v_add_f32_dpp v80, v140, v140 quad_perm:[1,0,3,2] row_mask:0xf bank_mask:0xf
	v_add_f32_dpp v81, v141, v141 quad_perm:[1,0,3,2] row_mask:0xf bank_mask:0xf
	v_add_f32_dpp v82, v142, v142 quad_perm:[1,0,3,2] row_mask:0xf bank_mask:0xf
	v_add_f32_dpp v83, v143, v143 quad_perm:[1,0,3,2] row_mask:0xf bank_mask:0xf
	v_cndmask_b32_e32 v80, v82, v80, vcc
	v_cndmask_b32_e32 v81, v83, v81, vcc
	v_add_f32_dpp v86, v84, v84 quad_perm:[2,3,0,1] row_mask:0xf bank_mask:0xf
	v_add_f32_dpp v87, v85, v85 quad_perm:[2,3,0,1] row_mask:0xf bank_mask:0xf
	v_cndmask_b32_e64 v84, v87, v86, s[4:5]
	s_waitcnt vmcnt(18)
	s_nop 0
	v_pk_mul_f32 v[140:141], v[236:237], v[72:73] op_sel_hi:[1,0]
	v_pk_mul_f32 v[142:143], v[244:245], v[72:73] op_sel_hi:[1,0]
	v_pk_fma_f32 v[140:141], v[238:239], v[72:73], v[140:141] op_sel:[0,1,0]
	v_pk_fma_f32 v[142:143], v[246:247], v[72:73], v[142:143] op_sel:[0,1,0]
	v_pk_fma_f32 v[140:141], v[240:241], v[74:75], v[140:141] op_sel_hi:[1,0,1]
	v_pk_fma_f32 v[142:143], v[248:249], v[74:75], v[142:143] op_sel_hi:[1,0,1]
	v_pk_fma_f32 v[140:141], v[242:243], v[74:75], v[140:141] op_sel:[0,1,0]
	v_pk_fma_f32 v[142:143], v[250:251], v[74:75], v[142:143] op_sel:[0,1,0]
	v_add_f32_dpp v76, v252, v252 quad_perm:[1,0,3,2] row_mask:0xf bank_mask:0xf
	v_add_f32_dpp v77, v253, v253 quad_perm:[1,0,3,2] row_mask:0xf bank_mask:0xf
	v_add_f32_dpp v78, v254, v254 quad_perm:[1,0,3,2] row_mask:0xf bank_mask:0xf
	v_add_f32_dpp v79, v255, v255 quad_perm:[1,0,3,2] row_mask:0xf bank_mask:0xf
	v_cndmask_b32_e32 v76, v78, v76, vcc
	v_cndmask_b32_e32 v77, v79, v77, vcc
	v_add_f32_dpp v82, v80, v80 quad_perm:[2,3,0,1] row_mask:0xf bank_mask:0xf
	v_add_f32_dpp v83, v81, v81 quad_perm:[2,3,0,1] row_mask:0xf bank_mask:0xf
	v_cndmask_b32_e64 v80, v83, v82, s[4:5]
	v_cndmask_b32_e64 v85, v80, v84, s[6:7]
	v_cndmask_b32_e64 v86, v84, v80, s[6:7]
	s_waitcnt vmcnt(17)
	s_nop 0
	v_pk_mul_f32 v[252:253], v[236:237], v[68:69] op_sel_hi:[1,0]
	v_pk_mul_f32 v[254:255], v[244:245], v[68:69] op_sel_hi:[1,0]
	v_pk_fma_f32 v[252:253], v[238:239], v[68:69], v[252:253] op_sel:[0,1,0]
	v_pk_fma_f32 v[254:255], v[246:247], v[68:69], v[254:255] op_sel:[0,1,0]
	v_pk_fma_f32 v[252:253], v[240:241], v[70:71], v[252:253] op_sel_hi:[1,0,1]
	v_pk_fma_f32 v[254:255], v[248:249], v[70:71], v[254:255] op_sel_hi:[1,0,1]
	v_pk_fma_f32 v[252:253], v[242:243], v[70:71], v[252:253] op_sel:[0,1,0]
	v_pk_fma_f32 v[254:255], v[250:251], v[70:71], v[254:255] op_sel:[0,1,0]
	v_add_f32_dpp v84, v86, v85 row_ror:4 row_mask:0xf bank_mask:0xf
	v_cndmask_b32_e64 v93, v84, v92, s[64:65]
	v_cndmask_b32_e64 v94, v92, v84, s[64:65]
	v_add_f32_dpp v72, v140, v140 quad_perm:[1,0,3,2] row_mask:0xf bank_mask:0xf
	v_add_f32_dpp v73, v141, v141 quad_perm:[1,0,3,2] row_mask:0xf bank_mask:0xf
	v_add_f32_dpp v74, v142, v142 quad_perm:[1,0,3,2] row_mask:0xf bank_mask:0xf
	v_add_f32_dpp v75, v143, v143 quad_perm:[1,0,3,2] row_mask:0xf bank_mask:0xf
	v_cndmask_b32_e32 v72, v74, v72, vcc
	v_cndmask_b32_e32 v73, v75, v73, vcc
	v_add_f32_dpp v78, v76, v76 quad_perm:[2,3,0,1] row_mask:0xf bank_mask:0xf
	v_add_f32_dpp v79, v77, v77 quad_perm:[2,3,0,1] row_mask:0xf bank_mask:0xf
	v_cndmask_b32_e64 v76, v79, v78, s[4:5]
	s_waitcnt vmcnt(16)
	s_nop 0
	v_pk_mul_f32 v[140:141], v[236:237], v[64:65] op_sel_hi:[1,0]
	v_pk_mul_f32 v[142:143], v[244:245], v[64:65] op_sel_hi:[1,0]
	v_pk_fma_f32 v[140:141], v[238:239], v[64:65], v[140:141] op_sel:[0,1,0]
	v_pk_fma_f32 v[142:143], v[246:247], v[64:65], v[142:143] op_sel:[0,1,0]
	v_pk_fma_f32 v[140:141], v[240:241], v[66:67], v[140:141] op_sel_hi:[1,0,1]
	v_pk_fma_f32 v[142:143], v[248:249], v[66:67], v[142:143] op_sel_hi:[1,0,1]
	v_pk_fma_f32 v[140:141], v[242:243], v[66:67], v[140:141] op_sel:[0,1,0]
	v_pk_fma_f32 v[142:143], v[250:251], v[66:67], v[142:143] op_sel:[0,1,0]
	v_add_f32_dpp v92, v94, v93 row_ror:8 row_mask:0xf bank_mask:0xf
	v_add_f32_dpp v68, v252, v252 quad_perm:[1,0,3,2] row_mask:0xf bank_mask:0xf
	v_add_f32_dpp v69, v253, v253 quad_perm:[1,0,3,2] row_mask:0xf bank_mask:0xf
	v_add_f32_dpp v70, v254, v254 quad_perm:[1,0,3,2] row_mask:0xf bank_mask:0xf
	v_add_f32_dpp v71, v255, v255 quad_perm:[1,0,3,2] row_mask:0xf bank_mask:0xf
	v_cndmask_b32_e32 v68, v70, v68, vcc
	v_cndmask_b32_e32 v69, v71, v69, vcc
	v_add_f32_dpp v74, v72, v72 quad_perm:[2,3,0,1] row_mask:0xf bank_mask:0xf
	v_add_f32_dpp v75, v73, v73 quad_perm:[2,3,0,1] row_mask:0xf bank_mask:0xf
	v_cndmask_b32_e64 v72, v75, v74, s[4:5]
	v_cndmask_b32_e64 v77, v72, v76, s[6:7]
	v_cndmask_b32_e64 v78, v76, v72, s[6:7]
	s_waitcnt vmcnt(15)
; DI void attn_sample_item(const Params& p, int item, ldsp lds, int tid_) {
;     ...
;   SC_SCORE(kvA, 0)
;   SC_SCORE(kvB, 1)
	s_nop 0
	v_pk_mul_f32 v[252:253], v[236:237], v[60:61] op_sel_hi:[1,0]
	v_pk_mul_f32 v[254:255], v[244:245], v[60:61] op_sel_hi:[1,0]
	v_pk_fma_f32 v[252:253], v[238:239], v[60:61], v[252:253] op_sel:[0,1,0]
	v_pk_fma_f32 v[254:255], v[246:247], v[60:61], v[254:255] op_sel:[0,1,0]
	v_pk_fma_f32 v[252:253], v[240:241], v[62:63], v[252:253] op_sel_hi:[1,0,1]
	v_pk_fma_f32 v[254:255], v[248:249], v[62:63], v[254:255] op_sel_hi:[1,0,1]
	v_pk_fma_f32 v[252:253], v[242:243], v[62:63], v[252:253] op_sel:[0,1,0]
	v_pk_fma_f32 v[254:255], v[250:251], v[62:63], v[254:255] op_sel:[0,1,0]
	v_add_f32_dpp v76, v78, v77 row_ror:4 row_mask:0xf bank_mask:0xf
	v_add_f32_dpp v64, v140, v140 quad_perm:[1,0,3,2] row_mask:0xf bank_mask:0xf
	v_add_f32_dpp v65, v141, v141 quad_perm:[1,0,3,2] row_mask:0xf bank_mask:0xf
	v_add_f32_dpp v66, v142, v142 quad_perm:[1,0,3,2] row_mask:0xf bank_mask:0xf
	v_add_f32_dpp v67, v143, v143 quad_perm:[1,0,3,2] row_mask:0xf bank_mask:0xf
	v_cndmask_b32_e32 v64, v66, v64, vcc
	v_cndmask_b32_e32 v65, v67, v65, vcc
	v_add_f32_dpp v70, v68, v68 quad_perm:[2,3,0,1] row_mask:0xf bank_mask:0xf
	v_add_f32_dpp v71, v69, v69 quad_perm:[2,3,0,1] row_mask:0xf bank_mask:0xf
	v_cndmask_b32_e64 v68, v71, v70, s[4:5]
	s_waitcnt vmcnt(14)
	s_nop 0
	v_pk_mul_f32 v[140:141], v[236:237], v[56:57] op_sel_hi:[1,0]
	v_pk_mul_f32 v[142:143], v[244:245], v[56:57] op_sel_hi:[1,0]
	v_pk_fma_f32 v[140:141], v[238:239], v[56:57], v[140:141] op_sel:[0,1,0]
	v_pk_fma_f32 v[142:143], v[246:247], v[56:57], v[142:143] op_sel:[0,1,0]
	v_pk_fma_f32 v[140:141], v[240:241], v[58:59], v[140:141] op_sel_hi:[1,0,1]
	v_pk_fma_f32 v[142:143], v[248:249], v[58:59], v[142:143] op_sel_hi:[1,0,1]
	v_pk_fma_f32 v[140:141], v[242:243], v[58:59], v[140:141] op_sel:[0,1,0]
	v_pk_fma_f32 v[142:143], v[250:251], v[58:59], v[142:143] op_sel:[0,1,0]
	v_add_f32_dpp v60, v252, v252 quad_perm:[1,0,3,2] row_mask:0xf bank_mask:0xf
	v_add_f32_dpp v61, v253, v253 quad_perm:[1,0,3,2] row_mask:0xf bank_mask:0xf
	v_add_f32_dpp v62, v254, v254 quad_perm:[1,0,3,2] row_mask:0xf bank_mask:0xf
	v_add_f32_dpp v63, v255, v255 quad_perm:[1,0,3,2] row_mask:0xf bank_mask:0xf
	v_cndmask_b32_e32 v60, v62, v60, vcc
	v_cndmask_b32_e32 v61, v63, v61, vcc
	v_add_f32_dpp v66, v64, v64 quad_perm:[2,3,0,1] row_mask:0xf bank_mask:0xf
	v_add_f32_dpp v67, v65, v65 quad_perm:[2,3,0,1] row_mask:0xf bank_mask:0xf
	v_cndmask_b32_e64 v64, v67, v66, s[4:5]
	v_cndmask_b32_e64 v69, v64, v68, s[6:7]
	v_cndmask_b32_e64 v70, v68, v64, s[6:7]
	s_waitcnt vmcnt(13)
	s_nop 0
	v_pk_mul_f32 v[252:253], v[236:237], v[52:53] op_sel_hi:[1,0]
	v_pk_mul_f32 v[254:255], v[244:245], v[52:53] op_sel_hi:[1,0]
	v_pk_fma_f32 v[252:253], v[238:239], v[52:53], v[252:253] op_sel:[0,1,0]
	v_pk_fma_f32 v[254:255], v[246:247], v[52:53], v[254:255] op_sel:[0,1,0]
	v_pk_fma_f32 v[252:253], v[240:241], v[54:55], v[252:253] op_sel_hi:[1,0,1]
	v_pk_fma_f32 v[254:255], v[248:249], v[54:55], v[254:255] op_sel_hi:[1,0,1]
	v_pk_fma_f32 v[252:253], v[242:243], v[54:55], v[252:253] op_sel:[0,1,0]
	v_pk_fma_f32 v[254:255], v[250:251], v[54:55], v[254:255] op_sel:[0,1,0]
	v_add_f32_dpp v68, v70, v69 row_ror:4 row_mask:0xf bank_mask:0xf
	v_cndmask_b32_e64 v77, v68, v76, s[64:65]
	v_cndmask_b32_e64 v78, v76, v68, s[64:65]
	v_add_f32_dpp v56, v140, v140 quad_perm:[1,0,3,2] row_mask:0xf bank_mask:0xf
	v_add_f32_dpp v57, v141, v141 quad_perm:[1,0,3,2] row_mask:0xf bank_mask:0xf
	v_add_f32_dpp v58, v142, v142 quad_perm:[1,0,3,2] row_mask:0xf bank_mask:0xf
	v_add_f32_dpp v59, v143, v143 quad_perm:[1,0,3,2] row_mask:0xf bank_mask:0xf
	v_cndmask_b32_e32 v56, v58, v56, vcc
	v_cndmask_b32_e32 v57, v59, v57, vcc
	v_add_f32_dpp v62, v60, v60 quad_perm:[2,3,0,1] row_mask:0xf bank_mask:0xf
	v_add_f32_dpp v63, v61, v61 quad_perm:[2,3,0,1] row_mask:0xf bank_mask:0xf
	v_cndmask_b32_e64 v60, v63, v62, s[4:5]
	s_waitcnt vmcnt(12)
	s_nop 0
	v_pk_mul_f32 v[140:141], v[236:237], v[48:49] op_sel_hi:[1,0]
	v_pk_mul_f32 v[142:143], v[244:245], v[48:49] op_sel_hi:[1,0]
	v_pk_fma_f32 v[140:141], v[238:239], v[48:49], v[140:141] op_sel:[0,1,0]
	v_pk_fma_f32 v[142:143], v[246:247], v[48:49], v[142:143] op_sel:[0,1,0]
	v_pk_fma_f32 v[140:141], v[240:241], v[50:51], v[140:141] op_sel_hi:[1,0,1]
	v_pk_fma_f32 v[142:143], v[248:249], v[50:51], v[142:143] op_sel_hi:[1,0,1]
	v_pk_fma_f32 v[140:141], v[242:243], v[50:51], v[140:141] op_sel:[0,1,0]
	v_pk_fma_f32 v[142:143], v[250:251], v[50:51], v[142:143] op_sel:[0,1,0]
	v_add_f32_dpp v76, v78, v77 row_ror:8 row_mask:0xf bank_mask:0xf
	v_add_f32_dpp v52, v252, v252 quad_perm:[1,0,3,2] row_mask:0xf bank_mask:0xf
	v_add_f32_dpp v53, v253, v253 quad_perm:[1,0,3,2] row_mask:0xf bank_mask:0xf
	v_add_f32_dpp v54, v254, v254 quad_perm:[1,0,3,2] row_mask:0xf bank_mask:0xf
	v_add_f32_dpp v55, v255, v255 quad_perm:[1,0,3,2] row_mask:0xf bank_mask:0xf
	v_cndmask_b32_e32 v52, v54, v52, vcc
	v_cndmask_b32_e32 v53, v55, v53, vcc
	v_add_f32_dpp v58, v56, v56 quad_perm:[2,3,0,1] row_mask:0xf bank_mask:0xf
	v_add_f32_dpp v59, v57, v57 quad_perm:[2,3,0,1] row_mask:0xf bank_mask:0xf
	v_cndmask_b32_e64 v56, v59, v58, s[4:5]
	v_cndmask_b32_e64 v61, v56, v60, s[6:7]
	v_cndmask_b32_e64 v62, v60, v56, s[6:7]
	s_waitcnt vmcnt(11)
; DI void attn_sample_item(const Params& p, int item, ldsp lds, int tid_) {
;     ...
;   SC_SCORE(kvA, 0)
;   SC_SCORE(kvB, 1)
	s_nop 0
	v_pk_mul_f32 v[252:253], v[236:237], v[44:45] op_sel_hi:[1,0]
	v_pk_mul_f32 v[254:255], v[244:245], v[44:45] op_sel_hi:[1,0]
	v_pk_fma_f32 v[252:253], v[238:239], v[44:45], v[252:253] op_sel:[0,1,0]
	v_pk_fma_f32 v[254:255], v[246:247], v[44:45], v[254:255] op_sel:[0,1,0]
	v_pk_fma_f32 v[252:253], v[240:241], v[46:47], v[252:253] op_sel_hi:[1,0,1]
	v_pk_fma_f32 v[254:255], v[248:249], v[46:47], v[254:255] op_sel_hi:[1,0,1]
	v_pk_fma_f32 v[252:253], v[242:243], v[46:47], v[252:253] op_sel:[0,1,0]
	v_pk_fma_f32 v[254:255], v[250:251], v[46:47], v[254:255] op_sel:[0,1,0]
	v_permlane16_swap_b32_e32 v92, v76
	v_add_f32_e32 v92, v92, v76
	v_add_f32_dpp v60, v62, v61 row_ror:4 row_mask:0xf bank_mask:0xf
	v_add_f32_dpp v48, v140, v140 quad_perm:[1,0,3,2] row_mask:0xf bank_mask:0xf
	v_add_f32_dpp v49, v141, v141 quad_perm:[1,0,3,2] row_mask:0xf bank_mask:0xf
	v_add_f32_dpp v50, v142, v142 quad_perm:[1,0,3,2] row_mask:0xf bank_mask:0xf
	v_add_f32_dpp v51, v143, v143 quad_perm:[1,0,3,2] row_mask:0xf bank_mask:0xf
	v_cndmask_b32_e32 v48, v50, v48, vcc
	v_cndmask_b32_e32 v49, v51, v49, vcc
	v_add_f32_dpp v54, v52, v52 quad_perm:[2,3,0,1] row_mask:0xf bank_mask:0xf
	v_add_f32_dpp v55, v53, v53 quad_perm:[2,3,0,1] row_mask:0xf bank_mask:0xf
	v_cndmask_b32_e64 v52, v55, v54, s[4:5]
	s_waitcnt vmcnt(10)
	s_nop 0
	v_pk_mul_f32 v[140:141], v[236:237], v[40:41] op_sel_hi:[1,0]
	v_pk_mul_f32 v[142:143], v[244:245], v[40:41] op_sel_hi:[1,0]
	v_pk_fma_f32 v[140:141], v[238:239], v[40:41], v[140:141] op_sel:[0,1,0]
	v_pk_fma_f32 v[142:143], v[246:247], v[40:41], v[142:143] op_sel:[0,1,0]
	v_pk_fma_f32 v[140:141], v[240:241], v[42:43], v[140:141] op_sel_hi:[1,0,1]
	v_pk_fma_f32 v[142:143], v[248:249], v[42:43], v[142:143] op_sel_hi:[1,0,1]
	v_pk_fma_f32 v[140:141], v[242:243], v[42:43], v[140:141] op_sel:[0,1,0]
	v_pk_fma_f32 v[142:143], v[250:251], v[42:43], v[142:143] op_sel:[0,1,0]
	v_permlane32_swap_b32_e32 v124, v92
	v_add_f32_e32 v124, v124, v92
	ds_write_b32 v235, v124
	v_add_f32_dpp v44, v252, v252 quad_perm:[1,0,3,2] row_mask:0xf bank_mask:0xf
	v_add_f32_dpp v45, v253, v253 quad_perm:[1,0,3,2] row_mask:0xf bank_mask:0xf
	v_add_f32_dpp v46, v254, v254 quad_perm:[1,0,3,2] row_mask:0xf bank_mask:0xf
	v_add_f32_dpp v47, v255, v255 quad_perm:[1,0,3,2] row_mask:0xf bank_mask:0xf
	v_cndmask_b32_e32 v44, v46, v44, vcc
	v_cndmask_b32_e32 v45, v47, v45, vcc
	v_add_f32_dpp v50, v48, v48 quad_perm:[2,3,0,1] row_mask:0xf bank_mask:0xf
	v_add_f32_dpp v51, v49, v49 quad_perm:[2,3,0,1] row_mask:0xf bank_mask:0xf
	v_cndmask_b32_e64 v48, v51, v50, s[4:5]
	v_cndmask_b32_e64 v53, v48, v52, s[6:7]
	v_cndmask_b32_e64 v54, v52, v48, s[6:7]
	s_waitcnt vmcnt(9)
	s_nop 0
	v_pk_mul_f32 v[252:253], v[236:237], v[36:37] op_sel_hi:[1,0]
	v_pk_mul_f32 v[254:255], v[244:245], v[36:37] op_sel_hi:[1,0]
	v_pk_fma_f32 v[252:253], v[238:239], v[36:37], v[252:253] op_sel:[0,1,0]
	v_pk_fma_f32 v[254:255], v[246:247], v[36:37], v[254:255] op_sel:[0,1,0]
	v_pk_fma_f32 v[252:253], v[240:241], v[38:39], v[252:253] op_sel_hi:[1,0,1]
	v_pk_fma_f32 v[254:255], v[248:249], v[38:39], v[254:255] op_sel_hi:[1,0,1]
	v_pk_fma_f32 v[252:253], v[242:243], v[38:39], v[252:253] op_sel:[0,1,0]
	v_pk_fma_f32 v[254:255], v[250:251], v[38:39], v[254:255] op_sel:[0,1,0]
	v_add_f32_dpp v52, v54, v53 row_ror:4 row_mask:0xf bank_mask:0xf
	v_cndmask_b32_e64 v61, v52, v60, s[64:65]
	v_cndmask_b32_e64 v62, v60, v52, s[64:65]
	v_add_f32_dpp v40, v140, v140 quad_perm:[1,0,3,2] row_mask:0xf bank_mask:0xf
	v_add_f32_dpp v41, v141, v141 quad_perm:[1,0,3,2] row_mask:0xf bank_mask:0xf
	v_add_f32_dpp v42, v142, v142 quad_perm:[1,0,3,2] row_mask:0xf bank_mask:0xf
	v_add_f32_dpp v43, v143, v143 quad_perm:[1,0,3,2] row_mask:0xf bank_mask:0xf
	v_cndmask_b32_e32 v40, v42, v40, vcc
	v_cndmask_b32_e32 v41, v43, v41, vcc
	v_add_f32_dpp v46, v44, v44 quad_perm:[2,3,0,1] row_mask:0xf bank_mask:0xf
	v_add_f32_dpp v47, v45, v45 quad_perm:[2,3,0,1] row_mask:0xf bank_mask:0xf
	v_cndmask_b32_e64 v44, v47, v46, s[4:5]
	s_waitcnt vmcnt(8)
	s_nop 0
	v_pk_mul_f32 v[140:141], v[236:237], v[32:33] op_sel_hi:[1,0]
	v_pk_mul_f32 v[142:143], v[244:245], v[32:33] op_sel_hi:[1,0]
	v_pk_fma_f32 v[140:141], v[238:239], v[32:33], v[140:141] op_sel:[0,1,0]
	v_pk_fma_f32 v[142:143], v[246:247], v[32:33], v[142:143] op_sel:[0,1,0]
	v_pk_fma_f32 v[140:141], v[240:241], v[34:35], v[140:141] op_sel_hi:[1,0,1]
	v_pk_fma_f32 v[142:143], v[248:249], v[34:35], v[142:143] op_sel_hi:[1,0,1]
	v_pk_fma_f32 v[140:141], v[242:243], v[34:35], v[140:141] op_sel:[0,1,0]
	v_pk_fma_f32 v[142:143], v[250:251], v[34:35], v[142:143] op_sel:[0,1,0]
	v_add_f32_dpp v60, v62, v61 row_ror:8 row_mask:0xf bank_mask:0xf
	v_add_f32_dpp v36, v252, v252 quad_perm:[1,0,3,2] row_mask:0xf bank_mask:0xf
	v_add_f32_dpp v37, v253, v253 quad_perm:[1,0,3,2] row_mask:0xf bank_mask:0xf
	v_add_f32_dpp v38, v254, v254 quad_perm:[1,0,3,2] row_mask:0xf bank_mask:0xf
	v_add_f32_dpp v39, v255, v255 quad_perm:[1,0,3,2] row_mask:0xf bank_mask:0xf
	v_cndmask_b32_e32 v36, v38, v36, vcc
	v_cndmask_b32_e32 v37, v39, v37, vcc
	v_add_f32_dpp v42, v40, v40 quad_perm:[2,3,0,1] row_mask:0xf bank_mask:0xf
	v_add_f32_dpp v43, v41, v41 quad_perm:[2,3,0,1] row_mask:0xf bank_mask:0xf
	v_cndmask_b32_e64 v40, v43, v42, s[4:5]
	v_cndmask_b32_e64 v45, v40, v44, s[6:7]
	v_cndmask_b32_e64 v46, v44, v40, s[6:7]
	s_waitcnt vmcnt(7)
; DI void attn_sample_item(const Params& p, int item, ldsp lds, int tid_) {
;     ...
;   SC_SCORE(kvA, 0)
;   SC_SCORE(kvB, 1)
	s_nop 0
	v_pk_mul_f32 v[252:253], v[236:237], v[28:29] op_sel_hi:[1,0]
	v_pk_mul_f32 v[254:255], v[244:245], v[28:29] op_sel_hi:[1,0]
	v_pk_fma_f32 v[252:253], v[238:239], v[28:29], v[252:253] op_sel:[0,1,0]
	v_pk_fma_f32 v[254:255], v[246:247], v[28:29], v[254:255] op_sel:[0,1,0]
	v_pk_fma_f32 v[252:253], v[240:241], v[30:31], v[252:253] op_sel_hi:[1,0,1]
	v_pk_fma_f32 v[254:255], v[248:249], v[30:31], v[254:255] op_sel_hi:[1,0,1]
	v_pk_fma_f32 v[252:253], v[242:243], v[30:31], v[252:253] op_sel:[0,1,0]
	v_pk_fma_f32 v[254:255], v[250:251], v[30:31], v[254:255] op_sel:[0,1,0]
	v_add_f32_dpp v44, v46, v45 row_ror:4 row_mask:0xf bank_mask:0xf
	v_add_f32_dpp v32, v140, v140 quad_perm:[1,0,3,2] row_mask:0xf bank_mask:0xf
	v_add_f32_dpp v33, v141, v141 quad_perm:[1,0,3,2] row_mask:0xf bank_mask:0xf
	v_add_f32_dpp v34, v142, v142 quad_perm:[1,0,3,2] row_mask:0xf bank_mask:0xf
	v_add_f32_dpp v35, v143, v143 quad_perm:[1,0,3,2] row_mask:0xf bank_mask:0xf
	v_cndmask_b32_e32 v32, v34, v32, vcc
	v_cndmask_b32_e32 v33, v35, v33, vcc
	v_add_f32_dpp v38, v36, v36 quad_perm:[2,3,0,1] row_mask:0xf bank_mask:0xf
	v_add_f32_dpp v39, v37, v37 quad_perm:[2,3,0,1] row_mask:0xf bank_mask:0xf
	v_cndmask_b32_e64 v36, v39, v38, s[4:5]
	s_waitcnt vmcnt(6)
	s_nop 0
	v_pk_mul_f32 v[140:141], v[236:237], v[24:25] op_sel_hi:[1,0]
	v_pk_mul_f32 v[142:143], v[244:245], v[24:25] op_sel_hi:[1,0]
	v_pk_fma_f32 v[140:141], v[238:239], v[24:25], v[140:141] op_sel:[0,1,0]
	v_pk_fma_f32 v[142:143], v[246:247], v[24:25], v[142:143] op_sel:[0,1,0]
	v_pk_fma_f32 v[140:141], v[240:241], v[26:27], v[140:141] op_sel_hi:[1,0,1]
	v_pk_fma_f32 v[142:143], v[248:249], v[26:27], v[142:143] op_sel_hi:[1,0,1]
	v_pk_fma_f32 v[140:141], v[242:243], v[26:27], v[140:141] op_sel:[0,1,0]
	v_pk_fma_f32 v[142:143], v[250:251], v[26:27], v[142:143] op_sel:[0,1,0]
	v_add_f32_dpp v28, v252, v252 quad_perm:[1,0,3,2] row_mask:0xf bank_mask:0xf
	v_add_f32_dpp v29, v253, v253 quad_perm:[1,0,3,2] row_mask:0xf bank_mask:0xf
	v_add_f32_dpp v30, v254, v254 quad_perm:[1,0,3,2] row_mask:0xf bank_mask:0xf
	v_add_f32_dpp v31, v255, v255 quad_perm:[1,0,3,2] row_mask:0xf bank_mask:0xf
	v_cndmask_b32_e32 v28, v30, v28, vcc
	v_cndmask_b32_e32 v29, v31, v29, vcc
	v_add_f32_dpp v34, v32, v32 quad_perm:[2,3,0,1] row_mask:0xf bank_mask:0xf
	v_add_f32_dpp v35, v33, v33 quad_perm:[2,3,0,1] row_mask:0xf bank_mask:0xf
	v_cndmask_b32_e64 v32, v35, v34, s[4:5]
	v_cndmask_b32_e64 v37, v32, v36, s[6:7]
	v_cndmask_b32_e64 v38, v36, v32, s[6:7]
	s_waitcnt vmcnt(5)
	s_nop 0
	v_pk_mul_f32 v[252:253], v[236:237], v[20:21] op_sel_hi:[1,0]
	v_pk_mul_f32 v[254:255], v[244:245], v[20:21] op_sel_hi:[1,0]
	v_pk_fma_f32 v[252:253], v[238:239], v[20:21], v[252:253] op_sel:[0,1,0]
	v_pk_fma_f32 v[254:255], v[246:247], v[20:21], v[254:255] op_sel:[0,1,0]
	v_pk_fma_f32 v[252:253], v[240:241], v[22:23], v[252:253] op_sel_hi:[1,0,1]
	v_pk_fma_f32 v[254:255], v[248:249], v[22:23], v[254:255] op_sel_hi:[1,0,1]
	v_pk_fma_f32 v[252:253], v[242:243], v[22:23], v[252:253] op_sel:[0,1,0]
	v_pk_fma_f32 v[254:255], v[250:251], v[22:23], v[254:255] op_sel:[0,1,0]
	v_add_f32_dpp v36, v38, v37 row_ror:4 row_mask:0xf bank_mask:0xf
	v_cndmask_b32_e64 v45, v36, v44, s[64:65]
	v_cndmask_b32_e64 v46, v44, v36, s[64:65]
	v_add_f32_dpp v24, v140, v140 quad_perm:[1,0,3,2] row_mask:0xf bank_mask:0xf
	v_add_f32_dpp v25, v141, v141 quad_perm:[1,0,3,2] row_mask:0xf bank_mask:0xf
	v_add_f32_dpp v26, v142, v142 quad_perm:[1,0,3,2] row_mask:0xf bank_mask:0xf
	v_add_f32_dpp v27, v143, v143 quad_perm:[1,0,3,2] row_mask:0xf bank_mask:0xf
	v_cndmask_b32_e32 v24, v26, v24, vcc
	v_cndmask_b32_e32 v25, v27, v25, vcc
	v_add_f32_dpp v30, v28, v28 quad_perm:[2,3,0,1] row_mask:0xf bank_mask:0xf
	v_add_f32_dpp v31, v29, v29 quad_perm:[2,3,0,1] row_mask:0xf bank_mask:0xf
	v_cndmask_b32_e64 v28, v31, v30, s[4:5]
	s_waitcnt vmcnt(4)
	s_nop 0
	v_pk_mul_f32 v[140:141], v[236:237], v[16:17] op_sel_hi:[1,0]
	v_pk_mul_f32 v[142:143], v[244:245], v[16:17] op_sel_hi:[1,0]
	v_pk_fma_f32 v[140:141], v[238:239], v[16:17], v[140:141] op_sel:[0,1,0]
	v_pk_fma_f32 v[142:143], v[246:247], v[16:17], v[142:143] op_sel:[0,1,0]
	v_pk_fma_f32 v[140:141], v[240:241], v[18:19], v[140:141] op_sel_hi:[1,0,1]
	v_pk_fma_f32 v[142:143], v[248:249], v[18:19], v[142:143] op_sel_hi:[1,0,1]
	v_pk_fma_f32 v[140:141], v[242:243], v[18:19], v[140:141] op_sel:[0,1,0]
	v_pk_fma_f32 v[142:143], v[250:251], v[18:19], v[142:143] op_sel:[0,1,0]
	v_add_f32_dpp v44, v46, v45 row_ror:8 row_mask:0xf bank_mask:0xf
	v_add_f32_dpp v20, v252, v252 quad_perm:[1,0,3,2] row_mask:0xf bank_mask:0xf
	v_add_f32_dpp v21, v253, v253 quad_perm:[1,0,3,2] row_mask:0xf bank_mask:0xf
	v_add_f32_dpp v22, v254, v254 quad_perm:[1,0,3,2] row_mask:0xf bank_mask:0xf
	v_add_f32_dpp v23, v255, v255 quad_perm:[1,0,3,2] row_mask:0xf bank_mask:0xf
	v_cndmask_b32_e32 v20, v22, v20, vcc
	v_cndmask_b32_e32 v21, v23, v21, vcc
	v_add_f32_dpp v26, v24, v24 quad_perm:[2,3,0,1] row_mask:0xf bank_mask:0xf
	v_add_f32_dpp v27, v25, v25 quad_perm:[2,3,0,1] row_mask:0xf bank_mask:0xf
	v_cndmask_b32_e64 v24, v27, v26, s[4:5]
	v_cndmask_b32_e64 v29, v24, v28, s[6:7]
	v_cndmask_b32_e64 v30, v28, v24, s[6:7]
	s_waitcnt vmcnt(3)
; DI void attn_sample_item(const Params& p, int item, ldsp lds, int tid_) {
;     ...
;   SC_SCORE(kvA, 0)
;   SC_SCORE(kvB, 1)
;     ...
;   f32x4 vvA[16], vvB[16];
; #pragma unroll
;   for (int j = 0; j < 16; ++j) vvA[j] = __builtin_nontemporal_load((const f32x4*)(cv + (size_t)(wid * 32 + j) * 1024 + lane * 4));
	s_nop 0
	v_pk_mul_f32 v[252:253], v[236:237], v[12:13] op_sel_hi:[1,0]
	v_pk_mul_f32 v[254:255], v[244:245], v[12:13] op_sel_hi:[1,0]
	v_pk_fma_f32 v[252:253], v[238:239], v[12:13], v[252:253] op_sel:[0,1,0]
	v_pk_fma_f32 v[254:255], v[246:247], v[12:13], v[254:255] op_sel:[0,1,0]
	v_pk_fma_f32 v[252:253], v[240:241], v[14:15], v[252:253] op_sel_hi:[1,0,1]
	v_pk_fma_f32 v[254:255], v[248:249], v[14:15], v[254:255] op_sel_hi:[1,0,1]
	v_pk_fma_f32 v[252:253], v[242:243], v[14:15], v[252:253] op_sel:[0,1,0]
	v_pk_fma_f32 v[254:255], v[250:251], v[14:15], v[254:255] op_sel:[0,1,0]
	v_permlane16_swap_b32_e32 v60, v44
	v_add_f32_e32 v60, v60, v44
	v_add_f32_dpp v28, v30, v29 row_ror:4 row_mask:0xf bank_mask:0xf
	v_add_f32_dpp v16, v140, v140 quad_perm:[1,0,3,2] row_mask:0xf bank_mask:0xf
	v_add_f32_dpp v17, v141, v141 quad_perm:[1,0,3,2] row_mask:0xf bank_mask:0xf
	v_add_f32_dpp v18, v142, v142 quad_perm:[1,0,3,2] row_mask:0xf bank_mask:0xf
	v_add_f32_dpp v19, v143, v143 quad_perm:[1,0,3,2] row_mask:0xf bank_mask:0xf
	v_cndmask_b32_e32 v16, v18, v16, vcc
	v_cndmask_b32_e32 v17, v19, v17, vcc
	v_add_f32_dpp v22, v20, v20 quad_perm:[2,3,0,1] row_mask:0xf bank_mask:0xf
	v_add_f32_dpp v23, v21, v21 quad_perm:[2,3,0,1] row_mask:0xf bank_mask:0xf
	v_cndmask_b32_e64 v20, v23, v22, s[4:5]
	s_waitcnt vmcnt(2)
	s_nop 0
	v_pk_mul_f32 v[140:141], v[236:237], v[8:9] op_sel_hi:[1,0]
	v_pk_mul_f32 v[142:143], v[244:245], v[8:9] op_sel_hi:[1,0]
	v_pk_fma_f32 v[140:141], v[238:239], v[8:9], v[140:141] op_sel:[0,1,0]
	v_pk_fma_f32 v[142:143], v[246:247], v[8:9], v[142:143] op_sel:[0,1,0]
	v_pk_fma_f32 v[140:141], v[240:241], v[10:11], v[140:141] op_sel_hi:[1,0,1]
	v_pk_fma_f32 v[142:143], v[248:249], v[10:11], v[142:143] op_sel_hi:[1,0,1]
	v_pk_fma_f32 v[140:141], v[242:243], v[10:11], v[140:141] op_sel:[0,1,0]
	v_pk_fma_f32 v[142:143], v[250:251], v[10:11], v[142:143] op_sel:[0,1,0]
	v_add_f32_dpp v12, v252, v252 quad_perm:[1,0,3,2] row_mask:0xf bank_mask:0xf
	v_add_f32_dpp v13, v253, v253 quad_perm:[1,0,3,2] row_mask:0xf bank_mask:0xf
	v_add_f32_dpp v14, v254, v254 quad_perm:[1,0,3,2] row_mask:0xf bank_mask:0xf
	v_add_f32_dpp v15, v255, v255 quad_perm:[1,0,3,2] row_mask:0xf bank_mask:0xf
	v_cndmask_b32_e32 v12, v14, v12, vcc
	v_cndmask_b32_e32 v13, v15, v13, vcc
	v_add_f32_dpp v18, v16, v16 quad_perm:[2,3,0,1] row_mask:0xf bank_mask:0xf
	v_add_f32_dpp v19, v17, v17 quad_perm:[2,3,0,1] row_mask:0xf bank_mask:0xf
	v_cndmask_b32_e64 v16, v19, v18, s[4:5]
	v_cndmask_b32_e64 v21, v16, v20, s[6:7]
	v_cndmask_b32_e64 v22, v20, v16, s[6:7]
	s_waitcnt vmcnt(1)
	s_nop 0
	v_pk_mul_f32 v[252:253], v[236:237], v[4:5] op_sel_hi:[1,0]
	v_pk_mul_f32 v[254:255], v[244:245], v[4:5] op_sel_hi:[1,0]
	v_pk_fma_f32 v[252:253], v[238:239], v[4:5], v[252:253] op_sel:[0,1,0]
	v_pk_fma_f32 v[254:255], v[246:247], v[4:5], v[254:255] op_sel:[0,1,0]
	v_pk_fma_f32 v[252:253], v[240:241], v[6:7], v[252:253] op_sel_hi:[1,0,1]
	v_pk_fma_f32 v[254:255], v[248:249], v[6:7], v[254:255] op_sel_hi:[1,0,1]
	v_pk_fma_f32 v[252:253], v[242:243], v[6:7], v[252:253] op_sel:[0,1,0]
	v_pk_fma_f32 v[254:255], v[250:251], v[6:7], v[254:255] op_sel:[0,1,0]
	v_add_f32_dpp v20, v22, v21 row_ror:4 row_mask:0xf bank_mask:0xf
	v_cndmask_b32_e64 v29, v20, v28, s[64:65]
	v_cndmask_b32_e64 v30, v28, v20, s[64:65]
	v_add_f32_dpp v8, v140, v140 quad_perm:[1,0,3,2] row_mask:0xf bank_mask:0xf
	v_add_f32_dpp v9, v141, v141 quad_perm:[1,0,3,2] row_mask:0xf bank_mask:0xf
	v_add_f32_dpp v10, v142, v142 quad_perm:[1,0,3,2] row_mask:0xf bank_mask:0xf
	v_add_f32_dpp v11, v143, v143 quad_perm:[1,0,3,2] row_mask:0xf bank_mask:0xf
	v_cndmask_b32_e32 v8, v10, v8, vcc
	v_cndmask_b32_e32 v9, v11, v9, vcc
	v_add_f32_dpp v14, v12, v12 quad_perm:[2,3,0,1] row_mask:0xf bank_mask:0xf
	v_add_f32_dpp v15, v13, v13 quad_perm:[2,3,0,1] row_mask:0xf bank_mask:0xf
	v_cndmask_b32_e64 v12, v15, v14, s[4:5]
	s_waitcnt vmcnt(0)
	s_nop 0
	v_pk_mul_f32 v[140:141], v[236:237], v[0:1] op_sel_hi:[1,0]
	v_pk_mul_f32 v[142:143], v[244:245], v[0:1] op_sel_hi:[1,0]
	v_pk_fma_f32 v[140:141], v[238:239], v[0:1], v[140:141] op_sel:[0,1,0]
	v_pk_fma_f32 v[142:143], v[246:247], v[0:1], v[142:143] op_sel:[0,1,0]
	v_pk_fma_f32 v[140:141], v[240:241], v[2:3], v[140:141] op_sel_hi:[1,0,1]
	v_pk_fma_f32 v[142:143], v[248:249], v[2:3], v[142:143] op_sel_hi:[1,0,1]
	v_pk_fma_f32 v[140:141], v[242:243], v[2:3], v[140:141] op_sel:[0,1,0]
	v_pk_fma_f32 v[142:143], v[250:251], v[2:3], v[142:143] op_sel:[0,1,0]
	v_add_f32_dpp v28, v30, v29 row_ror:8 row_mask:0xf bank_mask:0xf
	v_add_f32_dpp v4, v252, v252 quad_perm:[1,0,3,2] row_mask:0xf bank_mask:0xf
	v_add_f32_dpp v5, v253, v253 quad_perm:[1,0,3,2] row_mask:0xf bank_mask:0xf
	v_add_f32_dpp v6, v254, v254 quad_perm:[1,0,3,2] row_mask:0xf bank_mask:0xf
	v_add_f32_dpp v7, v255, v255 quad_perm:[1,0,3,2] row_mask:0xf bank_mask:0xf
	v_cndmask_b32_e32 v4, v6, v4, vcc
	v_cndmask_b32_e32 v5, v7, v5, vcc
	v_add_f32_dpp v10, v8, v8 quad_perm:[2,3,0,1] row_mask:0xf bank_mask:0xf
	v_add_f32_dpp v11, v9, v9 quad_perm:[2,3,0,1] row_mask:0xf bank_mask:0xf
	v_cndmask_b32_e64 v8, v11, v10, s[4:5]
	v_cndmask_b32_e64 v13, v8, v12, s[6:7]
	v_cndmask_b32_e64 v14, v12, v8, s[6:7]
	s_nop 1
	s_nop 0
	v_add_f32_dpp v12, v14, v13 row_ror:4 row_mask:0xf bank_mask:0xf
	v_add_f32_dpp v0, v140, v140 quad_perm:[1,0,3,2] row_mask:0xf bank_mask:0xf
	v_add_f32_dpp v1, v141, v141 quad_perm:[1,0,3,2] row_mask:0xf bank_mask:0xf
	v_add_f32_dpp v2, v142, v142 quad_perm:[1,0,3,2] row_mask:0xf bank_mask:0xf
	v_add_f32_dpp v3, v143, v143 quad_perm:[1,0,3,2] row_mask:0xf bank_mask:0xf
	v_cndmask_b32_e32 v0, v2, v0, vcc
	v_cndmask_b32_e32 v1, v3, v1, vcc
	v_add_f32_dpp v6, v4, v4 quad_perm:[2,3,0,1] row_mask:0xf bank_mask:0xf
	v_add_f32_dpp v7, v5, v5 quad_perm:[2,3,0,1] row_mask:0xf bank_mask:0xf
	v_cndmask_b32_e64 v4, v7, v6, s[4:5]
	v_add_f32_dpp v2, v0, v0 quad_perm:[2,3,0,1] row_mask:0xf bank_mask:0xf
	v_add_f32_dpp v3, v1, v1 quad_perm:[2,3,0,1] row_mask:0xf bank_mask:0xf
	v_cndmask_b32_e64 v0, v3, v2, s[4:5]
	v_cndmask_b32_e64 v5, v0, v4, s[6:7]
	v_cndmask_b32_e64 v6, v4, v0, s[6:7]
	s_nop 1
	s_nop 0
	v_add_f32_dpp v4, v6, v5 row_ror:4 row_mask:0xf bank_mask:0xf
	v_cndmask_b32_e64 v13, v4, v12, s[64:65]
	v_cndmask_b32_e64 v14, v12, v4, s[64:65]
	s_nop 1
	s_nop 0
	v_add_f32_dpp v12, v14, v13 row_ror:8 row_mask:0xf bank_mask:0xf
	s_nop 1
	v_permlane16_swap_b32_e32 v28, v12
	v_add_f32_e32 v28, v28, v12
	s_nop 1
	v_permlane32_swap_b32_e32 v60, v28
	v_add_f32_e32 v60, v60, v28
	ds_write_b32 v235, v60 offset:64
	v_lshlrev_b32_e32 v2, 2, v223
	s_add_u32 s4, s14, s30
	s_addc_u32 s5, s15, s31
	v_lshlrev_b32_e32 v0, 2, v2
	s_waitcnt lgkmcnt(0)
; DI void lbar() { asm volatile("s_waitcnt lgkmcnt(0)" ::: "memory"); __builtin_amdgcn_s_barrier(); asm volatile("" ::: "memory"); }
; DI float wave_sum(float v) { for (int o = 32; o >= 1; o >>= 1) v += __shfl_xor(v, o); return v; }
; DI void attn_sample_item(const Params& p, int item, ldsp lds, int tid_) {
;     ...
;   for (int j = 0; j < 16; ++j) vvA[j] = __builtin_nontemporal_load((const f32x4*)(cv + (size_t)(wid * 32 + j) * 1024 + lane * 4));
;   lbar();
;   if (wid < 4) {
;     float v[4]; float mx = -1e30f;
; #pragma unroll
;     for (int j = 0; j < 4; ++j) { v[j] = SC[wid * 256 + j * 64 + lane]; mx = fmaxf(mx, v[j]); }
;     for (int o = 32; o >= 1; o >>= 1) mx = fmaxf(mx, __shfl_xor(mx, o));
;     float s = 0.f;
; #pragma unroll
;     for (int j = 0; j < 4; ++j) { v[j] = __expf(v[j] - mx); s += v[j]; }
;     s = wave_sum(s); const float inv = 1.f / s;
; #pragma unroll
;     for (int j = 0; j < 4; ++j) SC[wid * 256 + j * 64 + lane] = v[j] * inv;
;   }
	v_mov_b32_e32 v1, v145
	v_lshl_add_u64 v[0:1], s[4:5], 0, v[0:1]
	v_lshl_add_u64 v[4:5], v[0:1], 0, v[162:163]
	v_lshl_add_u64 v[6:7], v[0:1], 0, v[166:167]
	global_load_dwordx4 v[100:103], v[4:5], off nt
	global_load_dwordx4 v[92:95], v[6:7], off nt
	v_lshl_add_u64 v[4:5], v[0:1], 0, v[168:169]
	v_lshl_add_u64 v[6:7], v[0:1], 0, v[172:173]
	global_load_dwordx4 v[112:115], v[4:5], off nt
	global_load_dwordx4 v[108:111], v[6:7], off nt
	v_lshl_add_u64 v[4:5], v[0:1], 0, v[176:177]
	v_lshl_add_u64 v[6:7], v[0:1], 0, v[180:181]
	global_load_dwordx4 v[120:123], v[4:5], off nt
	global_load_dwordx4 v[116:119], v[6:7], off nt
	v_lshl_add_u64 v[4:5], v[0:1], 0, v[182:183]
	v_lshl_add_u64 v[6:7], v[0:1], 0, v[186:187]
	global_load_dwordx4 v[124:127], v[4:5], off nt
	global_load_dwordx4 v[104:107], v[6:7], off nt
	v_lshl_add_u64 v[4:5], v[0:1], 0, v[190:191]
	v_lshl_add_u64 v[6:7], v[0:1], 0, v[194:195]
	global_load_dwordx4 v[68:71], v[4:5], off nt
	global_load_dwordx4 v[64:67], v[6:7], off nt
	v_lshl_add_u64 v[4:5], v[0:1], 0, v[198:199]
	v_lshl_add_u64 v[6:7], v[0:1], 0, v[200:201]
	global_load_dwordx4 v[80:83], v[4:5], off nt
	global_load_dwordx4 v[76:79], v[6:7], off nt
	v_lshl_add_u64 v[4:5], v[0:1], 0, v[202:203]
	v_lshl_add_u64 v[6:7], v[0:1], 0, v[204:205]
	global_load_dwordx4 v[88:91], v[4:5], off nt
	global_load_dwordx4 v[84:87], v[6:7], off nt
	v_lshl_add_u64 v[4:5], v[0:1], 0, v[206:207]
	v_lshl_add_u64 v[6:7], v[0:1], 0, v[208:209]
	global_load_dwordx4 v[96:99], v[4:5], off nt
	global_load_dwordx4 v[72:75], v[6:7], off nt
	s_waitcnt lgkmcnt(0)
	s_barrier
	v_cmp_gt_i32_e32 vcc, 4, v210
	s_and_saveexec_b64 s[4:5], vcc
	s_cbranch_execz .LBB0_1603
	v_lshlrev_b32_e32 v3, 10, v210
	v_add3_u32 v6, 16, v3, v2
	ds_read2st64_b32 v[2:3], v6 offset1:1
	ds_read2st64_b32 v[4:5], v6 offset0:2 offset1:3
	s_waitcnt lgkmcnt(1)
	v_max3_f32 v7, v2, s39, v3
	s_waitcnt lgkmcnt(0)
	v_max3_f32 v7, v7, v4, v5
	ds_bpermute_b32 v8, v133, v7
	s_waitcnt lgkmcnt(0)
	v_max_f32_e32 v8, v8, v8
	v_max_f32_e32 v7, v7, v8
	ds_bpermute_b32 v8, v132, v7
	s_waitcnt lgkmcnt(0)
	v_max_f32_e32 v8, v8, v8
	v_max_f32_e32 v7, v7, v8
	ds_bpermute_b32 v8, v131, v7
	s_waitcnt lgkmcnt(0)
	v_max_f32_e32 v8, v8, v8
	v_max_f32_e32 v7, v7, v8
	ds_bpermute_b32 v8, v130, v7
	s_waitcnt lgkmcnt(0)
	v_max_f32_e32 v8, v8, v8
	v_max_f32_e32 v7, v7, v8
	ds_bpermute_b32 v8, v129, v7
	s_waitcnt lgkmcnt(0)
	v_max_f32_e32 v8, v8, v8
	v_max_f32_e32 v7, v7, v8
	ds_bpermute_b32 v8, v128, v7
	s_waitcnt lgkmcnt(0)
	v_max_f32_e32 v8, v8, v8
	v_max_f32_e32 v7, v7, v8
	v_sub_f32_e32 v2, v2, v7
	v_sub_f32_e32 v3, v3, v7
	v_mul_f32_e32 v2, 0x3fb8aa3b, v2
	v_sub_f32_e32 v4, v4, v7
	v_mul_f32_e32 v3, 0x3fb8aa3b, v3
	v_exp_f32_e32 v2, v2
	v_sub_f32_e32 v5, v5, v7
	v_mul_f32_e32 v4, 0x3fb8aa3b, v4
	v_exp_f32_e32 v3, v3
	v_mul_f32_e32 v5, 0x3fb8aa3b, v5
	v_exp_f32_e32 v4, v4
	v_exp_f32_e32 v5, v5
	v_add_f32_e32 v7, 0, v2
	v_add_f32_e32 v7, v3, v7
	v_add_f32_e32 v7, v4, v7
	v_add_f32_e32 v7, v5, v7
	ds_bpermute_b32 v8, v133, v7
	s_waitcnt lgkmcnt(0)
	v_add_f32_e32 v7, v7, v8
	ds_bpermute_b32 v8, v132, v7
	s_waitcnt lgkmcnt(0)
	v_add_f32_e32 v7, v7, v8
	ds_bpermute_b32 v8, v131, v7
	s_waitcnt lgkmcnt(0)
	v_add_f32_e32 v7, v7, v8
	ds_bpermute_b32 v8, v130, v7
	s_waitcnt lgkmcnt(0)
	v_add_f32_e32 v7, v7, v8
	ds_bpermute_b32 v8, v129, v7
	s_waitcnt lgkmcnt(0)
	v_add_f32_e32 v7, v7, v8
	ds_bpermute_b32 v8, v128, v7
	s_waitcnt lgkmcnt(0)
	v_add_f32_e32 v7, v7, v8
	v_div_scale_f32 v8, s[6:7], v7, v7, 1.0
	v_rcp_f32_e32 v9, v8
	v_div_scale_f32 v10, vcc, 1.0, v7, 1.0
	v_fma_f32 v11, -v8, v9, 1.0
	v_fmac_f32_e32 v9, v11, v9
	v_mul_f32_e32 v11, v10, v9
	v_fma_f32 v12, -v8, v11, v10
	v_fmac_f32_e32 v11, v12, v9
	v_fma_f32 v8, -v8, v11, v10
	v_div_fmas_f32 v8, v8, v9, v11
	v_div_fixup_f32 v7, v8, v7, 1.0
	v_mul_f32_e32 v2, v2, v7
	v_mul_f32_e32 v3, v3, v7
	v_mul_f32_e32 v4, v4, v7
	v_mul_f32_e32 v5, v5, v7
	ds_write2st64_b32 v6, v2, v3 offset1:1
	ds_write2st64_b32 v6, v4, v5 offset0:2 offset1:3
	s_branch .LBB0_1603

; DI void attn_sample_item(const Params& p, int item, ldsp lds, int tid_) {
;     ...
;   float q[4][4];
; #pragma unroll
;   for (int t = 0; t < 4; ++t) { f32x4 a = {0.f, 0.f, 0.f, 0.f}; const float* pp = (const float*)(p.ws + B_PART) + (size_t)(b * 4 + t) * 1024 + h * 256 + lane * 4;
; #pragma unroll
;     for (int kp = 0; kp < 4; ++kp) a += *(const f32x4*)(pp + (size_t)kp * 512 * 1024);
;     q[t][0] = a[0] * 0.0625f; q[t][1] = a[1] * 0.0625f; q[t][2] = a[2] * 0.0625f; q[t][3] = a[3] * 0.0625f; }
;   const bool b0 = lane & 1, b1 = lane & 2;
;   f32x4 kvA[16], kvB[16];
; #pragma unroll
;   for (int j = 0; j < 16; ++j) kvA[j] = __builtin_nontemporal_load((const f32x4*)(ck + (size_t)(wid * 32 + j) * 1024 + lane * 4));
; #pragma unroll
;   for (int j = 0; j < 16; ++j) kvB[j] = __builtin_nontemporal_load((const f32x4*)(ck + (size_t)(wid * 32 + 16 + j) * 1024 + lane * 4));
.LBB0_1676:
	s_ashr_i32 s4, s38, 2
	s_ashr_i32 s5, s4, 31
	s_lshl_b64 s[4:5], s[4:5], 18
	s_and_b32 s24, s0, 0x300
	v_mov_b32_e32 v222, v212
	s_or_b32 s4, s4, s24
	s_and_b32 s26, s38, -4
	s_lshl_b32 s6, s24, 2
	s_add_u32 s6, s36, s6
	v_and_b32_e32 v223, 63, v222
	s_addc_u32 s7, s37, 0
	v_lshlrev_b32_e32 v144, 4, v223
	s_ashr_i32 s27, s26, 31
	v_lshl_add_u64 v[48:49], s[6:7], 0, v[144:145]
	s_lshl_b64 s[6:7], s[26:27], 12
	v_lshl_add_u64 v[8:9], v[48:49], 0, s[6:7]
	v_add_co_u32_e32 v10, vcc, s3, v8
	s_or_b32 s6, s26, 1
	s_nop 0
	v_addc_co_u32_e32 v11, vcc, 0, v9, vcc
	global_load_dwordx4 v[0:3], v[8:9], off
	global_load_dwordx4 v[4:7], v[10:11], off
	v_add_co_u32_e32 v10, vcc, s33, v8
	s_ashr_i32 s7, s6, 31
	s_nop 0
	v_addc_co_u32_e32 v11, vcc, 0, v9, vcc
	v_add_co_u32_e32 v12, vcc, s34, v8
	s_lshl_b64 s[6:7], s[6:7], 12
	s_nop 0
	v_addc_co_u32_e32 v13, vcc, 0, v9, vcc
	v_lshl_add_u64 v[24:25], v[48:49], 0, s[6:7]
	v_add_co_u32_e32 v20, vcc, s3, v24
	s_or_b32 s6, s26, 2
	s_nop 0
	v_addc_co_u32_e32 v21, vcc, 0, v25, vcc
	v_add_co_u32_e32 v26, vcc, s33, v24
	s_ashr_i32 s7, s6, 31
	s_nop 0
	v_addc_co_u32_e32 v27, vcc, 0, v25, vcc
	v_add_co_u32_e32 v28, vcc, s34, v24
	s_lshl_b64 s[6:7], s[6:7], 12
	s_nop 0
	v_addc_co_u32_e32 v29, vcc, 0, v25, vcc
	v_lshl_add_u64 v[44:45], v[48:49], 0, s[6:7]
	global_load_dwordx4 v[8:11], v[10:11], off
	s_nop 0
	global_load_dwordx4 v[12:15], v[12:13], off
	s_nop 0
	global_load_dwordx4 v[16:19], v[24:25], off
	s_nop 0
	global_load_dwordx4 v[20:23], v[20:21], off
	v_add_co_u32_e32 v36, vcc, s3, v44
	global_load_dwordx4 v[24:27], v[26:27], off
	s_nop 0
	global_load_dwordx4 v[28:31], v[28:29], off
	v_addc_co_u32_e32 v37, vcc, 0, v45, vcc
	v_add_co_u32_e32 v40, vcc, s33, v44
	global_load_dwordx4 v[32:35], v[44:45], off
	s_nop 0
	global_load_dwordx4 v[36:39], v[36:37], off
	v_addc_co_u32_e32 v41, vcc, 0, v45, vcc
	v_add_co_u32_e32 v44, vcc, s34, v44
	global_load_dwordx4 v[40:43], v[40:41], off
	s_nop 0
	v_addc_co_u32_e32 v45, vcc, 0, v45, vcc
	global_load_dwordx4 v[44:47], v[44:45], off
	s_or_b32 s6, s38, 3
	s_ashr_i32 s7, s6, 31
	s_lshl_b64 s[6:7], s[6:7], 12
	s_lshl_b64 s[28:29], s[4:5], 2
	s_add_u32 s4, s12, s28
	s_addc_u32 s5, s13, s29
	s_waitcnt vmcnt(11)
	v_pk_add_f32 v[2:3], v[2:3], 0 op_sel_hi:[1,0]
	v_pk_add_f32 v[0:1], v[0:1], 0 op_sel_hi:[1,0]
	s_waitcnt vmcnt(10)
	v_pk_add_f32 v[2:3], v[2:3], v[6:7]
	v_pk_add_f32 v[0:1], v[0:1], v[4:5]
	s_waitcnt vmcnt(9)
	v_pk_add_f32 v[2:3], v[2:3], v[10:11]
	s_waitcnt vmcnt(7)
	v_pk_add_f32 v[4:5], v[18:19], 0 op_sel_hi:[1,0]
	v_pk_add_f32 v[6:7], v[16:17], 0 op_sel_hi:[1,0]
	v_pk_add_f32 v[0:1], v[0:1], v[8:9]
	s_waitcnt vmcnt(6)
	v_pk_add_f32 v[4:5], v[4:5], v[22:23]
	v_pk_add_f32 v[6:7], v[6:7], v[20:21]
	v_pk_add_f32 v[2:3], v[2:3], v[14:15]
	v_pk_add_f32 v[0:1], v[0:1], v[12:13]
	s_waitcnt vmcnt(5)
	v_pk_add_f32 v[4:5], v[4:5], v[26:27]
	v_pk_add_f32 v[6:7], v[6:7], v[24:25]
	v_mul_f32_e32 v228, 0x3d800000, v0
	v_mul_f32_e32 v231, 0x3d800000, v1
	v_mul_f32_e32 v229, 0x3d800000, v2
	v_mul_f32_e32 v225, 0x3d800000, v3
	s_waitcnt vmcnt(4)
	v_pk_add_f32 v[0:1], v[4:5], v[30:31]
	v_pk_add_f32 v[2:3], v[6:7], v[28:29]
	v_mul_f32_e32 v227, 0x3d800000, v0
	v_mul_f32_e32 v226, 0x3d800000, v2
	v_mul_f32_e32 v230, 0x3d800000, v3
	v_mul_f32_e32 v224, 0x3d800000, v1
	s_waitcnt vmcnt(3)
	v_pk_add_f32 v[0:1], v[34:35], 0 op_sel_hi:[1,0]
	v_pk_add_f32 v[2:3], v[32:33], 0 op_sel_hi:[1,0]
	s_waitcnt vmcnt(2)
	v_pk_add_f32 v[0:1], v[0:1], v[38:39]
	v_pk_add_f32 v[2:3], v[2:3], v[36:37]
	s_waitcnt vmcnt(1)
	v_pk_add_f32 v[0:1], v[0:1], v[42:43]
	v_pk_add_f32 v[2:3], v[2:3], v[40:41]
	s_waitcnt vmcnt(0)
	v_pk_add_f32 v[210:211], v[0:1], v[46:47]
	v_pk_add_f32 v[0:1], v[2:3], v[44:45]
	v_mul_f32_e32 v233, 0x3d800000, v210
	v_mul_f32_e32 v232, 0x3d800000, v0
	v_mul_f32_e32 v234, 0x3d800000, v1
	v_lshl_add_u64 v[0:1], v[48:49], 0, s[6:7]
	v_add_co_u32_e32 v2, vcc, s3, v0
	v_ashrrev_i32_e32 v210, 6, v222
	s_nop 0
	v_addc_co_u32_e32 v3, vcc, 0, v1, vcc
	global_load_dwordx4 v[128:131], v[0:1], off
	global_load_dwordx4 v[132:135], v[2:3], off
	v_add_co_u32_e32 v2, vcc, s33, v0
	v_mul_f32_e32 v211, 0x3d800000, v211
	s_nop 0
	v_addc_co_u32_e32 v3, vcc, 0, v1, vcc
	v_add_co_u32_e32 v0, vcc, s34, v0
	v_cmp_lt_i32_e64 s[6:7], v218, v216
	s_nop 0
	v_addc_co_u32_e32 v1, vcc, 0, v1, vcc
	global_load_dwordx4 v[136:139], v[2:3], off
	global_load_dwordx4 v[140:143], v[0:1], off
	v_lshlrev_b32_e32 v0, 5, v210
	v_ashrrev_i32_e32 v1, 31, v0
	v_or_b32_e32 v6, 1, v0
	v_lshl_add_u64 v[2:3], s[4:5], 0, v[144:145]
	v_lshlrev_b64 v[158:159], 12, v[0:1]
	v_ashrrev_i32_e32 v7, 31, v6
	v_lshl_add_u64 v[4:5], v[2:3], 0, v[158:159]
	v_lshlrev_b64 v[162:163], 12, v[6:7]
	v_lshl_add_u64 v[6:7], v[2:3], 0, v[162:163]
	global_load_dwordx4 v[124:127], v[4:5], off nt
	global_load_dwordx4 v[120:123], v[6:7], off nt
	v_or_b32_e32 v4, 2, v0
	v_ashrrev_i32_e32 v5, 31, v4
	v_or_b32_e32 v6, 3, v0
	v_lshlrev_b64 v[164:165], 12, v[4:5]
	v_ashrrev_i32_e32 v7, 31, v6
	v_lshl_add_u64 v[4:5], v[2:3], 0, v[164:165]
	v_lshlrev_b64 v[168:169], 12, v[6:7]
	v_lshl_add_u64 v[6:7], v[2:3], 0, v[168:169]
	global_load_dwordx4 v[116:119], v[4:5], off nt
	global_load_dwordx4 v[112:115], v[6:7], off nt
	v_or_b32_e32 v4, 4, v0
	v_ashrrev_i32_e32 v5, 31, v4
	v_or_b32_e32 v6, 5, v0
	v_lshlrev_b64 v[172:173], 12, v[4:5]
	v_ashrrev_i32_e32 v7, 31, v6
	v_lshl_add_u64 v[4:5], v[2:3], 0, v[172:173]
	v_lshlrev_b64 v[176:177], 12, v[6:7]
	v_lshl_add_u64 v[6:7], v[2:3], 0, v[176:177]
	global_load_dwordx4 v[108:111], v[4:5], off nt
	global_load_dwordx4 v[104:107], v[6:7], off nt
	v_or_b32_e32 v4, 6, v0
	v_ashrrev_i32_e32 v5, 31, v4
	v_or_b32_e32 v6, 7, v0
; DI void attn_sample_item(const Params& p, int item, ldsp lds, int tid_) {
;     ...
;   for (int t = 0; t < 4; ++t) { f32x4 a = {0.f, 0.f, 0.f, 0.f}; const float* pp = (const float*)(p.ws + B_PART) + (size_t)(b * 4 + t) * 1024 + h * 256 + lane * 4;
; #pragma unroll
;     for (int kp = 0; kp < 4; ++kp) a += *(const f32x4*)(pp + (size_t)kp * 512 * 1024);
;     q[t][0] = a[0] * 0.0625f; q[t][1] = a[1] * 0.0625f; q[t][2] = a[2] * 0.0625f; q[t][3] = a[3] * 0.0625f; }
;   const bool b0 = lane & 1, b1 = lane & 2;
;   f32x4 kvA[16], kvB[16];
; #pragma unroll
;   for (int j = 0; j < 16; ++j) kvA[j] = __builtin_nontemporal_load((const f32x4*)(ck + (size_t)(wid * 32 + j) * 1024 + lane * 4));
; #pragma unroll
;   for (int j = 0; j < 16; ++j) kvB[j] = __builtin_nontemporal_load((const f32x4*)(ck + (size_t)(wid * 32 + 16 + j) * 1024 + lane * 4));
	v_lshlrev_b64 v[180:181], 12, v[4:5]
	v_ashrrev_i32_e32 v7, 31, v6
	v_lshl_add_u64 v[4:5], v[2:3], 0, v[180:181]
	v_lshlrev_b64 v[184:185], 12, v[6:7]
	v_lshl_add_u64 v[6:7], v[2:3], 0, v[184:185]
	global_load_dwordx4 v[100:103], v[4:5], off nt
	global_load_dwordx4 v[96:99], v[6:7], off nt
	v_or_b32_e32 v4, 8, v0
	v_ashrrev_i32_e32 v5, 31, v4
	v_or_b32_e32 v6, 9, v0
	v_lshlrev_b64 v[188:189], 12, v[4:5]
	v_ashrrev_i32_e32 v7, 31, v6
	v_lshl_add_u64 v[4:5], v[2:3], 0, v[188:189]
	v_lshlrev_b64 v[192:193], 12, v[6:7]
	v_lshl_add_u64 v[6:7], v[2:3], 0, v[192:193]
	global_load_dwordx4 v[92:95], v[4:5], off nt
	global_load_dwordx4 v[88:91], v[6:7], off nt
	v_or_b32_e32 v4, 10, v0
	v_ashrrev_i32_e32 v5, 31, v4
	v_or_b32_e32 v6, 11, v0
	v_lshlrev_b64 v[196:197], 12, v[4:5]
	v_ashrrev_i32_e32 v7, 31, v6
	v_lshl_add_u64 v[4:5], v[2:3], 0, v[196:197]
	v_lshlrev_b64 v[200:201], 12, v[6:7]
	v_lshl_add_u64 v[6:7], v[2:3], 0, v[200:201]
	global_load_dwordx4 v[84:87], v[4:5], off nt
	global_load_dwordx4 v[80:83], v[6:7], off nt
	v_or_b32_e32 v4, 12, v0
	v_ashrrev_i32_e32 v5, 31, v4
	v_or_b32_e32 v6, 13, v0
	v_lshlrev_b64 v[202:203], 12, v[4:5]
	v_ashrrev_i32_e32 v7, 31, v6
	v_lshl_add_u64 v[4:5], v[2:3], 0, v[202:203]
	v_lshlrev_b64 v[204:205], 12, v[6:7]
	v_lshl_add_u64 v[6:7], v[2:3], 0, v[204:205]
	global_load_dwordx4 v[76:79], v[4:5], off nt
	global_load_dwordx4 v[72:75], v[6:7], off nt
	v_or_b32_e32 v4, 14, v0
	v_ashrrev_i32_e32 v5, 31, v4
	v_or_b32_e32 v6, 15, v0
	v_lshlrev_b64 v[206:207], 12, v[4:5]
	v_ashrrev_i32_e32 v7, 31, v6
	v_lshl_add_u64 v[4:5], v[2:3], 0, v[206:207]
	v_lshlrev_b64 v[208:209], 12, v[6:7]
	v_lshl_add_u64 v[6:7], v[2:3], 0, v[208:209]
	global_load_dwordx4 v[68:71], v[4:5], off nt
	global_load_dwordx4 v[64:67], v[6:7], off nt
	v_or_b32_e32 v4, 16, v0
	v_ashrrev_i32_e32 v5, 31, v4
	v_or_b32_e32 v6, 17, v0
	v_lshlrev_b64 v[146:147], 12, v[4:5]
	v_ashrrev_i32_e32 v7, 31, v6
	v_lshl_add_u64 v[4:5], v[2:3], 0, v[146:147]
	v_lshlrev_b64 v[148:149], 12, v[6:7]
	v_lshl_add_u64 v[6:7], v[2:3], 0, v[148:149]
	global_load_dwordx4 v[60:63], v[4:5], off nt
	global_load_dwordx4 v[56:59], v[6:7], off nt
	v_or_b32_e32 v4, 18, v0
	v_ashrrev_i32_e32 v5, 31, v4
	v_or_b32_e32 v6, 19, v0
	v_lshlrev_b64 v[150:151], 12, v[4:5]
	v_ashrrev_i32_e32 v7, 31, v6
	v_lshl_add_u64 v[4:5], v[2:3], 0, v[150:151]
	v_lshlrev_b64 v[152:153], 12, v[6:7]
	v_lshl_add_u64 v[6:7], v[2:3], 0, v[152:153]
	global_load_dwordx4 v[52:55], v[4:5], off nt
	global_load_dwordx4 v[48:51], v[6:7], off nt
	v_or_b32_e32 v4, 20, v0
	v_ashrrev_i32_e32 v5, 31, v4
	v_or_b32_e32 v6, 21, v0
	v_lshlrev_b64 v[154:155], 12, v[4:5]
	v_ashrrev_i32_e32 v7, 31, v6
	v_lshl_add_u64 v[4:5], v[2:3], 0, v[154:155]
	v_lshlrev_b64 v[156:157], 12, v[6:7]
	v_lshl_add_u64 v[6:7], v[2:3], 0, v[156:157]
	global_load_dwordx4 v[44:47], v[4:5], off nt
	global_load_dwordx4 v[40:43], v[6:7], off nt
	v_or_b32_e32 v4, 22, v0
	v_ashrrev_i32_e32 v5, 31, v4
	v_or_b32_e32 v6, 23, v0
	v_lshlrev_b64 v[160:161], 12, v[4:5]
	v_ashrrev_i32_e32 v7, 31, v6
	v_lshl_add_u64 v[4:5], v[2:3], 0, v[160:161]
	v_lshlrev_b64 v[166:167], 12, v[6:7]
	v_lshl_add_u64 v[6:7], v[2:3], 0, v[166:167]
	global_load_dwordx4 v[36:39], v[4:5], off nt
	global_load_dwordx4 v[32:35], v[6:7], off nt
	v_or_b32_e32 v4, 24, v0
	v_ashrrev_i32_e32 v5, 31, v4
	v_or_b32_e32 v6, 25, v0
	v_lshlrev_b64 v[170:171], 12, v[4:5]
	v_ashrrev_i32_e32 v7, 31, v6
	v_lshl_add_u64 v[4:5], v[2:3], 0, v[170:171]
	v_lshlrev_b64 v[174:175], 12, v[6:7]
	v_lshl_add_u64 v[6:7], v[2:3], 0, v[174:175]
	global_load_dwordx4 v[28:31], v[4:5], off nt
	global_load_dwordx4 v[24:27], v[6:7], off nt
	v_or_b32_e32 v4, 26, v0
	v_ashrrev_i32_e32 v5, 31, v4
	v_or_b32_e32 v6, 27, v0
	v_lshlrev_b64 v[178:179], 12, v[4:5]
	v_ashrrev_i32_e32 v7, 31, v6
	v_lshl_add_u64 v[4:5], v[2:3], 0, v[178:179]
	v_lshlrev_b64 v[182:183], 12, v[6:7]
	v_lshl_add_u64 v[6:7], v[2:3], 0, v[182:183]
	global_load_dwordx4 v[20:23], v[4:5], off nt
	global_load_dwordx4 v[16:19], v[6:7], off nt
	v_or_b32_e32 v4, 28, v0
	v_ashrrev_i32_e32 v5, 31, v4
	v_or_b32_e32 v6, 29, v0
	v_lshlrev_b64 v[186:187], 12, v[4:5]
	v_ashrrev_i32_e32 v7, 31, v6
	v_lshl_add_u64 v[4:5], v[2:3], 0, v[186:187]
	v_lshlrev_b64 v[190:191], 12, v[6:7]
	v_lshl_add_u64 v[6:7], v[2:3], 0, v[190:191]
	global_load_dwordx4 v[12:15], v[4:5], off nt
	global_load_dwordx4 v[8:11], v[6:7], off nt
	v_or_b32_e32 v4, 30, v0
	v_or_b32_e32 v0, 31, v0
	v_ashrrev_i32_e32 v5, 31, v4
	v_ashrrev_i32_e32 v1, 31, v0
	v_lshlrev_b64 v[194:195], 12, v[4:5]
	v_lshlrev_b64 v[198:199], 12, v[0:1]
	v_lshl_add_u64 v[4:5], v[2:3], 0, v[194:195]
	v_lshl_add_u64 v[0:1], v[2:3], 0, v[198:199]
	global_load_dwordx4 v[4:7], v[4:5], off nt
	s_nop 0
	global_load_dwordx4 v[0:3], v[0:1], off nt
	s_waitcnt vmcnt(35)
	v_pk_add_f32 v[128:129], v[128:129], 0 op_sel_hi:[1,0]
	v_pk_add_f32 v[130:131], v[130:131], 0 op_sel_hi:[1,0]
	s_waitcnt vmcnt(34)
	v_pk_add_f32 v[128:129], v[128:129], v[132:133]
	v_pk_add_f32 v[130:131], v[130:131], v[134:135]
	s_waitcnt vmcnt(33)
	v_pk_add_f32 v[128:129], v[128:129], v[136:137]
	v_pk_add_f32 v[130:131], v[130:131], v[138:139]
	s_waitcnt vmcnt(32)
; DI void attn_sample_item(const Params& p, int item, ldsp lds, int tid_) {
;     ...
;     q[t][0] = a[0] * 0.0625f; q[t][1] = a[1] * 0.0625f; q[t][2] = a[2] * 0.0625f; q[t][3] = a[3] * 0.0625f; }
;   const bool b0 = lane & 1, b1 = lane & 2;
;   f32x4 kvA[16], kvB[16];
; #pragma unroll
;   for (int j = 0; j < 16; ++j) kvA[j] = __builtin_nontemporal_load((const f32x4*)(ck + (size_t)(wid * 32 + j) * 1024 + lane * 4));
; #pragma unroll
;   for (int j = 0; j < 16; ++j) kvB[j] = __builtin_nontemporal_load((const f32x4*)(ck + (size_t)(wid * 32 + 16 + j) * 1024 + lane * 4));
	v_pk_add_f32 v[128:129], v[128:129], v[140:141]
	v_pk_add_f32 v[130:131], v[130:131], v[142:143]
	v_mul_f32_e32 v138, 0x3d800000, v129
	v_mul_f32_e32 v135, 0x3d800000, v128
	v_mul_f32_e32 v134, 0x3d800000, v131
	v_mul_f32_e32 v137, 0x3d800000, v130
	v_lshlrev_b32_e32 v128, 2, v215
	v_lshlrev_b32_e32 v129, 2, v217
	v_lshlrev_b32_e32 v130, 2, v218
	v_lshlrev_b32_e32 v131, 2, v219
	v_lshlrev_b32_e32 v132, 2, v220
	v_lshlrev_b32_e32 v133, 2, v221
	v_lshl_add_u32 v136, v210, 7, 16
	v_and_b32_e32 v139, 3, v223
	v_bfrev_b32_e32 v139, v139
	v_lshrrev_b32_e32 v139, 20, v139
	v_and_b32_e32 v235, -4, v223
	v_add3_u32 v235, v136, v139, v235
	v_mov_b32_e32 v236, v228
	v_mov_b32_e32 v237, v226
	v_mov_b32_e32 v238, v231
	v_mov_b32_e32 v239, v230
	v_mov_b32_e32 v240, v229
	v_mov_b32_e32 v241, v227
	v_mov_b32_e32 v242, v225
	v_mov_b32_e32 v243, v224
	v_mov_b32_e32 v244, v232
	v_mov_b32_e32 v245, v135
	v_mov_b32_e32 v246, v234
	v_mov_b32_e32 v247, v138
	v_mov_b32_e32 v248, v233
	v_mov_b32_e32 v249, v137
	v_mov_b32_e32 v250, v211
	v_mov_b32_e32 v251, v134
	s_mov_b32 vcc_lo, 0x55555555
	s_mov_b32 vcc_hi, 0x55555555
	s_mov_b32 s4, 0x33333333
	s_mov_b32 s5, 0x33333333
	s_mov_b32 s6, 0x0f0f0f0f
	s_mov_b32 s7, 0x0f0f0f0f
	s_mov_b32 s64, 0x00ff00ff
	s_mov_b32 s65, 0x00ff00ff
	s_waitcnt vmcnt(31)
	s_nop 0
	v_pk_mul_f32 v[252:253], v[236:237], v[124:125] op_sel_hi:[1,0]
	v_pk_mul_f32 v[254:255], v[244:245], v[124:125] op_sel_hi:[1,0]
	v_pk_fma_f32 v[252:253], v[238:239], v[124:125], v[252:253] op_sel:[0,1,0]
	v_pk_fma_f32 v[254:255], v[246:247], v[124:125], v[254:255] op_sel:[0,1,0]
	v_pk_fma_f32 v[252:253], v[240:241], v[126:127], v[252:253] op_sel_hi:[1,0,1]
	v_pk_fma_f32 v[254:255], v[248:249], v[126:127], v[254:255] op_sel_hi:[1,0,1]
	v_pk_fma_f32 v[252:253], v[242:243], v[126:127], v[252:253] op_sel:[0,1,0]
	v_pk_fma_f32 v[254:255], v[250:251], v[126:127], v[254:255] op_sel:[0,1,0]
	s_waitcnt vmcnt(30)
	s_nop 0
	v_pk_mul_f32 v[140:141], v[236:237], v[120:121] op_sel_hi:[1,0]
	v_pk_mul_f32 v[142:143], v[244:245], v[120:121] op_sel_hi:[1,0]
	v_pk_fma_f32 v[140:141], v[238:239], v[120:121], v[140:141] op_sel:[0,1,0]
	v_pk_fma_f32 v[142:143], v[246:247], v[120:121], v[142:143] op_sel:[0,1,0]
	v_pk_fma_f32 v[140:141], v[240:241], v[122:123], v[140:141] op_sel_hi:[1,0,1]
	v_pk_fma_f32 v[142:143], v[248:249], v[122:123], v[142:143] op_sel_hi:[1,0,1]
	v_pk_fma_f32 v[140:141], v[242:243], v[122:123], v[140:141] op_sel:[0,1,0]
	v_pk_fma_f32 v[142:143], v[250:251], v[122:123], v[142:143] op_sel:[0,1,0]
	v_add_f32_dpp v124, v252, v252 quad_perm:[1,0,3,2] row_mask:0xf bank_mask:0xf
	v_add_f32_dpp v125, v253, v253 quad_perm:[1,0,3,2] row_mask:0xf bank_mask:0xf
	v_add_f32_dpp v126, v254, v254 quad_perm:[1,0,3,2] row_mask:0xf bank_mask:0xf
	v_add_f32_dpp v127, v255, v255 quad_perm:[1,0,3,2] row_mask:0xf bank_mask:0xf
	v_cndmask_b32_e32 v124, v126, v124, vcc
	v_cndmask_b32_e32 v125, v127, v125, vcc
	s_waitcnt vmcnt(29)
	s_nop 0
	v_pk_mul_f32 v[252:253], v[236:237], v[116:117] op_sel_hi:[1,0]
	v_pk_mul_f32 v[254:255], v[244:245], v[116:117] op_sel_hi:[1,0]
	v_pk_fma_f32 v[252:253], v[238:239], v[116:117], v[252:253] op_sel:[0,1,0]
	v_pk_fma_f32 v[254:255], v[246:247], v[116:117], v[254:255] op_sel:[0,1,0]
	v_pk_fma_f32 v[252:253], v[240:241], v[118:119], v[252:253] op_sel_hi:[1,0,1]
	v_pk_fma_f32 v[254:255], v[248:249], v[118:119], v[254:255] op_sel_hi:[1,0,1]
	v_pk_fma_f32 v[252:253], v[242:243], v[118:119], v[252:253] op_sel:[0,1,0]
	v_pk_fma_f32 v[254:255], v[250:251], v[118:119], v[254:255] op_sel:[0,1,0]
	v_add_f32_dpp v120, v140, v140 quad_perm:[1,0,3,2] row_mask:0xf bank_mask:0xf
	v_add_f32_dpp v121, v141, v141 quad_perm:[1,0,3,2] row_mask:0xf bank_mask:0xf
	v_add_f32_dpp v122, v142, v142 quad_perm:[1,0,3,2] row_mask:0xf bank_mask:0xf
	v_add_f32_dpp v123, v143, v143 quad_perm:[1,0,3,2] row_mask:0xf bank_mask:0xf
	v_cndmask_b32_e32 v120, v122, v120, vcc
	v_cndmask_b32_e32 v121, v123, v121, vcc
	v_add_f32_dpp v126, v124, v124 quad_perm:[2,3,0,1] row_mask:0xf bank_mask:0xf
	v_add_f32_dpp v127, v125, v125 quad_perm:[2,3,0,1] row_mask:0xf bank_mask:0xf
	v_cndmask_b32_e64 v124, v127, v126, s[4:5]
	s_waitcnt vmcnt(28)
	s_nop 0
	v_pk_mul_f32 v[140:141], v[236:237], v[112:113] op_sel_hi:[1,0]
	v_pk_mul_f32 v[142:143], v[244:245], v[112:113] op_sel_hi:[1,0]
	v_pk_fma_f32 v[140:141], v[238:239], v[112:113], v[140:141] op_sel:[0,1,0]
	v_pk_fma_f32 v[142:143], v[246:247], v[112:113], v[142:143] op_sel:[0,1,0]
	v_pk_fma_f32 v[140:141], v[240:241], v[114:115], v[140:141] op_sel_hi:[1,0,1]
	v_pk_fma_f32 v[142:143], v[248:249], v[114:115], v[142:143] op_sel_hi:[1,0,1]
	v_pk_fma_f32 v[140:141], v[242:243], v[114:115], v[140:141] op_sel:[0,1,0]
	v_pk_fma_f32 v[142:143], v[250:251], v[114:115], v[142:143] op_sel:[0,1,0]
	v_add_f32_dpp v116, v252, v252 quad_perm:[1,0,3,2] row_mask:0xf bank_mask:0xf
	v_add_f32_dpp v117, v253, v253 quad_perm:[1,0,3,2] row_mask:0xf bank_mask:0xf
	v_add_f32_dpp v118, v254, v254 quad_perm:[1,0,3,2] row_mask:0xf bank_mask:0xf
	v_add_f32_dpp v119, v255, v255 quad_perm:[1,0,3,2] row_mask:0xf bank_mask:0xf
	v_cndmask_b32_e32 v116, v118, v116, vcc
	v_cndmask_b32_e32 v117, v119, v117, vcc
	v_add_f32_dpp v122, v120, v120 quad_perm:[2,3,0,1] row_mask:0xf bank_mask:0xf
	v_add_f32_dpp v123, v121, v121 quad_perm:[2,3,0,1] row_mask:0xf bank_mask:0xf
	v_cndmask_b32_e64 v120, v123, v122, s[4:5]
	v_cndmask_b32_e64 v125, v120, v124, s[6:7]
	v_cndmask_b32_e64 v126, v124, v120, s[6:7]
	s_waitcnt vmcnt(27)
; DI void attn_sample_item(const Params& p, int item, ldsp lds, int tid_) {
;     ...
;   SC_SCORE(kvA, 0)
;   SC_SCORE(kvB, 1)
	s_nop 0
	v_pk_mul_f32 v[252:253], v[236:237], v[108:109] op_sel_hi:[1,0]
	v_pk_mul_f32 v[254:255], v[244:245], v[108:109] op_sel_hi:[1,0]
	v_pk_fma_f32 v[252:253], v[238:239], v[108:109], v[252:253] op_sel:[0,1,0]
	v_pk_fma_f32 v[254:255], v[246:247], v[108:109], v[254:255] op_sel:[0,1,0]
	v_pk_fma_f32 v[252:253], v[240:241], v[110:111], v[252:253] op_sel_hi:[1,0,1]
	v_pk_fma_f32 v[254:255], v[248:249], v[110:111], v[254:255] op_sel_hi:[1,0,1]
	v_pk_fma_f32 v[252:253], v[242:243], v[110:111], v[252:253] op_sel:[0,1,0]
	v_pk_fma_f32 v[254:255], v[250:251], v[110:111], v[254:255] op_sel:[0,1,0]
	v_add_f32_dpp v124, v126, v125 row_ror:4 row_mask:0xf bank_mask:0xf
	v_add_f32_dpp v112, v140, v140 quad_perm:[1,0,3,2] row_mask:0xf bank_mask:0xf
	v_add_f32_dpp v113, v141, v141 quad_perm:[1,0,3,2] row_mask:0xf bank_mask:0xf
	v_add_f32_dpp v114, v142, v142 quad_perm:[1,0,3,2] row_mask:0xf bank_mask:0xf
	v_add_f32_dpp v115, v143, v143 quad_perm:[1,0,3,2] row_mask:0xf bank_mask:0xf
	v_cndmask_b32_e32 v112, v114, v112, vcc
	v_cndmask_b32_e32 v113, v115, v113, vcc
	v_add_f32_dpp v118, v116, v116 quad_perm:[2,3,0,1] row_mask:0xf bank_mask:0xf
	v_add_f32_dpp v119, v117, v117 quad_perm:[2,3,0,1] row_mask:0xf bank_mask:0xf
	v_cndmask_b32_e64 v116, v119, v118, s[4:5]
	s_waitcnt vmcnt(26)
	s_nop 0
	v_pk_mul_f32 v[140:141], v[236:237], v[104:105] op_sel_hi:[1,0]
	v_pk_mul_f32 v[142:143], v[244:245], v[104:105] op_sel_hi:[1,0]
	v_pk_fma_f32 v[140:141], v[238:239], v[104:105], v[140:141] op_sel:[0,1,0]
	v_pk_fma_f32 v[142:143], v[246:247], v[104:105], v[142:143] op_sel:[0,1,0]
	v_pk_fma_f32 v[140:141], v[240:241], v[106:107], v[140:141] op_sel_hi:[1,0,1]
	v_pk_fma_f32 v[142:143], v[248:249], v[106:107], v[142:143] op_sel_hi:[1,0,1]
	v_pk_fma_f32 v[140:141], v[242:243], v[106:107], v[140:141] op_sel:[0,1,0]
	v_pk_fma_f32 v[142:143], v[250:251], v[106:107], v[142:143] op_sel:[0,1,0]
	v_add_f32_dpp v108, v252, v252 quad_perm:[1,0,3,2] row_mask:0xf bank_mask:0xf
	v_add_f32_dpp v109, v253, v253 quad_perm:[1,0,3,2] row_mask:0xf bank_mask:0xf
	v_add_f32_dpp v110, v254, v254 quad_perm:[1,0,3,2] row_mask:0xf bank_mask:0xf
	v_add_f32_dpp v111, v255, v255 quad_perm:[1,0,3,2] row_mask:0xf bank_mask:0xf
	v_cndmask_b32_e32 v108, v110, v108, vcc
	v_cndmask_b32_e32 v109, v111, v109, vcc
	v_add_f32_dpp v114, v112, v112 quad_perm:[2,3,0,1] row_mask:0xf bank_mask:0xf
	v_add_f32_dpp v115, v113, v113 quad_perm:[2,3,0,1] row_mask:0xf bank_mask:0xf
	v_cndmask_b32_e64 v112, v115, v114, s[4:5]
	v_cndmask_b32_e64 v117, v112, v116, s[6:7]
	v_cndmask_b32_e64 v118, v116, v112, s[6:7]
	s_waitcnt vmcnt(25)
	s_nop 0
	v_pk_mul_f32 v[252:253], v[236:237], v[100:101] op_sel_hi:[1,0]
	v_pk_mul_f32 v[254:255], v[244:245], v[100:101] op_sel_hi:[1,0]
	v_pk_fma_f32 v[252:253], v[238:239], v[100:101], v[252:253] op_sel:[0,1,0]
	v_pk_fma_f32 v[254:255], v[246:247], v[100:101], v[254:255] op_sel:[0,1,0]
	v_pk_fma_f32 v[252:253], v[240:241], v[102:103], v[252:253] op_sel_hi:[1,0,1]
	v_pk_fma_f32 v[254:255], v[248:249], v[102:103], v[254:255] op_sel_hi:[1,0,1]
	v_pk_fma_f32 v[252:253], v[242:243], v[102:103], v[252:253] op_sel:[0,1,0]
	v_pk_fma_f32 v[254:255], v[250:251], v[102:103], v[254:255] op_sel:[0,1,0]
	v_add_f32_dpp v116, v118, v117 row_ror:4 row_mask:0xf bank_mask:0xf
	v_cndmask_b32_e64 v125, v116, v124, s[64:65]
	v_cndmask_b32_e64 v126, v124, v116, s[64:65]
	v_add_f32_dpp v104, v140, v140 quad_perm:[1,0,3,2] row_mask:0xf bank_mask:0xf
	v_add_f32_dpp v105, v141, v141 quad_perm:[1,0,3,2] row_mask:0xf bank_mask:0xf
	v_add_f32_dpp v106, v142, v142 quad_perm:[1,0,3,2] row_mask:0xf bank_mask:0xf
	v_add_f32_dpp v107, v143, v143 quad_perm:[1,0,3,2] row_mask:0xf bank_mask:0xf
	v_cndmask_b32_e32 v104, v106, v104, vcc
	v_cndmask_b32_e32 v105, v107, v105, vcc
	v_add_f32_dpp v110, v108, v108 quad_perm:[2,3,0,1] row_mask:0xf bank_mask:0xf
	v_add_f32_dpp v111, v109, v109 quad_perm:[2,3,0,1] row_mask:0xf bank_mask:0xf
	v_cndmask_b32_e64 v108, v111, v110, s[4:5]
	s_waitcnt vmcnt(24)
	s_nop 0
	v_pk_mul_f32 v[140:141], v[236:237], v[96:97] op_sel_hi:[1,0]
	v_pk_mul_f32 v[142:143], v[244:245], v[96:97] op_sel_hi:[1,0]
	v_pk_fma_f32 v[140:141], v[238:239], v[96:97], v[140:141] op_sel:[0,1,0]
	v_pk_fma_f32 v[142:143], v[246:247], v[96:97], v[142:143] op_sel:[0,1,0]
	v_pk_fma_f32 v[140:141], v[240:241], v[98:99], v[140:141] op_sel_hi:[1,0,1]
	v_pk_fma_f32 v[142:143], v[248:249], v[98:99], v[142:143] op_sel_hi:[1,0,1]
	v_pk_fma_f32 v[140:141], v[242:243], v[98:99], v[140:141] op_sel:[0,1,0]
	v_pk_fma_f32 v[142:143], v[250:251], v[98:99], v[142:143] op_sel:[0,1,0]
	v_add_f32_dpp v124, v126, v125 row_ror:8 row_mask:0xf bank_mask:0xf
	v_add_f32_dpp v100, v252, v252 quad_perm:[1,0,3,2] row_mask:0xf bank_mask:0xf
	v_add_f32_dpp v101, v253, v253 quad_perm:[1,0,3,2] row_mask:0xf bank_mask:0xf
	v_add_f32_dpp v102, v254, v254 quad_perm:[1,0,3,2] row_mask:0xf bank_mask:0xf
	v_add_f32_dpp v103, v255, v255 quad_perm:[1,0,3,2] row_mask:0xf bank_mask:0xf
	v_cndmask_b32_e32 v100, v102, v100, vcc
	v_cndmask_b32_e32 v101, v103, v101, vcc
	v_add_f32_dpp v106, v104, v104 quad_perm:[2,3,0,1] row_mask:0xf bank_mask:0xf
	v_add_f32_dpp v107, v105, v105 quad_perm:[2,3,0,1] row_mask:0xf bank_mask:0xf
	v_cndmask_b32_e64 v104, v107, v106, s[4:5]
	v_cndmask_b32_e64 v109, v104, v108, s[6:7]
	v_cndmask_b32_e64 v110, v108, v104, s[6:7]
	s_waitcnt vmcnt(23)
; DI void attn_sample_item(const Params& p, int item, ldsp lds, int tid_) {
;     ...
;   SC_SCORE(kvA, 0)
;   SC_SCORE(kvB, 1)
	s_nop 0
	v_pk_mul_f32 v[252:253], v[236:237], v[92:93] op_sel_hi:[1,0]
	v_pk_mul_f32 v[254:255], v[244:245], v[92:93] op_sel_hi:[1,0]
	v_pk_fma_f32 v[252:253], v[238:239], v[92:93], v[252:253] op_sel:[0,1,0]
	v_pk_fma_f32 v[254:255], v[246:247], v[92:93], v[254:255] op_sel:[0,1,0]
	v_pk_fma_f32 v[252:253], v[240:241], v[94:95], v[252:253] op_sel_hi:[1,0,1]
	v_pk_fma_f32 v[254:255], v[248:249], v[94:95], v[254:255] op_sel_hi:[1,0,1]
	v_pk_fma_f32 v[252:253], v[242:243], v[94:95], v[252:253] op_sel:[0,1,0]
	v_pk_fma_f32 v[254:255], v[250:251], v[94:95], v[254:255] op_sel:[0,1,0]
	v_add_f32_dpp v108, v110, v109 row_ror:4 row_mask:0xf bank_mask:0xf
	v_add_f32_dpp v96, v140, v140 quad_perm:[1,0,3,2] row_mask:0xf bank_mask:0xf
	v_add_f32_dpp v97, v141, v141 quad_perm:[1,0,3,2] row_mask:0xf bank_mask:0xf
	v_add_f32_dpp v98, v142, v142 quad_perm:[1,0,3,2] row_mask:0xf bank_mask:0xf
	v_add_f32_dpp v99, v143, v143 quad_perm:[1,0,3,2] row_mask:0xf bank_mask:0xf
	v_cndmask_b32_e32 v96, v98, v96, vcc
	v_cndmask_b32_e32 v97, v99, v97, vcc
	v_add_f32_dpp v102, v100, v100 quad_perm:[2,3,0,1] row_mask:0xf bank_mask:0xf
	v_add_f32_dpp v103, v101, v101 quad_perm:[2,3,0,1] row_mask:0xf bank_mask:0xf
	v_cndmask_b32_e64 v100, v103, v102, s[4:5]
	s_waitcnt vmcnt(22)
	s_nop 0
	v_pk_mul_f32 v[140:141], v[236:237], v[88:89] op_sel_hi:[1,0]
	v_pk_mul_f32 v[142:143], v[244:245], v[88:89] op_sel_hi:[1,0]
	v_pk_fma_f32 v[140:141], v[238:239], v[88:89], v[140:141] op_sel:[0,1,0]
	v_pk_fma_f32 v[142:143], v[246:247], v[88:89], v[142:143] op_sel:[0,1,0]
	v_pk_fma_f32 v[140:141], v[240:241], v[90:91], v[140:141] op_sel_hi:[1,0,1]
	v_pk_fma_f32 v[142:143], v[248:249], v[90:91], v[142:143] op_sel_hi:[1,0,1]
	v_pk_fma_f32 v[140:141], v[242:243], v[90:91], v[140:141] op_sel:[0,1,0]
	v_pk_fma_f32 v[142:143], v[250:251], v[90:91], v[142:143] op_sel:[0,1,0]
	v_add_f32_dpp v92, v252, v252 quad_perm:[1,0,3,2] row_mask:0xf bank_mask:0xf
	v_add_f32_dpp v93, v253, v253 quad_perm:[1,0,3,2] row_mask:0xf bank_mask:0xf
	v_add_f32_dpp v94, v254, v254 quad_perm:[1,0,3,2] row_mask:0xf bank_mask:0xf
	v_add_f32_dpp v95, v255, v255 quad_perm:[1,0,3,2] row_mask:0xf bank_mask:0xf
	v_cndmask_b32_e32 v92, v94, v92, vcc
	v_cndmask_b32_e32 v93, v95, v93, vcc
	v_add_f32_dpp v98, v96, v96 quad_perm:[2,3,0,1] row_mask:0xf bank_mask:0xf
	v_add_f32_dpp v99, v97, v97 quad_perm:[2,3,0,1] row_mask:0xf bank_mask:0xf
	v_cndmask_b32_e64 v96, v99, v98, s[4:5]
	v_cndmask_b32_e64 v101, v96, v100, s[6:7]
	v_cndmask_b32_e64 v102, v100, v96, s[6:7]
	s_waitcnt vmcnt(21)
	s_nop 0
	v_pk_mul_f32 v[252:253], v[236:237], v[84:85] op_sel_hi:[1,0]
	v_pk_mul_f32 v[254:255], v[244:245], v[84:85] op_sel_hi:[1,0]
	v_pk_fma_f32 v[252:253], v[238:239], v[84:85], v[252:253] op_sel:[0,1,0]
	v_pk_fma_f32 v[254:255], v[246:247], v[84:85], v[254:255] op_sel:[0,1,0]
	v_pk_fma_f32 v[252:253], v[240:241], v[86:87], v[252:253] op_sel_hi:[1,0,1]
	v_pk_fma_f32 v[254:255], v[248:249], v[86:87], v[254:255] op_sel_hi:[1,0,1]
	v_pk_fma_f32 v[252:253], v[242:243], v[86:87], v[252:253] op_sel:[0,1,0]
	v_pk_fma_f32 v[254:255], v[250:251], v[86:87], v[254:255] op_sel:[0,1,0]
	v_add_f32_dpp v100, v102, v101 row_ror:4 row_mask:0xf bank_mask:0xf
	v_cndmask_b32_e64 v109, v100, v108, s[64:65]
	v_cndmask_b32_e64 v110, v108, v100, s[64:65]
	v_add_f32_dpp v88, v140, v140 quad_perm:[1,0,3,2] row_mask:0xf bank_mask:0xf
	v_add_f32_dpp v89, v141, v141 quad_perm:[1,0,3,2] row_mask:0xf bank_mask:0xf
	v_add_f32_dpp v90, v142, v142 quad_perm:[1,0,3,2] row_mask:0xf bank_mask:0xf
	v_add_f32_dpp v91, v143, v143 quad_perm:[1,0,3,2] row_mask:0xf bank_mask:0xf
	v_cndmask_b32_e32 v88, v90, v88, vcc
	v_cndmask_b32_e32 v89, v91, v89, vcc
	v_add_f32_dpp v94, v92, v92 quad_perm:[2,3,0,1] row_mask:0xf bank_mask:0xf
	v_add_f32_dpp v95, v93, v93 quad_perm:[2,3,0,1] row_mask:0xf bank_mask:0xf
	v_cndmask_b32_e64 v92, v95, v94, s[4:5]
	s_waitcnt vmcnt(20)
	s_nop 0
	v_pk_mul_f32 v[140:141], v[236:237], v[80:81] op_sel_hi:[1,0]
	v_pk_mul_f32 v[142:143], v[244:245], v[80:81] op_sel_hi:[1,0]
	v_pk_fma_f32 v[140:141], v[238:239], v[80:81], v[140:141] op_sel:[0,1,0]
	v_pk_fma_f32 v[142:143], v[246:247], v[80:81], v[142:143] op_sel:[0,1,0]
	v_pk_fma_f32 v[140:141], v[240:241], v[82:83], v[140:141] op_sel_hi:[1,0,1]
	v_pk_fma_f32 v[142:143], v[248:249], v[82:83], v[142:143] op_sel_hi:[1,0,1]
	v_pk_fma_f32 v[140:141], v[242:243], v[82:83], v[140:141] op_sel:[0,1,0]
	v_pk_fma_f32 v[142:143], v[250:251], v[82:83], v[142:143] op_sel:[0,1,0]
	v_add_f32_dpp v108, v110, v109 row_ror:8 row_mask:0xf bank_mask:0xf
	v_add_f32_dpp v84, v252, v252 quad_perm:[1,0,3,2] row_mask:0xf bank_mask:0xf
	v_add_f32_dpp v85, v253, v253 quad_perm:[1,0,3,2] row_mask:0xf bank_mask:0xf
	v_add_f32_dpp v86, v254, v254 quad_perm:[1,0,3,2] row_mask:0xf bank_mask:0xf
	v_add_f32_dpp v87, v255, v255 quad_perm:[1,0,3,2] row_mask:0xf bank_mask:0xf
	v_cndmask_b32_e32 v84, v86, v84, vcc
	v_cndmask_b32_e32 v85, v87, v85, vcc
	v_add_f32_dpp v90, v88, v88 quad_perm:[2,3,0,1] row_mask:0xf bank_mask:0xf
	v_add_f32_dpp v91, v89, v89 quad_perm:[2,3,0,1] row_mask:0xf bank_mask:0xf
	v_cndmask_b32_e64 v88, v91, v90, s[4:5]
	v_cndmask_b32_e64 v93, v88, v92, s[6:7]
	v_cndmask_b32_e64 v94, v92, v88, s[6:7]
	s_waitcnt vmcnt(19)
; DI void attn_sample_item(const Params& p, int item, ldsp lds, int tid_) {
;     ...
;   SC_SCORE(kvA, 0)
;   SC_SCORE(kvB, 1)
	s_nop 0
	v_pk_mul_f32 v[252:253], v[236:237], v[76:77] op_sel_hi:[1,0]
	v_pk_mul_f32 v[254:255], v[244:245], v[76:77] op_sel_hi:[1,0]
	v_pk_fma_f32 v[252:253], v[238:239], v[76:77], v[252:253] op_sel:[0,1,0]
	v_pk_fma_f32 v[254:255], v[246:247], v[76:77], v[254:255] op_sel:[0,1,0]
	v_pk_fma_f32 v[252:253], v[240:241], v[78:79], v[252:253] op_sel_hi:[1,0,1]
	v_pk_fma_f32 v[254:255], v[248:249], v[78:79], v[254:255] op_sel_hi:[1,0,1]
	v_pk_fma_f32 v[252:253], v[242:243], v[78:79], v[252:253] op_sel:[0,1,0]
	v_pk_fma_f32 v[254:255], v[250:251], v[78:79], v[254:255] op_sel:[0,1,0]
	v_permlane16_swap_b32_e32 v124, v108
	v_add_f32_e32 v124, v124, v108
	v_add_f32_dpp v92, v94, v93 row_ror:4 row_mask:0xf bank_mask:0xf
	v_add_f32_dpp v80, v140, v140 quad_perm:[1,0,3,2] row_mask:0xf bank_mask:0xf
	v_add_f32_dpp v81, v141, v141 quad_perm:[1,0,3,2] row_mask:0xf bank_mask:0xf
	v_add_f32_dpp v82, v142, v142 quad_perm:[1,0,3,2] row_mask:0xf bank_mask:0xf
	v_add_f32_dpp v83, v143, v143 quad_perm:[1,0,3,2] row_mask:0xf bank_mask:0xf
	v_cndmask_b32_e32 v80, v82, v80, vcc
	v_cndmask_b32_e32 v81, v83, v81, vcc
	v_add_f32_dpp v86, v84, v84 quad_perm:[2,3,0,1] row_mask:0xf bank_mask:0xf
	v_add_f32_dpp v87, v85, v85 quad_perm:[2,3,0,1] row_mask:0xf bank_mask:0xf
	v_cndmask_b32_e64 v84, v87, v86, s[4:5]
	s_waitcnt vmcnt(18)
	s_nop 0
	v_pk_mul_f32 v[140:141], v[236:237], v[72:73] op_sel_hi:[1,0]
	v_pk_mul_f32 v[142:143], v[244:245], v[72:73] op_sel_hi:[1,0]
	v_pk_fma_f32 v[140:141], v[238:239], v[72:73], v[140:141] op_sel:[0,1,0]
	v_pk_fma_f32 v[142:143], v[246:247], v[72:73], v[142:143] op_sel:[0,1,0]
	v_pk_fma_f32 v[140:141], v[240:241], v[74:75], v[140:141] op_sel_hi:[1,0,1]
	v_pk_fma_f32 v[142:143], v[248:249], v[74:75], v[142:143] op_sel_hi:[1,0,1]
	v_pk_fma_f32 v[140:141], v[242:243], v[74:75], v[140:141] op_sel:[0,1,0]
	v_pk_fma_f32 v[142:143], v[250:251], v[74:75], v[142:143] op_sel:[0,1,0]
	v_add_f32_dpp v76, v252, v252 quad_perm:[1,0,3,2] row_mask:0xf bank_mask:0xf
	v_add_f32_dpp v77, v253, v253 quad_perm:[1,0,3,2] row_mask:0xf bank_mask:0xf
	v_add_f32_dpp v78, v254, v254 quad_perm:[1,0,3,2] row_mask:0xf bank_mask:0xf
	v_add_f32_dpp v79, v255, v255 quad_perm:[1,0,3,2] row_mask:0xf bank_mask:0xf
	v_cndmask_b32_e32 v76, v78, v76, vcc
	v_cndmask_b32_e32 v77, v79, v77, vcc
	v_add_f32_dpp v82, v80, v80 quad_perm:[2,3,0,1] row_mask:0xf bank_mask:0xf
	v_add_f32_dpp v83, v81, v81 quad_perm:[2,3,0,1] row_mask:0xf bank_mask:0xf
	v_cndmask_b32_e64 v80, v83, v82, s[4:5]
	v_cndmask_b32_e64 v85, v80, v84, s[6:7]
	v_cndmask_b32_e64 v86, v84, v80, s[6:7]
	s_waitcnt vmcnt(17)
	s_nop 0
	v_pk_mul_f32 v[252:253], v[236:237], v[68:69] op_sel_hi:[1,0]
	v_pk_mul_f32 v[254:255], v[244:245], v[68:69] op_sel_hi:[1,0]
	v_pk_fma_f32 v[252:253], v[238:239], v[68:69], v[252:253] op_sel:[0,1,0]
	v_pk_fma_f32 v[254:255], v[246:247], v[68:69], v[254:255] op_sel:[0,1,0]
	v_pk_fma_f32 v[252:253], v[240:241], v[70:71], v[252:253] op_sel_hi:[1,0,1]
	v_pk_fma_f32 v[254:255], v[248:249], v[70:71], v[254:255] op_sel_hi:[1,0,1]
	v_pk_fma_f32 v[252:253], v[242:243], v[70:71], v[252:253] op_sel:[0,1,0]
	v_pk_fma_f32 v[254:255], v[250:251], v[70:71], v[254:255] op_sel:[0,1,0]
	v_add_f32_dpp v84, v86, v85 row_ror:4 row_mask:0xf bank_mask:0xf
	v_cndmask_b32_e64 v93, v84, v92, s[64:65]
	v_cndmask_b32_e64 v94, v92, v84, s[64:65]
	v_add_f32_dpp v72, v140, v140 quad_perm:[1,0,3,2] row_mask:0xf bank_mask:0xf
	v_add_f32_dpp v73, v141, v141 quad_perm:[1,0,3,2] row_mask:0xf bank_mask:0xf
	v_add_f32_dpp v74, v142, v142 quad_perm:[1,0,3,2] row_mask:0xf bank_mask:0xf
	v_add_f32_dpp v75, v143, v143 quad_perm:[1,0,3,2] row_mask:0xf bank_mask:0xf
	v_cndmask_b32_e32 v72, v74, v72, vcc
	v_cndmask_b32_e32 v73, v75, v73, vcc
	v_add_f32_dpp v78, v76, v76 quad_perm:[2,3,0,1] row_mask:0xf bank_mask:0xf
	v_add_f32_dpp v79, v77, v77 quad_perm:[2,3,0,1] row_mask:0xf bank_mask:0xf
	v_cndmask_b32_e64 v76, v79, v78, s[4:5]
	s_waitcnt vmcnt(16)
	s_nop 0
	v_pk_mul_f32 v[140:141], v[236:237], v[64:65] op_sel_hi:[1,0]
	v_pk_mul_f32 v[142:143], v[244:245], v[64:65] op_sel_hi:[1,0]
	v_pk_fma_f32 v[140:141], v[238:239], v[64:65], v[140:141] op_sel:[0,1,0]
	v_pk_fma_f32 v[142:143], v[246:247], v[64:65], v[142:143] op_sel:[0,1,0]
	v_pk_fma_f32 v[140:141], v[240:241], v[66:67], v[140:141] op_sel_hi:[1,0,1]
	v_pk_fma_f32 v[142:143], v[248:249], v[66:67], v[142:143] op_sel_hi:[1,0,1]
	v_pk_fma_f32 v[140:141], v[242:243], v[66:67], v[140:141] op_sel:[0,1,0]
	v_pk_fma_f32 v[142:143], v[250:251], v[66:67], v[142:143] op_sel:[0,1,0]
	v_add_f32_dpp v92, v94, v93 row_ror:8 row_mask:0xf bank_mask:0xf
	v_add_f32_dpp v68, v252, v252 quad_perm:[1,0,3,2] row_mask:0xf bank_mask:0xf
	v_add_f32_dpp v69, v253, v253 quad_perm:[1,0,3,2] row_mask:0xf bank_mask:0xf
	v_add_f32_dpp v70, v254, v254 quad_perm:[1,0,3,2] row_mask:0xf bank_mask:0xf
	v_add_f32_dpp v71, v255, v255 quad_perm:[1,0,3,2] row_mask:0xf bank_mask:0xf
	v_cndmask_b32_e32 v68, v70, v68, vcc
	v_cndmask_b32_e32 v69, v71, v69, vcc
	v_add_f32_dpp v74, v72, v72 quad_perm:[2,3,0,1] row_mask:0xf bank_mask:0xf
	v_add_f32_dpp v75, v73, v73 quad_perm:[2,3,0,1] row_mask:0xf bank_mask:0xf
	v_cndmask_b32_e64 v72, v75, v74, s[4:5]
	v_cndmask_b32_e64 v77, v72, v76, s[6:7]
	v_cndmask_b32_e64 v78, v76, v72, s[6:7]
	s_waitcnt vmcnt(15)
; DI void attn_sample_item(const Params& p, int item, ldsp lds, int tid_) {
;     ...
;   SC_SCORE(kvA, 0)
;   SC_SCORE(kvB, 1)
	s_nop 0
	v_pk_mul_f32 v[252:253], v[236:237], v[60:61] op_sel_hi:[1,0]
	v_pk_mul_f32 v[254:255], v[244:245], v[60:61] op_sel_hi:[1,0]
	v_pk_fma_f32 v[252:253], v[238:239], v[60:61], v[252:253] op_sel:[0,1,0]
	v_pk_fma_f32 v[254:255], v[246:247], v[60:61], v[254:255] op_sel:[0,1,0]
	v_pk_fma_f32 v[252:253], v[240:241], v[62:63], v[252:253] op_sel_hi:[1,0,1]
	v_pk_fma_f32 v[254:255], v[248:249], v[62:63], v[254:255] op_sel_hi:[1,0,1]
	v_pk_fma_f32 v[252:253], v[242:243], v[62:63], v[252:253] op_sel:[0,1,0]
	v_pk_fma_f32 v[254:255], v[250:251], v[62:63], v[254:255] op_sel:[0,1,0]
	v_add_f32_dpp v76, v78, v77 row_ror:4 row_mask:0xf bank_mask:0xf
	v_add_f32_dpp v64, v140, v140 quad_perm:[1,0,3,2] row_mask:0xf bank_mask:0xf
	v_add_f32_dpp v65, v141, v141 quad_perm:[1,0,3,2] row_mask:0xf bank_mask:0xf
	v_add_f32_dpp v66, v142, v142 quad_perm:[1,0,3,2] row_mask:0xf bank_mask:0xf
	v_add_f32_dpp v67, v143, v143 quad_perm:[1,0,3,2] row_mask:0xf bank_mask:0xf
	v_cndmask_b32_e32 v64, v66, v64, vcc
	v_cndmask_b32_e32 v65, v67, v65, vcc
	v_add_f32_dpp v70, v68, v68 quad_perm:[2,3,0,1] row_mask:0xf bank_mask:0xf
	v_add_f32_dpp v71, v69, v69 quad_perm:[2,3,0,1] row_mask:0xf bank_mask:0xf
	v_cndmask_b32_e64 v68, v71, v70, s[4:5]
	s_waitcnt vmcnt(14)
	s_nop 0
	v_pk_mul_f32 v[140:141], v[236:237], v[56:57] op_sel_hi:[1,0]
	v_pk_mul_f32 v[142:143], v[244:245], v[56:57] op_sel_hi:[1,0]
	v_pk_fma_f32 v[140:141], v[238:239], v[56:57], v[140:141] op_sel:[0,1,0]
	v_pk_fma_f32 v[142:143], v[246:247], v[56:57], v[142:143] op_sel:[0,1,0]
	v_pk_fma_f32 v[140:141], v[240:241], v[58:59], v[140:141] op_sel_hi:[1,0,1]
	v_pk_fma_f32 v[142:143], v[248:249], v[58:59], v[142:143] op_sel_hi:[1,0,1]
	v_pk_fma_f32 v[140:141], v[242:243], v[58:59], v[140:141] op_sel:[0,1,0]
	v_pk_fma_f32 v[142:143], v[250:251], v[58:59], v[142:143] op_sel:[0,1,0]
	v_add_f32_dpp v60, v252, v252 quad_perm:[1,0,3,2] row_mask:0xf bank_mask:0xf
	v_add_f32_dpp v61, v253, v253 quad_perm:[1,0,3,2] row_mask:0xf bank_mask:0xf
	v_add_f32_dpp v62, v254, v254 quad_perm:[1,0,3,2] row_mask:0xf bank_mask:0xf
	v_add_f32_dpp v63, v255, v255 quad_perm:[1,0,3,2] row_mask:0xf bank_mask:0xf
	v_cndmask_b32_e32 v60, v62, v60, vcc
	v_cndmask_b32_e32 v61, v63, v61, vcc
	v_add_f32_dpp v66, v64, v64 quad_perm:[2,3,0,1] row_mask:0xf bank_mask:0xf
	v_add_f32_dpp v67, v65, v65 quad_perm:[2,3,0,1] row_mask:0xf bank_mask:0xf
	v_cndmask_b32_e64 v64, v67, v66, s[4:5]
	v_cndmask_b32_e64 v69, v64, v68, s[6:7]
	v_cndmask_b32_e64 v70, v68, v64, s[6:7]
	s_waitcnt vmcnt(13)
	s_nop 0
	v_pk_mul_f32 v[252:253], v[236:237], v[52:53] op_sel_hi:[1,0]
	v_pk_mul_f32 v[254:255], v[244:245], v[52:53] op_sel_hi:[1,0]
	v_pk_fma_f32 v[252:253], v[238:239], v[52:53], v[252:253] op_sel:[0,1,0]
	v_pk_fma_f32 v[254:255], v[246:247], v[52:53], v[254:255] op_sel:[0,1,0]
	v_pk_fma_f32 v[252:253], v[240:241], v[54:55], v[252:253] op_sel_hi:[1,0,1]
	v_pk_fma_f32 v[254:255], v[248:249], v[54:55], v[254:255] op_sel_hi:[1,0,1]
	v_pk_fma_f32 v[252:253], v[242:243], v[54:55], v[252:253] op_sel:[0,1,0]
	v_pk_fma_f32 v[254:255], v[250:251], v[54:55], v[254:255] op_sel:[0,1,0]
	v_add_f32_dpp v68, v70, v69 row_ror:4 row_mask:0xf bank_mask:0xf
	v_cndmask_b32_e64 v77, v68, v76, s[64:65]
	v_cndmask_b32_e64 v78, v76, v68, s[64:65]
	v_add_f32_dpp v56, v140, v140 quad_perm:[1,0,3,2] row_mask:0xf bank_mask:0xf
	v_add_f32_dpp v57, v141, v141 quad_perm:[1,0,3,2] row_mask:0xf bank_mask:0xf
	v_add_f32_dpp v58, v142, v142 quad_perm:[1,0,3,2] row_mask:0xf bank_mask:0xf
	v_add_f32_dpp v59, v143, v143 quad_perm:[1,0,3,2] row_mask:0xf bank_mask:0xf
	v_cndmask_b32_e32 v56, v58, v56, vcc
	v_cndmask_b32_e32 v57, v59, v57, vcc
	v_add_f32_dpp v62, v60, v60 quad_perm:[2,3,0,1] row_mask:0xf bank_mask:0xf
	v_add_f32_dpp v63, v61, v61 quad_perm:[2,3,0,1] row_mask:0xf bank_mask:0xf
	v_cndmask_b32_e64 v60, v63, v62, s[4:5]
	s_waitcnt vmcnt(12)
	s_nop 0
	v_pk_mul_f32 v[140:141], v[236:237], v[48:49] op_sel_hi:[1,0]
	v_pk_mul_f32 v[142:143], v[244:245], v[48:49] op_sel_hi:[1,0]
	v_pk_fma_f32 v[140:141], v[238:239], v[48:49], v[140:141] op_sel:[0,1,0]
	v_pk_fma_f32 v[142:143], v[246:247], v[48:49], v[142:143] op_sel:[0,1,0]
	v_pk_fma_f32 v[140:141], v[240:241], v[50:51], v[140:141] op_sel_hi:[1,0,1]
	v_pk_fma_f32 v[142:143], v[248:249], v[50:51], v[142:143] op_sel_hi:[1,0,1]
	v_pk_fma_f32 v[140:141], v[242:243], v[50:51], v[140:141] op_sel:[0,1,0]
	v_pk_fma_f32 v[142:143], v[250:251], v[50:51], v[142:143] op_sel:[0,1,0]
	v_add_f32_dpp v76, v78, v77 row_ror:8 row_mask:0xf bank_mask:0xf
	v_add_f32_dpp v52, v252, v252 quad_perm:[1,0,3,2] row_mask:0xf bank_mask:0xf
	v_add_f32_dpp v53, v253, v253 quad_perm:[1,0,3,2] row_mask:0xf bank_mask:0xf
	v_add_f32_dpp v54, v254, v254 quad_perm:[1,0,3,2] row_mask:0xf bank_mask:0xf
	v_add_f32_dpp v55, v255, v255 quad_perm:[1,0,3,2] row_mask:0xf bank_mask:0xf
	v_cndmask_b32_e32 v52, v54, v52, vcc
	v_cndmask_b32_e32 v53, v55, v53, vcc
	v_add_f32_dpp v58, v56, v56 quad_perm:[2,3,0,1] row_mask:0xf bank_mask:0xf
	v_add_f32_dpp v59, v57, v57 quad_perm:[2,3,0,1] row_mask:0xf bank_mask:0xf
	v_cndmask_b32_e64 v56, v59, v58, s[4:5]
	v_cndmask_b32_e64 v61, v56, v60, s[6:7]
	v_cndmask_b32_e64 v62, v60, v56, s[6:7]
	s_waitcnt vmcnt(11)
; DI void attn_sample_item(const Params& p, int item, ldsp lds, int tid_) {
;     ...
;   SC_SCORE(kvA, 0)
;   SC_SCORE(kvB, 1)
	s_nop 0
	v_pk_mul_f32 v[252:253], v[236:237], v[44:45] op_sel_hi:[1,0]
	v_pk_mul_f32 v[254:255], v[244:245], v[44:45] op_sel_hi:[1,0]
	v_pk_fma_f32 v[252:253], v[238:239], v[44:45], v[252:253] op_sel:[0,1,0]
	v_pk_fma_f32 v[254:255], v[246:247], v[44:45], v[254:255] op_sel:[0,1,0]
	v_pk_fma_f32 v[252:253], v[240:241], v[46:47], v[252:253] op_sel_hi:[1,0,1]
	v_pk_fma_f32 v[254:255], v[248:249], v[46:47], v[254:255] op_sel_hi:[1,0,1]
	v_pk_fma_f32 v[252:253], v[242:243], v[46:47], v[252:253] op_sel:[0,1,0]
	v_pk_fma_f32 v[254:255], v[250:251], v[46:47], v[254:255] op_sel:[0,1,0]
	v_permlane16_swap_b32_e32 v92, v76
	v_add_f32_e32 v92, v92, v76
	v_add_f32_dpp v60, v62, v61 row_ror:4 row_mask:0xf bank_mask:0xf
	v_add_f32_dpp v48, v140, v140 quad_perm:[1,0,3,2] row_mask:0xf bank_mask:0xf
	v_add_f32_dpp v49, v141, v141 quad_perm:[1,0,3,2] row_mask:0xf bank_mask:0xf
	v_add_f32_dpp v50, v142, v142 quad_perm:[1,0,3,2] row_mask:0xf bank_mask:0xf
	v_add_f32_dpp v51, v143, v143 quad_perm:[1,0,3,2] row_mask:0xf bank_mask:0xf
	v_cndmask_b32_e32 v48, v50, v48, vcc
	v_cndmask_b32_e32 v49, v51, v49, vcc
	v_add_f32_dpp v54, v52, v52 quad_perm:[2,3,0,1] row_mask:0xf bank_mask:0xf
	v_add_f32_dpp v55, v53, v53 quad_perm:[2,3,0,1] row_mask:0xf bank_mask:0xf
	v_cndmask_b32_e64 v52, v55, v54, s[4:5]
	s_waitcnt vmcnt(10)
	s_nop 0
	v_pk_mul_f32 v[140:141], v[236:237], v[40:41] op_sel_hi:[1,0]
	v_pk_mul_f32 v[142:143], v[244:245], v[40:41] op_sel_hi:[1,0]
	v_pk_fma_f32 v[140:141], v[238:239], v[40:41], v[140:141] op_sel:[0,1,0]
	v_pk_fma_f32 v[142:143], v[246:247], v[40:41], v[142:143] op_sel:[0,1,0]
	v_pk_fma_f32 v[140:141], v[240:241], v[42:43], v[140:141] op_sel_hi:[1,0,1]
	v_pk_fma_f32 v[142:143], v[248:249], v[42:43], v[142:143] op_sel_hi:[1,0,1]
	v_pk_fma_f32 v[140:141], v[242:243], v[42:43], v[140:141] op_sel:[0,1,0]
	v_pk_fma_f32 v[142:143], v[250:251], v[42:43], v[142:143] op_sel:[0,1,0]
	v_permlane32_swap_b32_e32 v124, v92
	v_add_f32_e32 v124, v124, v92
	ds_write_b32 v235, v124
	v_add_f32_dpp v44, v252, v252 quad_perm:[1,0,3,2] row_mask:0xf bank_mask:0xf
	v_add_f32_dpp v45, v253, v253 quad_perm:[1,0,3,2] row_mask:0xf bank_mask:0xf
	v_add_f32_dpp v46, v254, v254 quad_perm:[1,0,3,2] row_mask:0xf bank_mask:0xf
	v_add_f32_dpp v47, v255, v255 quad_perm:[1,0,3,2] row_mask:0xf bank_mask:0xf
	v_cndmask_b32_e32 v44, v46, v44, vcc
	v_cndmask_b32_e32 v45, v47, v45, vcc
	v_add_f32_dpp v50, v48, v48 quad_perm:[2,3,0,1] row_mask:0xf bank_mask:0xf
	v_add_f32_dpp v51, v49, v49 quad_perm:[2,3,0,1] row_mask:0xf bank_mask:0xf
	v_cndmask_b32_e64 v48, v51, v50, s[4:5]
	v_cndmask_b32_e64 v53, v48, v52, s[6:7]
	v_cndmask_b32_e64 v54, v52, v48, s[6:7]
	s_waitcnt vmcnt(9)
	s_nop 0
	v_pk_mul_f32 v[252:253], v[236:237], v[36:37] op_sel_hi:[1,0]
	v_pk_mul_f32 v[254:255], v[244:245], v[36:37] op_sel_hi:[1,0]
	v_pk_fma_f32 v[252:253], v[238:239], v[36:37], v[252:253] op_sel:[0,1,0]
	v_pk_fma_f32 v[254:255], v[246:247], v[36:37], v[254:255] op_sel:[0,1,0]
	v_pk_fma_f32 v[252:253], v[240:241], v[38:39], v[252:253] op_sel_hi:[1,0,1]
	v_pk_fma_f32 v[254:255], v[248:249], v[38:39], v[254:255] op_sel_hi:[1,0,1]
	v_pk_fma_f32 v[252:253], v[242:243], v[38:39], v[252:253] op_sel:[0,1,0]
	v_pk_fma_f32 v[254:255], v[250:251], v[38:39], v[254:255] op_sel:[0,1,0]
	v_add_f32_dpp v52, v54, v53 row_ror:4 row_mask:0xf bank_mask:0xf
	v_cndmask_b32_e64 v61, v52, v60, s[64:65]
	v_cndmask_b32_e64 v62, v60, v52, s[64:65]
	v_add_f32_dpp v40, v140, v140 quad_perm:[1,0,3,2] row_mask:0xf bank_mask:0xf
	v_add_f32_dpp v41, v141, v141 quad_perm:[1,0,3,2] row_mask:0xf bank_mask:0xf
	v_add_f32_dpp v42, v142, v142 quad_perm:[1,0,3,2] row_mask:0xf bank_mask:0xf
	v_add_f32_dpp v43, v143, v143 quad_perm:[1,0,3,2] row_mask:0xf bank_mask:0xf
	v_cndmask_b32_e32 v40, v42, v40, vcc
	v_cndmask_b32_e32 v41, v43, v41, vcc
	v_add_f32_dpp v46, v44, v44 quad_perm:[2,3,0,1] row_mask:0xf bank_mask:0xf
	v_add_f32_dpp v47, v45, v45 quad_perm:[2,3,0,1] row_mask:0xf bank_mask:0xf
	v_cndmask_b32_e64 v44, v47, v46, s[4:5]
	s_waitcnt vmcnt(8)
	s_nop 0
	v_pk_mul_f32 v[140:141], v[236:237], v[32:33] op_sel_hi:[1,0]
	v_pk_mul_f32 v[142:143], v[244:245], v[32:33] op_sel_hi:[1,0]
	v_pk_fma_f32 v[140:141], v[238:239], v[32:33], v[140:141] op_sel:[0,1,0]
	v_pk_fma_f32 v[142:143], v[246:247], v[32:33], v[142:143] op_sel:[0,1,0]
	v_pk_fma_f32 v[140:141], v[240:241], v[34:35], v[140:141] op_sel_hi:[1,0,1]
	v_pk_fma_f32 v[142:143], v[248:249], v[34:35], v[142:143] op_sel_hi:[1,0,1]
	v_pk_fma_f32 v[140:141], v[242:243], v[34:35], v[140:141] op_sel:[0,1,0]
	v_pk_fma_f32 v[142:143], v[250:251], v[34:35], v[142:143] op_sel:[0,1,0]
	v_add_f32_dpp v60, v62, v61 row_ror:8 row_mask:0xf bank_mask:0xf
	v_add_f32_dpp v36, v252, v252 quad_perm:[1,0,3,2] row_mask:0xf bank_mask:0xf
	v_add_f32_dpp v37, v253, v253 quad_perm:[1,0,3,2] row_mask:0xf bank_mask:0xf
	v_add_f32_dpp v38, v254, v254 quad_perm:[1,0,3,2] row_mask:0xf bank_mask:0xf
	v_add_f32_dpp v39, v255, v255 quad_perm:[1,0,3,2] row_mask:0xf bank_mask:0xf
	v_cndmask_b32_e32 v36, v38, v36, vcc
	v_cndmask_b32_e32 v37, v39, v37, vcc
	v_add_f32_dpp v42, v40, v40 quad_perm:[2,3,0,1] row_mask:0xf bank_mask:0xf
	v_add_f32_dpp v43, v41, v41 quad_perm:[2,3,0,1] row_mask:0xf bank_mask:0xf
	v_cndmask_b32_e64 v40, v43, v42, s[4:5]
	v_cndmask_b32_e64 v45, v40, v44, s[6:7]
	v_cndmask_b32_e64 v46, v44, v40, s[6:7]
	s_waitcnt vmcnt(7)
	s_nop 0
	v_pk_mul_f32 v[252:253], v[236:237], v[28:29] op_sel_hi:[1,0]
	v_pk_mul_f32 v[254:255], v[244:245], v[28:29] op_sel_hi:[1,0]
	v_pk_fma_f32 v[252:253], v[238:239], v[28:29], v[252:253] op_sel:[0,1,0]
	v_pk_fma_f32 v[254:255], v[246:247], v[28:29], v[254:255] op_sel:[0,1,0]
	v_pk_fma_f32 v[252:253], v[240:241], v[30:31], v[252:253] op_sel_hi:[1,0,1]
	v_pk_fma_f32 v[254:255], v[248:249], v[30:31], v[254:255] op_sel_hi:[1,0,1]
	v_pk_fma_f32 v[252:253], v[242:243], v[30:31], v[252:253] op_sel:[0,1,0]
	v_pk_fma_f32 v[254:255], v[250:251], v[30:31], v[254:255] op_sel:[0,1,0]
	v_add_f32_dpp v44, v46, v45 row_ror:4 row_mask:0xf bank_mask:0xf
	v_add_f32_dpp v32, v140, v140 quad_perm:[1,0,3,2] row_mask:0xf bank_mask:0xf
	v_add_f32_dpp v33, v141, v141 quad_perm:[1,0,3,2] row_mask:0xf bank_mask:0xf
	v_add_f32_dpp v34, v142, v142 quad_perm:[1,0,3,2] row_mask:0xf bank_mask:0xf
	v_add_f32_dpp v35, v143, v143 quad_perm:[1,0,3,2] row_mask:0xf bank_mask:0xf
	v_cndmask_b32_e32 v32, v34, v32, vcc
	v_cndmask_b32_e32 v33, v35, v33, vcc
	v_add_f32_dpp v38, v36, v36 quad_perm:[2,3,0,1] row_mask:0xf bank_mask:0xf
	v_add_f32_dpp v39, v37, v37 quad_perm:[2,3,0,1] row_mask:0xf bank_mask:0xf
	v_cndmask_b32_e64 v36, v39, v38, s[4:5]
	s_waitcnt vmcnt(6)
	s_nop 0
	v_pk_mul_f32 v[140:141], v[236:237], v[24:25] op_sel_hi:[1,0]
	v_pk_mul_f32 v[142:143], v[244:245], v[24:25] op_sel_hi:[1,0]
	v_pk_fma_f32 v[140:141], v[238:239], v[24:25], v[140:141] op_sel:[0,1,0]
	v_pk_fma_f32 v[142:143], v[246:247], v[24:25], v[142:143] op_sel:[0,1,0]
	v_pk_fma_f32 v[140:141], v[240:241], v[26:27], v[140:141] op_sel_hi:[1,0,1]
	v_pk_fma_f32 v[142:143], v[248:249], v[26:27], v[142:143] op_sel_hi:[1,0,1]
	v_pk_fma_f32 v[140:141], v[242:243], v[26:27], v[140:141] op_sel:[0,1,0]
	v_pk_fma_f32 v[142:143], v[250:251], v[26:27], v[142:143] op_sel:[0,1,0]
	v_add_f32_dpp v28, v252, v252 quad_perm:[1,0,3,2] row_mask:0xf bank_mask:0xf
	v_add_f32_dpp v29, v253, v253 quad_perm:[1,0,3,2] row_mask:0xf bank_mask:0xf
	v_add_f32_dpp v30, v254, v254 quad_perm:[1,0,3,2] row_mask:0xf bank_mask:0xf
	v_add_f32_dpp v31, v255, v255 quad_perm:[1,0,3,2] row_mask:0xf bank_mask:0xf
	v_cndmask_b32_e32 v28, v30, v28, vcc
	v_cndmask_b32_e32 v29, v31, v29, vcc
	v_add_f32_dpp v34, v32, v32 quad_perm:[2,3,0,1] row_mask:0xf bank_mask:0xf
	v_add_f32_dpp v35, v33, v33 quad_perm:[2,3,0,1] row_mask:0xf bank_mask:0xf
	v_cndmask_b32_e64 v32, v35, v34, s[4:5]
	v_cndmask_b32_e64 v37, v32, v36, s[6:7]
	v_cndmask_b32_e64 v38, v36, v32, s[6:7]
	s_waitcnt vmcnt(5)
	s_nop 0
	v_pk_mul_f32 v[252:253], v[236:237], v[20:21] op_sel_hi:[1,0]
	v_pk_mul_f32 v[254:255], v[244:245], v[20:21] op_sel_hi:[1,0]
	v_pk_fma_f32 v[252:253], v[238:239], v[20:21], v[252:253] op_sel:[0,1,0]
	v_pk_fma_f32 v[254:255], v[246:247], v[20:21], v[254:255] op_sel:[0,1,0]
	v_pk_fma_f32 v[252:253], v[240:241], v[22:23], v[252:253] op_sel_hi:[1,0,1]
	v_pk_fma_f32 v[254:255], v[248:249], v[22:23], v[254:255] op_sel_hi:[1,0,1]
	v_pk_fma_f32 v[252:253], v[242:243], v[22:23], v[252:253] op_sel:[0,1,0]
	v_pk_fma_f32 v[254:255], v[250:251], v[22:23], v[254:255] op_sel:[0,1,0]
	v_add_f32_dpp v36, v38, v37 row_ror:4 row_mask:0xf bank_mask:0xf
	v_cndmask_b32_e64 v45, v36, v44, s[64:65]
	v_cndmask_b32_e64 v46, v44, v36, s[64:65]
	v_add_f32_dpp v24, v140, v140 quad_perm:[1,0,3,2] row_mask:0xf bank_mask:0xf
	v_add_f32_dpp v25, v141, v141 quad_perm:[1,0,3,2] row_mask:0xf bank_mask:0xf
	v_add_f32_dpp v26, v142, v142 quad_perm:[1,0,3,2] row_mask:0xf bank_mask:0xf
	v_add_f32_dpp v27, v143, v143 quad_perm:[1,0,3,2] row_mask:0xf bank_mask:0xf
	v_cndmask_b32_e32 v24, v26, v24, vcc
	v_cndmask_b32_e32 v25, v27, v25, vcc
	v_add_f32_dpp v30, v28, v28 quad_perm:[2,3,0,1] row_mask:0xf bank_mask:0xf
	v_add_f32_dpp v31, v29, v29 quad_perm:[2,3,0,1] row_mask:0xf bank_mask:0xf
	v_cndmask_b32_e64 v28, v31, v30, s[4:5]
	s_waitcnt vmcnt(4)
	s_nop 0
	v_pk_mul_f32 v[140:141], v[236:237], v[16:17] op_sel_hi:[1,0]
	v_pk_mul_f32 v[142:143], v[244:245], v[16:17] op_sel_hi:[1,0]
	v_pk_fma_f32 v[140:141], v[238:239], v[16:17], v[140:141] op_sel:[0,1,0]
	v_pk_fma_f32 v[142:143], v[246:247], v[16:17], v[142:143] op_sel:[0,1,0]
	v_pk_fma_f32 v[140:141], v[240:241], v[18:19], v[140:141] op_sel_hi:[1,0,1]
	v_pk_fma_f32 v[142:143], v[248:249], v[18:19], v[142:143] op_sel_hi:[1,0,1]
	v_pk_fma_f32 v[140:141], v[242:243], v[18:19], v[140:141] op_sel:[0,1,0]
	v_pk_fma_f32 v[142:143], v[250:251], v[18:19], v[142:143] op_sel:[0,1,0]
	v_add_f32_dpp v44, v46, v45 row_ror:8 row_mask:0xf bank_mask:0xf
	v_add_f32_dpp v20, v252, v252 quad_perm:[1,0,3,2] row_mask:0xf bank_mask:0xf
	v_add_f32_dpp v21, v253, v253 quad_perm:[1,0,3,2] row_mask:0xf bank_mask:0xf
	v_add_f32_dpp v22, v254, v254 quad_perm:[1,0,3,2] row_mask:0xf bank_mask:0xf
	v_add_f32_dpp v23, v255, v255 quad_perm:[1,0,3,2] row_mask:0xf bank_mask:0xf
	v_cndmask_b32_e32 v20, v22, v20, vcc
	v_cndmask_b32_e32 v21, v23, v21, vcc
	v_add_f32_dpp v26, v24, v24 quad_perm:[2,3,0,1] row_mask:0xf bank_mask:0xf
	v_add_f32_dpp v27, v25, v25 quad_perm:[2,3,0,1] row_mask:0xf bank_mask:0xf
	v_cndmask_b32_e64 v24, v27, v26, s[4:5]
	v_cndmask_b32_e64 v29, v24, v28, s[6:7]
	v_cndmask_b32_e64 v30, v28, v24, s[6:7]
	s_waitcnt vmcnt(3)
; DI void attn_sample_item(const Params& p, int item, ldsp lds, int tid_) {
;     ...
;   SC_SCORE(kvA, 0)
;   SC_SCORE(kvB, 1)
	s_nop 0
	v_pk_mul_f32 v[252:253], v[236:237], v[12:13] op_sel_hi:[1,0]
	v_pk_mul_f32 v[254:255], v[244:245], v[12:13] op_sel_hi:[1,0]
	v_pk_fma_f32 v[252:253], v[238:239], v[12:13], v[252:253] op_sel:[0,1,0]
	v_pk_fma_f32 v[254:255], v[246:247], v[12:13], v[254:255] op_sel:[0,1,0]
	v_pk_fma_f32 v[252:253], v[240:241], v[14:15], v[252:253] op_sel_hi:[1,0,1]
	v_pk_fma_f32 v[254:255], v[248:249], v[14:15], v[254:255] op_sel_hi:[1,0,1]
	v_pk_fma_f32 v[252:253], v[242:243], v[14:15], v[252:253] op_sel:[0,1,0]
	v_pk_fma_f32 v[254:255], v[250:251], v[14:15], v[254:255] op_sel:[0,1,0]
	v_permlane16_swap_b32_e32 v60, v44
	v_add_f32_e32 v60, v60, v44
	v_add_f32_dpp v28, v30, v29 row_ror:4 row_mask:0xf bank_mask:0xf
	v_add_f32_dpp v16, v140, v140 quad_perm:[1,0,3,2] row_mask:0xf bank_mask:0xf
	v_add_f32_dpp v17, v141, v141 quad_perm:[1,0,3,2] row_mask:0xf bank_mask:0xf
	v_add_f32_dpp v18, v142, v142 quad_perm:[1,0,3,2] row_mask:0xf bank_mask:0xf
	v_add_f32_dpp v19, v143, v143 quad_perm:[1,0,3,2] row_mask:0xf bank_mask:0xf
	v_cndmask_b32_e32 v16, v18, v16, vcc
	v_cndmask_b32_e32 v17, v19, v17, vcc
	v_add_f32_dpp v22, v20, v20 quad_perm:[2,3,0,1] row_mask:0xf bank_mask:0xf
	v_add_f32_dpp v23, v21, v21 quad_perm:[2,3,0,1] row_mask:0xf bank_mask:0xf
	v_cndmask_b32_e64 v20, v23, v22, s[4:5]
	s_waitcnt vmcnt(2)
	s_nop 0
	v_pk_mul_f32 v[140:141], v[236:237], v[8:9] op_sel_hi:[1,0]
	v_pk_mul_f32 v[142:143], v[244:245], v[8:9] op_sel_hi:[1,0]
	v_pk_fma_f32 v[140:141], v[238:239], v[8:9], v[140:141] op_sel:[0,1,0]
	v_pk_fma_f32 v[142:143], v[246:247], v[8:9], v[142:143] op_sel:[0,1,0]
	v_pk_fma_f32 v[140:141], v[240:241], v[10:11], v[140:141] op_sel_hi:[1,0,1]
	v_pk_fma_f32 v[142:143], v[248:249], v[10:11], v[142:143] op_sel_hi:[1,0,1]
	v_pk_fma_f32 v[140:141], v[242:243], v[10:11], v[140:141] op_sel:[0,1,0]
	v_pk_fma_f32 v[142:143], v[250:251], v[10:11], v[142:143] op_sel:[0,1,0]
	v_add_f32_dpp v12, v252, v252 quad_perm:[1,0,3,2] row_mask:0xf bank_mask:0xf
	v_add_f32_dpp v13, v253, v253 quad_perm:[1,0,3,2] row_mask:0xf bank_mask:0xf
	v_add_f32_dpp v14, v254, v254 quad_perm:[1,0,3,2] row_mask:0xf bank_mask:0xf
	v_add_f32_dpp v15, v255, v255 quad_perm:[1,0,3,2] row_mask:0xf bank_mask:0xf
	v_cndmask_b32_e32 v12, v14, v12, vcc
	v_cndmask_b32_e32 v13, v15, v13, vcc
	v_add_f32_dpp v18, v16, v16 quad_perm:[2,3,0,1] row_mask:0xf bank_mask:0xf
	v_add_f32_dpp v19, v17, v17 quad_perm:[2,3,0,1] row_mask:0xf bank_mask:0xf
	v_cndmask_b32_e64 v16, v19, v18, s[4:5]
	v_cndmask_b32_e64 v21, v16, v20, s[6:7]
	v_cndmask_b32_e64 v22, v20, v16, s[6:7]
	s_waitcnt vmcnt(1)
	s_nop 0
	v_pk_mul_f32 v[252:253], v[236:237], v[4:5] op_sel_hi:[1,0]
	v_pk_mul_f32 v[254:255], v[244:245], v[4:5] op_sel_hi:[1,0]
	v_pk_fma_f32 v[252:253], v[238:239], v[4:5], v[252:253] op_sel:[0,1,0]
	v_pk_fma_f32 v[254:255], v[246:247], v[4:5], v[254:255] op_sel:[0,1,0]
	v_pk_fma_f32 v[252:253], v[240:241], v[6:7], v[252:253] op_sel_hi:[1,0,1]
	v_pk_fma_f32 v[254:255], v[248:249], v[6:7], v[254:255] op_sel_hi:[1,0,1]
	v_pk_fma_f32 v[252:253], v[242:243], v[6:7], v[252:253] op_sel:[0,1,0]
	v_pk_fma_f32 v[254:255], v[250:251], v[6:7], v[254:255] op_sel:[0,1,0]
	v_add_f32_dpp v20, v22, v21 row_ror:4 row_mask:0xf bank_mask:0xf
	v_cndmask_b32_e64 v29, v20, v28, s[64:65]
	v_cndmask_b32_e64 v30, v28, v20, s[64:65]
	v_add_f32_dpp v8, v140, v140 quad_perm:[1,0,3,2] row_mask:0xf bank_mask:0xf
	v_add_f32_dpp v9, v141, v141 quad_perm:[1,0,3,2] row_mask:0xf bank_mask:0xf
	v_add_f32_dpp v10, v142, v142 quad_perm:[1,0,3,2] row_mask:0xf bank_mask:0xf
	v_add_f32_dpp v11, v143, v143 quad_perm:[1,0,3,2] row_mask:0xf bank_mask:0xf
	v_cndmask_b32_e32 v8, v10, v8, vcc
	v_cndmask_b32_e32 v9, v11, v9, vcc
	v_add_f32_dpp v14, v12, v12 quad_perm:[2,3,0,1] row_mask:0xf bank_mask:0xf
	v_add_f32_dpp v15, v13, v13 quad_perm:[2,3,0,1] row_mask:0xf bank_mask:0xf
	v_cndmask_b32_e64 v12, v15, v14, s[4:5]
	s_waitcnt vmcnt(0)
	s_nop 0
	v_pk_mul_f32 v[140:141], v[236:237], v[0:1] op_sel_hi:[1,0]
	v_pk_mul_f32 v[142:143], v[244:245], v[0:1] op_sel_hi:[1,0]
	v_pk_fma_f32 v[140:141], v[238:239], v[0:1], v[140:141] op_sel:[0,1,0]
	v_pk_fma_f32 v[142:143], v[246:247], v[0:1], v[142:143] op_sel:[0,1,0]
	v_pk_fma_f32 v[140:141], v[240:241], v[2:3], v[140:141] op_sel_hi:[1,0,1]
	v_pk_fma_f32 v[142:143], v[248:249], v[2:3], v[142:143] op_sel_hi:[1,0,1]
	v_pk_fma_f32 v[140:141], v[242:243], v[2:3], v[140:141] op_sel:[0,1,0]
	v_pk_fma_f32 v[142:143], v[250:251], v[2:3], v[142:143] op_sel:[0,1,0]
	v_add_f32_dpp v28, v30, v29 row_ror:8 row_mask:0xf bank_mask:0xf
	v_add_f32_dpp v4, v252, v252 quad_perm:[1,0,3,2] row_mask:0xf bank_mask:0xf
	v_add_f32_dpp v5, v253, v253 quad_perm:[1,0,3,2] row_mask:0xf bank_mask:0xf
	v_add_f32_dpp v6, v254, v254 quad_perm:[1,0,3,2] row_mask:0xf bank_mask:0xf
	v_add_f32_dpp v7, v255, v255 quad_perm:[1,0,3,2] row_mask:0xf bank_mask:0xf
	v_cndmask_b32_e32 v4, v6, v4, vcc
	v_cndmask_b32_e32 v5, v7, v5, vcc
	v_add_f32_dpp v10, v8, v8 quad_perm:[2,3,0,1] row_mask:0xf bank_mask:0xf
	v_add_f32_dpp v11, v9, v9 quad_perm:[2,3,0,1] row_mask:0xf bank_mask:0xf
	v_cndmask_b32_e64 v8, v11, v10, s[4:5]
	v_cndmask_b32_e64 v13, v8, v12, s[6:7]
	v_cndmask_b32_e64 v14, v12, v8, s[6:7]
	s_nop 1
	s_nop 0
	v_add_f32_dpp v12, v14, v13 row_ror:4 row_mask:0xf bank_mask:0xf
	v_add_f32_dpp v0, v140, v140 quad_perm:[1,0,3,2] row_mask:0xf bank_mask:0xf
	v_add_f32_dpp v1, v141, v141 quad_perm:[1,0,3,2] row_mask:0xf bank_mask:0xf
	v_add_f32_dpp v2, v142, v142 quad_perm:[1,0,3,2] row_mask:0xf bank_mask:0xf
	v_add_f32_dpp v3, v143, v143 quad_perm:[1,0,3,2] row_mask:0xf bank_mask:0xf
	v_cndmask_b32_e32 v0, v2, v0, vcc
	v_cndmask_b32_e32 v1, v3, v1, vcc
	v_add_f32_dpp v6, v4, v4 quad_perm:[2,3,0,1] row_mask:0xf bank_mask:0xf
	v_add_f32_dpp v7, v5, v5 quad_perm:[2,3,0,1] row_mask:0xf bank_mask:0xf
	v_cndmask_b32_e64 v4, v7, v6, s[4:5]
	v_add_f32_dpp v2, v0, v0 quad_perm:[2,3,0,1] row_mask:0xf bank_mask:0xf
	v_add_f32_dpp v3, v1, v1 quad_perm:[2,3,0,1] row_mask:0xf bank_mask:0xf
	v_cndmask_b32_e64 v0, v3, v2, s[4:5]
	v_cndmask_b32_e64 v5, v0, v4, s[6:7]
	v_cndmask_b32_e64 v6, v4, v0, s[6:7]
	s_nop 1
	s_nop 0
	v_add_f32_dpp v4, v6, v5 row_ror:4 row_mask:0xf bank_mask:0xf
	v_cndmask_b32_e64 v13, v4, v12, s[64:65]
	v_cndmask_b32_e64 v14, v12, v4, s[64:65]
	s_nop 1
	s_nop 0
	v_add_f32_dpp v12, v14, v13 row_ror:8 row_mask:0xf bank_mask:0xf
	s_nop 1
	v_permlane16_swap_b32_e32 v28, v12
	v_add_f32_e32 v28, v28, v12
	s_nop 1
	v_permlane32_swap_b32_e32 v60, v28
	v_add_f32_e32 v60, v60, v28
	ds_write_b32 v235, v60 offset:64
	v_lshlrev_b32_e32 v2, 2, v223
	s_add_u32 s4, s14, s28
	s_addc_u32 s5, s15, s29
	v_lshlrev_b32_e32 v0, 2, v2
	s_waitcnt lgkmcnt(0)
; DI void lbar() { asm volatile("s_waitcnt lgkmcnt(0)" ::: "memory"); __builtin_amdgcn_s_barrier(); asm volatile("" ::: "memory"); }
; DI float wave_sum(float v) { for (int o = 32; o >= 1; o >>= 1) v += __shfl_xor(v, o); return v; }
; DI void attn_sample_item(const Params& p, int item, ldsp lds, int tid_) {
;     ...
;   for (int j = 0; j < 16; ++j) vvA[j] = __builtin_nontemporal_load((const f32x4*)(cv + (size_t)(wid * 32 + j) * 1024 + lane * 4));
;   lbar();
;   if (wid < 4) {
;     float v[4]; float mx = -1e30f;
; #pragma unroll
;     for (int j = 0; j < 4; ++j) { v[j] = SC[wid * 256 + j * 64 + lane]; mx = fmaxf(mx, v[j]); }
;     for (int o = 32; o >= 1; o >>= 1) mx = fmaxf(mx, __shfl_xor(mx, o));
;     float s = 0.f;
; #pragma unroll
;     for (int j = 0; j < 4; ++j) { v[j] = __expf(v[j] - mx); s += v[j]; }
;     s = wave_sum(s); const float inv = 1.f / s;
; #pragma unroll
;     for (int j = 0; j < 4; ++j) SC[wid * 256 + j * 64 + lane] = v[j] * inv;
;   }
	v_mov_b32_e32 v1, v145
	v_lshl_add_u64 v[0:1], s[4:5], 0, v[0:1]
	v_lshl_add_u64 v[4:5], v[0:1], 0, v[158:159]
	v_lshl_add_u64 v[6:7], v[0:1], 0, v[162:163]
	global_load_dwordx4 v[100:103], v[4:5], off nt
	global_load_dwordx4 v[92:95], v[6:7], off nt
	v_lshl_add_u64 v[4:5], v[0:1], 0, v[164:165]
	v_lshl_add_u64 v[6:7], v[0:1], 0, v[168:169]
	global_load_dwordx4 v[112:115], v[4:5], off nt
	global_load_dwordx4 v[108:111], v[6:7], off nt
	v_lshl_add_u64 v[4:5], v[0:1], 0, v[172:173]
	v_lshl_add_u64 v[6:7], v[0:1], 0, v[176:177]
	global_load_dwordx4 v[120:123], v[4:5], off nt
	global_load_dwordx4 v[116:119], v[6:7], off nt
	v_lshl_add_u64 v[4:5], v[0:1], 0, v[180:181]
	v_lshl_add_u64 v[6:7], v[0:1], 0, v[184:185]
	global_load_dwordx4 v[124:127], v[4:5], off nt
	global_load_dwordx4 v[104:107], v[6:7], off nt
	v_lshl_add_u64 v[4:5], v[0:1], 0, v[188:189]
	v_lshl_add_u64 v[6:7], v[0:1], 0, v[192:193]
	global_load_dwordx4 v[68:71], v[4:5], off nt
	global_load_dwordx4 v[64:67], v[6:7], off nt
	v_lshl_add_u64 v[4:5], v[0:1], 0, v[196:197]
	v_lshl_add_u64 v[6:7], v[0:1], 0, v[200:201]
	global_load_dwordx4 v[80:83], v[4:5], off nt
	global_load_dwordx4 v[76:79], v[6:7], off nt
	v_lshl_add_u64 v[4:5], v[0:1], 0, v[202:203]
	v_lshl_add_u64 v[6:7], v[0:1], 0, v[204:205]
	global_load_dwordx4 v[88:91], v[4:5], off nt
	global_load_dwordx4 v[84:87], v[6:7], off nt
	v_lshl_add_u64 v[4:5], v[0:1], 0, v[206:207]
	v_lshl_add_u64 v[6:7], v[0:1], 0, v[208:209]
	global_load_dwordx4 v[96:99], v[4:5], off nt
	global_load_dwordx4 v[72:75], v[6:7], off nt
	s_waitcnt lgkmcnt(0)
	s_barrier
	v_cmp_gt_i32_e32 vcc, 4, v210
	s_and_saveexec_b64 s[4:5], vcc
	s_cbranch_execz .LBB0_1675
	v_lshlrev_b32_e32 v3, 10, v210
	v_add3_u32 v6, 16, v3, v2
	ds_read2st64_b32 v[2:3], v6 offset1:1
	ds_read2st64_b32 v[4:5], v6 offset0:2 offset1:3
	s_waitcnt lgkmcnt(1)
	v_max3_f32 v7, v2, s35, v3
	s_waitcnt lgkmcnt(0)
	v_max3_f32 v7, v7, v4, v5
	ds_bpermute_b32 v8, v133, v7
	s_waitcnt lgkmcnt(0)
	v_max_f32_e32 v8, v8, v8
	v_max_f32_e32 v7, v7, v8
	ds_bpermute_b32 v8, v132, v7
	s_waitcnt lgkmcnt(0)
	v_max_f32_e32 v8, v8, v8
	v_max_f32_e32 v7, v7, v8
	ds_bpermute_b32 v8, v131, v7
	s_waitcnt lgkmcnt(0)
	v_max_f32_e32 v8, v8, v8
	v_max_f32_e32 v7, v7, v8
	ds_bpermute_b32 v8, v130, v7
	s_waitcnt lgkmcnt(0)
	v_max_f32_e32 v8, v8, v8
	v_max_f32_e32 v7, v7, v8
	ds_bpermute_b32 v8, v129, v7
	s_waitcnt lgkmcnt(0)
	v_max_f32_e32 v8, v8, v8
	v_max_f32_e32 v7, v7, v8
	ds_bpermute_b32 v8, v128, v7
	s_waitcnt lgkmcnt(0)
	v_max_f32_e32 v8, v8, v8
	v_max_f32_e32 v7, v7, v8
	v_sub_f32_e32 v2, v2, v7
	v_sub_f32_e32 v3, v3, v7
	v_mul_f32_e32 v2, 0x3fb8aa3b, v2
	v_sub_f32_e32 v4, v4, v7
	v_mul_f32_e32 v3, 0x3fb8aa3b, v3
	v_exp_f32_e32 v2, v2
	v_sub_f32_e32 v5, v5, v7
	v_mul_f32_e32 v4, 0x3fb8aa3b, v4
	v_exp_f32_e32 v3, v3
	v_mul_f32_e32 v5, 0x3fb8aa3b, v5
	v_exp_f32_e32 v4, v4
	v_exp_f32_e32 v5, v5
	v_add_f32_e32 v7, 0, v2
	v_add_f32_e32 v7, v3, v7
	v_add_f32_e32 v7, v4, v7
	v_add_f32_e32 v7, v5, v7
	ds_bpermute_b32 v8, v133, v7
	s_waitcnt lgkmcnt(0)
	v_add_f32_e32 v7, v7, v8
	ds_bpermute_b32 v8, v132, v7
	s_waitcnt lgkmcnt(0)
	v_add_f32_e32 v7, v7, v8
	ds_bpermute_b32 v8, v131, v7
	s_waitcnt lgkmcnt(0)
	v_add_f32_e32 v7, v7, v8
	ds_bpermute_b32 v8, v130, v7
	s_waitcnt lgkmcnt(0)
	v_add_f32_e32 v7, v7, v8
	ds_bpermute_b32 v8, v129, v7
	s_waitcnt lgkmcnt(0)
	v_add_f32_e32 v7, v7, v8
	ds_bpermute_b32 v8, v128, v7
	s_waitcnt lgkmcnt(0)
	v_add_f32_e32 v7, v7, v8
	v_div_scale_f32 v8, s[6:7], v7, v7, 1.0
	v_rcp_f32_e32 v9, v8
	v_div_scale_f32 v10, vcc, 1.0, v7, 1.0
	v_fma_f32 v11, -v8, v9, 1.0
	v_fmac_f32_e32 v9, v11, v9
	v_mul_f32_e32 v11, v10, v9
	v_fma_f32 v12, -v8, v11, v10
	v_fmac_f32_e32 v11, v12, v9
	v_fma_f32 v8, -v8, v11, v10
	v_div_fmas_f32 v8, v8, v9, v11
	v_div_fixup_f32 v7, v8, v7, 1.0
	v_mul_f32_e32 v2, v2, v7
	v_mul_f32_e32 v3, v3, v7
	v_mul_f32_e32 v4, v4, v7
	v_mul_f32_e32 v5, v5, v7
	ds_write2st64_b32 v6, v2, v3 offset1:1
	ds_write2st64_b32 v6, v4, v5 offset0:2 offset1:3
	s_branch .LBB0_1675
